# prep row phase: five forget-gate weight sets in flight from LDS (was four)
# baseline (speedup 1.0000x reference)
.LBB0_54:
	s_or_b64 exec, exec, s[0:1]
	s_movk_i32 s2, 0x4000
	v_cmp_gt_i32_e32 vcc, s2, v66
	v_mbcnt_lo_u32_b32 v1, -1, 0
	s_waitcnt lgkmcnt(0)
	s_barrier
	s_and_saveexec_b64 s[8:9], vcc
	s_cbranch_execz .LBB0_61
	v_mov_b32_e32 v250, v66
	v_mov_b32_e32 v251, v69
	v_lshlrev_b32_e32 v206, 4, v251
	v_add_u32_e32 v207, 0x1000, v206
	global_load_dwordx4 v[2:5], v206, s[14:15]
	global_load_dwordx4 v[6:9], v206, s[14:15] offset:1024
	global_load_dwordx4 v[10:13], v206, s[14:15] offset:2048
	global_load_dwordx4 v[14:17], v206, s[14:15] offset:3072
	global_load_dwordx4 v[18:21], v207, s[14:15]
	global_load_dwordx4 v[22:25], v207, s[14:15] offset:1024
	global_load_dwordx4 v[26:29], v207, s[14:15] offset:2048
	global_load_dwordx4 v[30:33], v207, s[14:15] offset:3072
	v_and_b32_e32 v222, 7, v251
	v_lshlrev_b32_e32 v222, 2, v222
	global_load_dword v196, v222, s[18:19]
	v_lshlrev_b32_e32 v193, 13, v250
	v_add_u32_e32 v193, v193, v206
	v_add_u32_e32 v193, 0x1000, v193
	v_lshlrev_b32_e32 v194, 12, v250
	v_lshl_add_u32 v194, v251, 3, v194
	v_lshlrev_b32_e32 v195, 2, v250
	v_lshl_add_u32 v195, v251, 15, v195
	v_add_u32_e32 v192, 16, v206
	v_xor_b32_e32 v186, 32, v251
	v_lshlrev_b32_e32 v186, 2, v186
	v_xor_b32_e32 v187, 16, v251
	v_lshlrev_b32_e32 v187, 2, v187
	v_xor_b32_e32 v188, 8, v251
	v_lshlrev_b32_e32 v188, 2, v188
	v_xor_b32_e32 v189, 4, v251
	v_lshlrev_b32_e32 v189, 2, v189
	v_xor_b32_e32 v190, 2, v251
	v_lshlrev_b32_e32 v190, 2, v190
	v_xor_b32_e32 v191, 1, v251
	v_lshlrev_b32_e32 v191, 2, v191
	v_mov_b32_e32 v241, 0x358637bd
	v_mov_b32_e32 v242, 0x3ecc95a3
	v_mov_b32_e32 v243, 0x7f800000
	v_mov_b32_e32 v244, 0x7fc00000
	v_mov_b32_e32 v245, 0xff800000
	s_mov_b32 s17, 0x800000
	s_mov_b32 s24, 0xbfb8aa3b
	s_mov_b32 s25, 0x3f2aaaab
	s_mov_b32 s28, 0x3f317218
	s_mov_b32 s29, 0x7f800000
	s_mov_b32 s30, 0x33800000
	s_mov_b32 s0, 0x1000000
	global_load_dwordx4 v[34:37], v193, s[12:13] offset:-4096 nt
	global_load_dwordx4 v[38:41], v193, s[12:13] offset:-3072 nt
	global_load_dwordx4 v[42:45], v193, s[12:13] offset:-2048 nt
	global_load_dwordx4 v[46:49], v193, s[12:13] offset:-1024 nt
	global_load_dwordx4 v[50:53], v193, s[12:13] offset:0 nt
	global_load_dwordx4 v[54:57], v193, s[12:13] offset:1024 nt
	global_load_dwordx4 v[58:61], v193, s[12:13] offset:2048 nt
	global_load_dwordx4 v[62:65], v193, s[12:13] offset:3072 nt
	v_add_u32_e32 v193, s0, v193
	global_load_dwordx4 v[66:69], v193, s[12:13] offset:-4096 nt
	global_load_dwordx4 v[70:73], v193, s[12:13] offset:-3072 nt
	global_load_dwordx4 v[74:77], v193, s[12:13] offset:-2048 nt
	global_load_dwordx4 v[78:81], v193, s[12:13] offset:-1024 nt
	global_load_dwordx4 v[82:85], v193, s[12:13] offset:0 nt
	global_load_dwordx4 v[86:89], v193, s[12:13] offset:1024 nt
	global_load_dwordx4 v[90:93], v193, s[12:13] offset:2048 nt
	global_load_dwordx4 v[94:97], v193, s[12:13] offset:3072 nt
	v_add_u32_e32 v193, s0, v193
	s_waitcnt vmcnt(8)
	v_pk_mul_f32 v[198:199], v[34:35], v[34:35]
	v_pk_mul_f32 v[200:201], v[36:37], v[36:37]
	v_pk_fma_f32 v[198:199], v[38:39], v[38:39], v[198:199]
	v_pk_fma_f32 v[200:201], v[40:41], v[40:41], v[200:201]
	v_pk_fma_f32 v[198:199], v[42:43], v[42:43], v[198:199]
	v_pk_fma_f32 v[200:201], v[44:45], v[44:45], v[200:201]
	v_pk_fma_f32 v[198:199], v[46:47], v[46:47], v[198:199]
	v_pk_fma_f32 v[200:201], v[48:49], v[48:49], v[200:201]
	v_pk_fma_f32 v[198:199], v[50:51], v[50:51], v[198:199]
	v_pk_fma_f32 v[200:201], v[52:53], v[52:53], v[200:201]
	v_pk_fma_f32 v[198:199], v[54:55], v[54:55], v[198:199]
	v_pk_fma_f32 v[200:201], v[56:57], v[56:57], v[200:201]
	v_pk_fma_f32 v[198:199], v[58:59], v[58:59], v[198:199]
	v_pk_fma_f32 v[200:201], v[60:61], v[60:61], v[200:201]
	v_pk_fma_f32 v[198:199], v[62:63], v[62:63], v[198:199]
	v_pk_fma_f32 v[200:201], v[64:65], v[64:65], v[200:201]
	v_pk_add_f32 v[198:199], v[198:199], v[200:201]
	v_add_f32_e32 v198, v198, v199
	s_nop 1
	v_add_f32_dpp v198, v198, v198 quad_perm:[1,0,3,2] row_mask:0xf bank_mask:0xf
	s_nop 1
	v_add_f32_dpp v198, v198, v198 quad_perm:[2,3,0,1] row_mask:0xf bank_mask:0xf
	s_nop 1
	v_add_f32_dpp v198, v198, v198 row_half_mirror row_mask:0xf bank_mask:0xf
	s_nop 1
	v_add_f32_dpp v198, v198, v198 row_mirror row_mask:0xf bank_mask:0xf
	v_mov_b32_e32 v199, v198
	s_nop 1
	v_permlane16_swap_b32 v199, v198
	v_add_f32_e32 v198, v198, v199
	v_mov_b32_e32 v199, v198
	s_nop 1
	v_permlane32_swap_b32 v199, v198
	v_add_f32_e32 v198, v198, v199
	ds_read_b128 v[130:133], v192
	ds_read_b128 v[134:137], v192 offset:1024
	ds_read_b128 v[138:141], v192 offset:2048
	ds_read_b128 v[142:145], v192 offset:3072
	ds_read_b128 v[146:149], v192 offset:4096
	ds_read_b128 v[150:153], v192 offset:5120
	ds_read_b128 v[154:157], v192 offset:6144
	ds_read_b128 v[158:161], v192 offset:7168
	ds_read_b128 v[178:181], v192 offset:8192
	ds_read_b128 v[182:185], v192 offset:9216
	v_fmamk_f32 v198, v198, 0x3a000000, v241
	v_mul_f32_e32 v199, 0x4b800000, v198
	v_cmp_gt_f32_e32 vcc, s17, v198
	s_nop 1
	v_cndmask_b32_e32 v198, v198, v199, vcc
	v_rsq_f32_e32 v198, v198
	s_nop 0
	v_mul_f32_e32 v199, 0x45800000, v198
	v_cndmask_b32_e32 v202, v198, v199, vcc
	v_pk_mul_f32 v[98:99], v[34:35], v[202:203] op_sel_hi:[1,0]
	v_pk_mul_f32 v[98:99], v[2:3], v[98:99]
	v_pk_mul_f32 v[100:101], v[36:37], v[202:203] op_sel_hi:[1,0]
	v_pk_mul_f32 v[100:101], v[4:5], v[100:101]
	v_cvt_pk_bf16_f32 v206, v98, v99
	v_cvt_pk_bf16_f32 v207, v100, v101
	global_store_dwordx2 v194, v[206:207], s[52:53]
	v_pk_mul_f32 v[102:103], v[38:39], v[202:203] op_sel_hi:[1,0]
	v_pk_mul_f32 v[102:103], v[6:7], v[102:103]
	v_pk_mul_f32 v[104:105], v[40:41], v[202:203] op_sel_hi:[1,0]
	v_pk_mul_f32 v[104:105], v[8:9], v[104:105]
	v_cvt_pk_bf16_f32 v206, v102, v103
	v_cvt_pk_bf16_f32 v207, v104, v105
	global_store_dwordx2 v194, v[206:207], s[52:53] offset:512
	v_pk_mul_f32 v[106:107], v[42:43], v[202:203] op_sel_hi:[1,0]
	v_pk_mul_f32 v[106:107], v[10:11], v[106:107]
	v_pk_mul_f32 v[108:109], v[44:45], v[202:203] op_sel_hi:[1,0]
	v_pk_mul_f32 v[108:109], v[12:13], v[108:109]
	v_cvt_pk_bf16_f32 v206, v106, v107
	v_cvt_pk_bf16_f32 v207, v108, v109
	global_store_dwordx2 v194, v[206:207], s[52:53] offset:1024
	v_pk_mul_f32 v[110:111], v[46:47], v[202:203] op_sel_hi:[1,0]
	v_pk_mul_f32 v[110:111], v[14:15], v[110:111]
	v_pk_mul_f32 v[112:113], v[48:49], v[202:203] op_sel_hi:[1,0]
	v_pk_mul_f32 v[112:113], v[16:17], v[112:113]
	v_cvt_pk_bf16_f32 v206, v110, v111
	v_cvt_pk_bf16_f32 v207, v112, v113
	global_store_dwordx2 v194, v[206:207], s[52:53] offset:1536
	v_pk_mul_f32 v[114:115], v[50:51], v[202:203] op_sel_hi:[1,0]
	v_pk_mul_f32 v[114:115], v[18:19], v[114:115]
	v_pk_mul_f32 v[116:117], v[52:53], v[202:203] op_sel_hi:[1,0]
	v_pk_mul_f32 v[116:117], v[20:21], v[116:117]
	v_cvt_pk_bf16_f32 v206, v114, v115
	v_cvt_pk_bf16_f32 v207, v116, v117
	global_store_dwordx2 v194, v[206:207], s[52:53] offset:2048
	v_pk_mul_f32 v[118:119], v[54:55], v[202:203] op_sel_hi:[1,0]
	v_pk_mul_f32 v[118:119], v[22:23], v[118:119]
	v_pk_mul_f32 v[120:121], v[56:57], v[202:203] op_sel_hi:[1,0]
	v_pk_mul_f32 v[120:121], v[24:25], v[120:121]
	v_cvt_pk_bf16_f32 v206, v118, v119
	v_cvt_pk_bf16_f32 v207, v120, v121
	global_store_dwordx2 v194, v[206:207], s[52:53] offset:2560
	v_pk_mul_f32 v[122:123], v[58:59], v[202:203] op_sel_hi:[1,0]
	v_pk_mul_f32 v[122:123], v[26:27], v[122:123]
	v_pk_mul_f32 v[124:125], v[60:61], v[202:203] op_sel_hi:[1,0]
	v_pk_mul_f32 v[124:125], v[28:29], v[124:125]
	v_cvt_pk_bf16_f32 v206, v122, v123
	v_cvt_pk_bf16_f32 v207, v124, v125
	global_store_dwordx2 v194, v[206:207], s[52:53] offset:3072
	v_pk_mul_f32 v[126:127], v[62:63], v[202:203] op_sel_hi:[1,0]
	v_pk_mul_f32 v[126:127], v[30:31], v[126:127]
	v_pk_mul_f32 v[128:129], v[64:65], v[202:203] op_sel_hi:[1,0]
	v_pk_mul_f32 v[128:129], v[32:33], v[128:129]
	v_cvt_pk_bf16_f32 v206, v126, v127
	v_cvt_pk_bf16_f32 v207, v128, v129
	global_store_dwordx2 v194, v[206:207], s[52:53] offset:3584
	v_add_u32_e32 v194, 0x800000, v194
	global_load_dwordx4 v[34:37], v193, s[12:13] offset:-4096 nt
	global_load_dwordx4 v[38:41], v193, s[12:13] offset:-3072 nt
	global_load_dwordx4 v[42:45], v193, s[12:13] offset:-2048 nt
	global_load_dwordx4 v[46:49], v193, s[12:13] offset:-1024 nt
	global_load_dwordx4 v[50:53], v193, s[12:13] offset:0 nt
	global_load_dwordx4 v[54:57], v193, s[12:13] offset:1024 nt
	global_load_dwordx4 v[58:61], v193, s[12:13] offset:2048 nt
	global_load_dwordx4 v[62:65], v193, s[12:13] offset:3072 nt
	v_add_u32_e32 v193, s0, v193
	s_waitcnt lgkmcnt(8)
	v_pk_mul_f32 v[162:163], v[130:131], v[98:99] op_sel_hi:[1,0]
	v_pk_mul_f32 v[164:165], v[132:133], v[98:99] op_sel_hi:[1,0]
	v_pk_mul_f32 v[166:167], v[134:135], v[98:99] op_sel_hi:[1,0]
	v_pk_mul_f32 v[168:169], v[136:137], v[98:99] op_sel_hi:[1,0]
	ds_read_b128 v[130:133], v192 offset:10240
	ds_read_b128 v[134:137], v192 offset:11264
	s_waitcnt lgkmcnt(8)
	v_pk_fma_f32 v[162:163], v[138:139], v[98:99], v[162:163] op_sel:[0,1,0] op_sel_hi:[1,1,1]
	v_pk_fma_f32 v[164:165], v[140:141], v[98:99], v[164:165] op_sel:[0,1,0] op_sel_hi:[1,1,1]
	v_pk_fma_f32 v[166:167], v[142:143], v[98:99], v[166:167] op_sel:[0,1,0] op_sel_hi:[1,1,1]
	v_pk_fma_f32 v[168:169], v[144:145], v[98:99], v[168:169] op_sel:[0,1,0] op_sel_hi:[1,1,1]
	ds_read_b128 v[138:141], v192 offset:12288
	ds_read_b128 v[142:145], v192 offset:13312
	s_waitcnt lgkmcnt(8)
	v_pk_fma_f32 v[162:163], v[146:147], v[100:101], v[162:163] op_sel_hi:[1,0,1]
	v_pk_fma_f32 v[164:165], v[148:149], v[100:101], v[164:165] op_sel_hi:[1,0,1]
	v_pk_fma_f32 v[166:167], v[150:151], v[100:101], v[166:167] op_sel_hi:[1,0,1]
	v_pk_fma_f32 v[168:169], v[152:153], v[100:101], v[168:169] op_sel_hi:[1,0,1]
	ds_read_b128 v[146:149], v192 offset:14336
	ds_read_b128 v[150:153], v192 offset:15360
	s_waitcnt lgkmcnt(8)
	v_pk_fma_f32 v[162:163], v[154:155], v[100:101], v[162:163] op_sel:[0,1,0] op_sel_hi:[1,1,1]
	v_pk_fma_f32 v[164:165], v[156:157], v[100:101], v[164:165] op_sel:[0,1,0] op_sel_hi:[1,1,1]
	v_pk_fma_f32 v[166:167], v[158:159], v[100:101], v[166:167] op_sel:[0,1,0] op_sel_hi:[1,1,1]
	v_pk_fma_f32 v[168:169], v[160:161], v[100:101], v[168:169] op_sel:[0,1,0] op_sel_hi:[1,1,1]
	ds_read_b128 v[154:157], v192 offset:16384
	ds_read_b128 v[158:161], v192 offset:17408
	s_waitcnt lgkmcnt(8)
	v_pk_fma_f32 v[162:163], v[178:179], v[102:103], v[162:163] op_sel_hi:[1,0,1]
	v_pk_fma_f32 v[164:165], v[180:181], v[102:103], v[164:165] op_sel_hi:[1,0,1]
	v_pk_fma_f32 v[166:167], v[182:183], v[102:103], v[166:167] op_sel_hi:[1,0,1]
	v_pk_fma_f32 v[168:169], v[184:185], v[102:103], v[168:169] op_sel_hi:[1,0,1]
	ds_read_b128 v[178:181], v192 offset:18432
	ds_read_b128 v[182:185], v192 offset:19456
	s_waitcnt lgkmcnt(8)
	v_pk_fma_f32 v[162:163], v[130:131], v[102:103], v[162:163] op_sel:[0,1,0] op_sel_hi:[1,1,1]
	v_pk_fma_f32 v[164:165], v[132:133], v[102:103], v[164:165] op_sel:[0,1,0] op_sel_hi:[1,1,1]
	v_pk_fma_f32 v[166:167], v[134:135], v[102:103], v[166:167] op_sel:[0,1,0] op_sel_hi:[1,1,1]
	v_pk_fma_f32 v[168:169], v[136:137], v[102:103], v[168:169] op_sel:[0,1,0] op_sel_hi:[1,1,1]
	ds_read_b128 v[130:133], v192 offset:20480
	ds_read_b128 v[134:137], v192 offset:21504
	s_waitcnt lgkmcnt(8)
	v_pk_fma_f32 v[162:163], v[138:139], v[104:105], v[162:163] op_sel_hi:[1,0,1]
	v_pk_fma_f32 v[164:165], v[140:141], v[104:105], v[164:165] op_sel_hi:[1,0,1]
	v_pk_fma_f32 v[166:167], v[142:143], v[104:105], v[166:167] op_sel_hi:[1,0,1]
	v_pk_fma_f32 v[168:169], v[144:145], v[104:105], v[168:169] op_sel_hi:[1,0,1]
	ds_read_b128 v[138:141], v192 offset:22528
	ds_read_b128 v[142:145], v192 offset:23552
	s_waitcnt lgkmcnt(8)
	v_pk_fma_f32 v[162:163], v[146:147], v[104:105], v[162:163] op_sel:[0,1,0] op_sel_hi:[1,1,1]
	v_pk_fma_f32 v[164:165], v[148:149], v[104:105], v[164:165] op_sel:[0,1,0] op_sel_hi:[1,1,1]
	v_pk_fma_f32 v[166:167], v[150:151], v[104:105], v[166:167] op_sel:[0,1,0] op_sel_hi:[1,1,1]
	v_pk_fma_f32 v[168:169], v[152:153], v[104:105], v[168:169] op_sel:[0,1,0] op_sel_hi:[1,1,1]
	ds_read_b128 v[146:149], v192 offset:24576
	ds_read_b128 v[150:153], v192 offset:25600
	s_waitcnt lgkmcnt(8)
	v_pk_fma_f32 v[162:163], v[154:155], v[106:107], v[162:163] op_sel_hi:[1,0,1]
	v_pk_fma_f32 v[164:165], v[156:157], v[106:107], v[164:165] op_sel_hi:[1,0,1]
	v_pk_fma_f32 v[166:167], v[158:159], v[106:107], v[166:167] op_sel_hi:[1,0,1]
	v_pk_fma_f32 v[168:169], v[160:161], v[106:107], v[168:169] op_sel_hi:[1,0,1]
	ds_read_b128 v[154:157], v192 offset:26624
	ds_read_b128 v[158:161], v192 offset:27648
	s_waitcnt lgkmcnt(8)
	v_pk_fma_f32 v[162:163], v[178:179], v[106:107], v[162:163] op_sel:[0,1,0] op_sel_hi:[1,1,1]
	v_pk_fma_f32 v[164:165], v[180:181], v[106:107], v[164:165] op_sel:[0,1,0] op_sel_hi:[1,1,1]
	v_pk_fma_f32 v[166:167], v[182:183], v[106:107], v[166:167] op_sel:[0,1,0] op_sel_hi:[1,1,1]
	v_pk_fma_f32 v[168:169], v[184:185], v[106:107], v[168:169] op_sel:[0,1,0] op_sel_hi:[1,1,1]
	ds_read_b128 v[178:181], v192 offset:28672
	ds_read_b128 v[182:185], v192 offset:29696
	s_waitcnt lgkmcnt(8)
	v_pk_fma_f32 v[162:163], v[130:131], v[108:109], v[162:163] op_sel_hi:[1,0,1]
	v_pk_fma_f32 v[164:165], v[132:133], v[108:109], v[164:165] op_sel_hi:[1,0,1]
	v_pk_fma_f32 v[166:167], v[134:135], v[108:109], v[166:167] op_sel_hi:[1,0,1]
	v_pk_fma_f32 v[168:169], v[136:137], v[108:109], v[168:169] op_sel_hi:[1,0,1]
	ds_read_b128 v[130:133], v192 offset:30720
	ds_read_b128 v[134:137], v192 offset:31744
	s_waitcnt lgkmcnt(8)
	v_pk_fma_f32 v[162:163], v[138:139], v[108:109], v[162:163] op_sel:[0,1,0] op_sel_hi:[1,1,1]
	v_pk_fma_f32 v[164:165], v[140:141], v[108:109], v[164:165] op_sel:[0,1,0] op_sel_hi:[1,1,1]
	v_pk_fma_f32 v[166:167], v[142:143], v[108:109], v[166:167] op_sel:[0,1,0] op_sel_hi:[1,1,1]
	v_pk_fma_f32 v[168:169], v[144:145], v[108:109], v[168:169] op_sel:[0,1,0] op_sel_hi:[1,1,1]
	ds_read_b128 v[138:141], v192 offset:32768
	ds_read_b128 v[142:145], v192 offset:33792
	s_waitcnt lgkmcnt(8)
	v_pk_fma_f32 v[162:163], v[146:147], v[110:111], v[162:163] op_sel_hi:[1,0,1]
	v_pk_fma_f32 v[164:165], v[148:149], v[110:111], v[164:165] op_sel_hi:[1,0,1]
	v_pk_fma_f32 v[166:167], v[150:151], v[110:111], v[166:167] op_sel_hi:[1,0,1]
	v_pk_fma_f32 v[168:169], v[152:153], v[110:111], v[168:169] op_sel_hi:[1,0,1]
	ds_read_b128 v[146:149], v192 offset:34816
	ds_read_b128 v[150:153], v192 offset:35840
	s_waitcnt lgkmcnt(8)
	v_pk_fma_f32 v[162:163], v[154:155], v[110:111], v[162:163] op_sel:[0,1,0] op_sel_hi:[1,1,1]
	v_pk_fma_f32 v[164:165], v[156:157], v[110:111], v[164:165] op_sel:[0,1,0] op_sel_hi:[1,1,1]
	v_pk_fma_f32 v[166:167], v[158:159], v[110:111], v[166:167] op_sel:[0,1,0] op_sel_hi:[1,1,1]
	v_pk_fma_f32 v[168:169], v[160:161], v[110:111], v[168:169] op_sel:[0,1,0] op_sel_hi:[1,1,1]
	ds_read_b128 v[154:157], v192 offset:36864
	ds_read_b128 v[158:161], v192 offset:37888
	s_waitcnt lgkmcnt(8)
	v_pk_fma_f32 v[162:163], v[178:179], v[112:113], v[162:163] op_sel_hi:[1,0,1]
	v_pk_fma_f32 v[164:165], v[180:181], v[112:113], v[164:165] op_sel_hi:[1,0,1]
	v_pk_fma_f32 v[166:167], v[182:183], v[112:113], v[166:167] op_sel_hi:[1,0,1]
	v_pk_fma_f32 v[168:169], v[184:185], v[112:113], v[168:169] op_sel_hi:[1,0,1]
	ds_read_b128 v[178:181], v192 offset:38912
	ds_read_b128 v[182:185], v192 offset:39936
	s_waitcnt lgkmcnt(8)
	v_pk_fma_f32 v[162:163], v[130:131], v[112:113], v[162:163] op_sel:[0,1,0] op_sel_hi:[1,1,1]
	v_pk_fma_f32 v[164:165], v[132:133], v[112:113], v[164:165] op_sel:[0,1,0] op_sel_hi:[1,1,1]
	v_pk_fma_f32 v[166:167], v[134:135], v[112:113], v[166:167] op_sel:[0,1,0] op_sel_hi:[1,1,1]
	v_pk_fma_f32 v[168:169], v[136:137], v[112:113], v[168:169] op_sel:[0,1,0] op_sel_hi:[1,1,1]
	ds_read_b128 v[130:133], v192 offset:40960
	ds_read_b128 v[134:137], v192 offset:41984
	s_waitcnt lgkmcnt(8)
	v_pk_fma_f32 v[162:163], v[138:139], v[114:115], v[162:163] op_sel_hi:[1,0,1]
	v_pk_fma_f32 v[164:165], v[140:141], v[114:115], v[164:165] op_sel_hi:[1,0,1]
	v_pk_fma_f32 v[166:167], v[142:143], v[114:115], v[166:167] op_sel_hi:[1,0,1]
	v_pk_fma_f32 v[168:169], v[144:145], v[114:115], v[168:169] op_sel_hi:[1,0,1]
	ds_read_b128 v[138:141], v192 offset:43008
	ds_read_b128 v[142:145], v192 offset:44032
	s_waitcnt lgkmcnt(8)
	v_pk_fma_f32 v[162:163], v[146:147], v[114:115], v[162:163] op_sel:[0,1,0] op_sel_hi:[1,1,1]
	v_pk_fma_f32 v[164:165], v[148:149], v[114:115], v[164:165] op_sel:[0,1,0] op_sel_hi:[1,1,1]
	v_pk_fma_f32 v[166:167], v[150:151], v[114:115], v[166:167] op_sel:[0,1,0] op_sel_hi:[1,1,1]
	v_pk_fma_f32 v[168:169], v[152:153], v[114:115], v[168:169] op_sel:[0,1,0] op_sel_hi:[1,1,1]
	ds_read_b128 v[146:149], v192 offset:45056
	ds_read_b128 v[150:153], v192 offset:46080
	s_waitcnt lgkmcnt(8)
	v_pk_fma_f32 v[162:163], v[154:155], v[116:117], v[162:163] op_sel_hi:[1,0,1]
	v_pk_fma_f32 v[164:165], v[156:157], v[116:117], v[164:165] op_sel_hi:[1,0,1]
	v_pk_fma_f32 v[166:167], v[158:159], v[116:117], v[166:167] op_sel_hi:[1,0,1]
	v_pk_fma_f32 v[168:169], v[160:161], v[116:117], v[168:169] op_sel_hi:[1,0,1]
	ds_read_b128 v[154:157], v192 offset:47104
	ds_read_b128 v[158:161], v192 offset:48128
	s_waitcnt lgkmcnt(8)
	v_pk_fma_f32 v[162:163], v[178:179], v[116:117], v[162:163] op_sel:[0,1,0] op_sel_hi:[1,1,1]
	v_pk_fma_f32 v[164:165], v[180:181], v[116:117], v[164:165] op_sel:[0,1,0] op_sel_hi:[1,1,1]
	v_pk_fma_f32 v[166:167], v[182:183], v[116:117], v[166:167] op_sel:[0,1,0] op_sel_hi:[1,1,1]
	v_pk_fma_f32 v[168:169], v[184:185], v[116:117], v[168:169] op_sel:[0,1,0] op_sel_hi:[1,1,1]
	ds_read_b128 v[178:181], v192 offset:49152
	ds_read_b128 v[182:185], v192 offset:50176
	s_waitcnt lgkmcnt(8)
	v_pk_fma_f32 v[162:163], v[130:131], v[118:119], v[162:163] op_sel_hi:[1,0,1]
	v_pk_fma_f32 v[164:165], v[132:133], v[118:119], v[164:165] op_sel_hi:[1,0,1]
	v_pk_fma_f32 v[166:167], v[134:135], v[118:119], v[166:167] op_sel_hi:[1,0,1]
	v_pk_fma_f32 v[168:169], v[136:137], v[118:119], v[168:169] op_sel_hi:[1,0,1]
	ds_read_b128 v[130:133], v192 offset:51200
	ds_read_b128 v[134:137], v192 offset:52224
	s_waitcnt lgkmcnt(8)
	v_pk_fma_f32 v[162:163], v[138:139], v[118:119], v[162:163] op_sel:[0,1,0] op_sel_hi:[1,1,1]
	v_pk_fma_f32 v[164:165], v[140:141], v[118:119], v[164:165] op_sel:[0,1,0] op_sel_hi:[1,1,1]
	v_pk_fma_f32 v[166:167], v[142:143], v[118:119], v[166:167] op_sel:[0,1,0] op_sel_hi:[1,1,1]
	v_pk_fma_f32 v[168:169], v[144:145], v[118:119], v[168:169] op_sel:[0,1,0] op_sel_hi:[1,1,1]
	ds_read_b128 v[138:141], v192 offset:53248
	ds_read_b128 v[142:145], v192 offset:54272
	s_waitcnt lgkmcnt(8)
	v_pk_fma_f32 v[162:163], v[146:147], v[120:121], v[162:163] op_sel_hi:[1,0,1]
	v_pk_fma_f32 v[164:165], v[148:149], v[120:121], v[164:165] op_sel_hi:[1,0,1]
	v_pk_fma_f32 v[166:167], v[150:151], v[120:121], v[166:167] op_sel_hi:[1,0,1]
	v_pk_fma_f32 v[168:169], v[152:153], v[120:121], v[168:169] op_sel_hi:[1,0,1]
	ds_read_b128 v[146:149], v192 offset:55296
	ds_read_b128 v[150:153], v192 offset:56320
	s_waitcnt lgkmcnt(8)
	v_pk_fma_f32 v[162:163], v[154:155], v[120:121], v[162:163] op_sel:[0,1,0] op_sel_hi:[1,1,1]
	v_pk_fma_f32 v[164:165], v[156:157], v[120:121], v[164:165] op_sel:[0,1,0] op_sel_hi:[1,1,1]
	v_pk_fma_f32 v[166:167], v[158:159], v[120:121], v[166:167] op_sel:[0,1,0] op_sel_hi:[1,1,1]
	v_pk_fma_f32 v[168:169], v[160:161], v[120:121], v[168:169] op_sel:[0,1,0] op_sel_hi:[1,1,1]
	ds_read_b128 v[154:157], v192 offset:57344
	ds_read_b128 v[158:161], v192 offset:58368
	s_waitcnt lgkmcnt(8)
	v_pk_fma_f32 v[162:163], v[178:179], v[122:123], v[162:163] op_sel_hi:[1,0,1]
	v_pk_fma_f32 v[164:165], v[180:181], v[122:123], v[164:165] op_sel_hi:[1,0,1]
	v_pk_fma_f32 v[166:167], v[182:183], v[122:123], v[166:167] op_sel_hi:[1,0,1]
	v_pk_fma_f32 v[168:169], v[184:185], v[122:123], v[168:169] op_sel_hi:[1,0,1]
	ds_read_b128 v[178:181], v192 offset:59392
	ds_read_b128 v[182:185], v192 offset:60416
	s_waitcnt lgkmcnt(8)
	v_pk_fma_f32 v[162:163], v[130:131], v[122:123], v[162:163] op_sel:[0,1,0] op_sel_hi:[1,1,1]
	v_pk_fma_f32 v[164:165], v[132:133], v[122:123], v[164:165] op_sel:[0,1,0] op_sel_hi:[1,1,1]
	v_pk_fma_f32 v[166:167], v[134:135], v[122:123], v[166:167] op_sel:[0,1,0] op_sel_hi:[1,1,1]
	v_pk_fma_f32 v[168:169], v[136:137], v[122:123], v[168:169] op_sel:[0,1,0] op_sel_hi:[1,1,1]
	ds_read_b128 v[130:133], v192 offset:61440
	ds_read_b128 v[134:137], v192 offset:62464
	s_waitcnt lgkmcnt(8)
	v_pk_fma_f32 v[162:163], v[138:139], v[124:125], v[162:163] op_sel_hi:[1,0,1]
	v_pk_fma_f32 v[164:165], v[140:141], v[124:125], v[164:165] op_sel_hi:[1,0,1]
	v_pk_fma_f32 v[166:167], v[142:143], v[124:125], v[166:167] op_sel_hi:[1,0,1]
	v_pk_fma_f32 v[168:169], v[144:145], v[124:125], v[168:169] op_sel_hi:[1,0,1]
	ds_read_b128 v[138:141], v192 offset:63488
	ds_read_b128 v[142:145], v192 offset:64512
	s_waitcnt lgkmcnt(8)
	v_pk_fma_f32 v[162:163], v[146:147], v[124:125], v[162:163] op_sel:[0,1,0] op_sel_hi:[1,1,1]
	v_pk_fma_f32 v[164:165], v[148:149], v[124:125], v[164:165] op_sel:[0,1,0] op_sel_hi:[1,1,1]
	v_pk_fma_f32 v[166:167], v[150:151], v[124:125], v[166:167] op_sel:[0,1,0] op_sel_hi:[1,1,1]
	v_pk_fma_f32 v[168:169], v[152:153], v[124:125], v[168:169] op_sel:[0,1,0] op_sel_hi:[1,1,1]
	s_waitcnt lgkmcnt(6)
	v_pk_fma_f32 v[162:163], v[154:155], v[126:127], v[162:163] op_sel_hi:[1,0,1]
	v_pk_fma_f32 v[164:165], v[156:157], v[126:127], v[164:165] op_sel_hi:[1,0,1]
	v_pk_fma_f32 v[166:167], v[158:159], v[126:127], v[166:167] op_sel_hi:[1,0,1]
	v_pk_fma_f32 v[168:169], v[160:161], v[126:127], v[168:169] op_sel_hi:[1,0,1]
	s_waitcnt lgkmcnt(4)
	v_pk_fma_f32 v[162:163], v[178:179], v[126:127], v[162:163] op_sel:[0,1,0] op_sel_hi:[1,1,1]
	v_pk_fma_f32 v[164:165], v[180:181], v[126:127], v[164:165] op_sel:[0,1,0] op_sel_hi:[1,1,1]
	v_pk_fma_f32 v[166:167], v[182:183], v[126:127], v[166:167] op_sel:[0,1,0] op_sel_hi:[1,1,1]
	v_pk_fma_f32 v[168:169], v[184:185], v[126:127], v[168:169] op_sel:[0,1,0] op_sel_hi:[1,1,1]
	s_waitcnt lgkmcnt(2)
	v_pk_fma_f32 v[162:163], v[130:131], v[128:129], v[162:163] op_sel_hi:[1,0,1]
	v_pk_fma_f32 v[164:165], v[132:133], v[128:129], v[164:165] op_sel_hi:[1,0,1]
	v_pk_fma_f32 v[166:167], v[134:135], v[128:129], v[166:167] op_sel_hi:[1,0,1]
	v_pk_fma_f32 v[168:169], v[136:137], v[128:129], v[168:169] op_sel_hi:[1,0,1]
	s_waitcnt lgkmcnt(0)
	v_pk_fma_f32 v[162:163], v[138:139], v[128:129], v[162:163] op_sel:[0,1,0] op_sel_hi:[1,1,1]
	v_pk_fma_f32 v[164:165], v[140:141], v[128:129], v[164:165] op_sel:[0,1,0] op_sel_hi:[1,1,1]
	v_pk_fma_f32 v[166:167], v[142:143], v[128:129], v[166:167] op_sel:[0,1,0] op_sel_hi:[1,1,1]
	v_pk_fma_f32 v[168:169], v[144:145], v[128:129], v[168:169] op_sel:[0,1,0] op_sel_hi:[1,1,1]
	s_nop 1
	v_add_f32_dpp v162, v162, v162 quad_perm:[1,0,3,2] row_mask:0xf bank_mask:0xf
	v_add_f32_dpp v163, v163, v163 quad_perm:[1,0,3,2] row_mask:0xf bank_mask:0xf
	v_add_f32_dpp v164, v164, v164 quad_perm:[1,0,3,2] row_mask:0xf bank_mask:0xf
	v_add_f32_dpp v165, v165, v165 quad_perm:[1,0,3,2] row_mask:0xf bank_mask:0xf
	v_add_f32_dpp v166, v166, v166 quad_perm:[1,0,3,2] row_mask:0xf bank_mask:0xf
	v_add_f32_dpp v167, v167, v167 quad_perm:[1,0,3,2] row_mask:0xf bank_mask:0xf
	v_add_f32_dpp v168, v168, v168 quad_perm:[1,0,3,2] row_mask:0xf bank_mask:0xf
	v_add_f32_dpp v169, v169, v169 quad_perm:[1,0,3,2] row_mask:0xf bank_mask:0xf
	v_add_f32_dpp v162, v162, v162 quad_perm:[2,3,0,1] row_mask:0xf bank_mask:0xf
	v_add_f32_dpp v163, v163, v163 quad_perm:[2,3,0,1] row_mask:0xf bank_mask:0xf
	v_add_f32_dpp v164, v164, v164 quad_perm:[2,3,0,1] row_mask:0xf bank_mask:0xf
	v_add_f32_dpp v165, v165, v165 quad_perm:[2,3,0,1] row_mask:0xf bank_mask:0xf
	v_add_f32_dpp v166, v166, v166 quad_perm:[2,3,0,1] row_mask:0xf bank_mask:0xf
	v_add_f32_dpp v167, v167, v167 quad_perm:[2,3,0,1] row_mask:0xf bank_mask:0xf
	v_add_f32_dpp v168, v168, v168 quad_perm:[2,3,0,1] row_mask:0xf bank_mask:0xf
	v_add_f32_dpp v169, v169, v169 quad_perm:[2,3,0,1] row_mask:0xf bank_mask:0xf
	v_add_f32_dpp v162, v162, v162 row_half_mirror row_mask:0xf bank_mask:0xf
	v_add_f32_dpp v163, v163, v163 row_half_mirror row_mask:0xf bank_mask:0xf
	v_add_f32_dpp v164, v164, v164 row_half_mirror row_mask:0xf bank_mask:0xf
	v_add_f32_dpp v165, v165, v165 row_half_mirror row_mask:0xf bank_mask:0xf
	v_add_f32_dpp v166, v166, v166 row_half_mirror row_mask:0xf bank_mask:0xf
	v_add_f32_dpp v167, v167, v167 row_half_mirror row_mask:0xf bank_mask:0xf
	v_add_f32_dpp v168, v168, v168 row_half_mirror row_mask:0xf bank_mask:0xf
	v_add_f32_dpp v169, v169, v169 row_half_mirror row_mask:0xf bank_mask:0xf
	v_add_f32_dpp v162, v162, v162 row_mirror row_mask:0xf bank_mask:0xf
	v_add_f32_dpp v163, v163, v163 row_mirror row_mask:0xf bank_mask:0xf
	v_add_f32_dpp v164, v164, v164 row_mirror row_mask:0xf bank_mask:0xf
	v_add_f32_dpp v165, v165, v165 row_mirror row_mask:0xf bank_mask:0xf
	v_add_f32_dpp v166, v166, v166 row_mirror row_mask:0xf bank_mask:0xf
	v_add_f32_dpp v167, v167, v167 row_mirror row_mask:0xf bank_mask:0xf
	v_add_f32_dpp v168, v168, v168 row_mirror row_mask:0xf bank_mask:0xf
	v_add_f32_dpp v169, v169, v169 row_mirror row_mask:0xf bank_mask:0xf
	v_mov_b32_e32 v170, v162
	v_mov_b32_e32 v171, v163
	v_mov_b32_e32 v172, v164
	v_mov_b32_e32 v173, v165
	v_mov_b32_e32 v174, v166
	v_mov_b32_e32 v175, v167
	v_mov_b32_e32 v176, v168
	v_mov_b32_e32 v177, v169
	v_permlane16_swap_b32 v170, v162
	v_permlane16_swap_b32 v171, v163
	v_permlane16_swap_b32 v172, v164
	v_permlane16_swap_b32 v173, v165
	v_permlane16_swap_b32 v174, v166
	v_permlane16_swap_b32 v175, v167
	v_permlane16_swap_b32 v176, v168
	v_permlane16_swap_b32 v177, v169
	v_add_f32_e32 v162, v162, v170
	v_add_f32_e32 v163, v163, v171
	v_add_f32_e32 v164, v164, v172
	v_add_f32_e32 v165, v165, v173
	v_add_f32_e32 v166, v166, v174
	v_add_f32_e32 v167, v167, v175
	v_add_f32_e32 v168, v168, v176
	v_add_f32_e32 v169, v169, v177
	v_mov_b32_e32 v170, v162
	v_mov_b32_e32 v171, v163
	v_mov_b32_e32 v172, v164
	v_mov_b32_e32 v173, v165
	v_mov_b32_e32 v174, v166
	v_mov_b32_e32 v175, v167
	v_mov_b32_e32 v176, v168
	v_mov_b32_e32 v177, v169
	v_permlane32_swap_b32 v170, v162
	v_permlane32_swap_b32 v171, v163
	v_permlane32_swap_b32 v172, v164
	v_permlane32_swap_b32 v173, v165
	v_permlane32_swap_b32 v174, v166
	v_permlane32_swap_b32 v175, v167
	v_permlane32_swap_b32 v176, v168
	v_permlane32_swap_b32 v177, v169
	v_add_f32_e32 v162, v162, v170
	v_add_f32_e32 v163, v163, v171
	v_add_f32_e32 v164, v164, v172
	v_add_f32_e32 v165, v165, v173
	v_add_f32_e32 v166, v166, v174
	v_add_f32_e32 v167, v167, v175
	v_add_f32_e32 v168, v168, v176
	v_add_f32_e32 v169, v169, v177
	v_readfirstlane_b32 s98, v162
	v_readfirstlane_b32 s99, v163
	v_readfirstlane_b32 s100, v164
	v_readfirstlane_b32 s101, v165
	v_writelane_b32 v230, s98, 0
	v_writelane_b32 v230, s99, 1
	v_writelane_b32 v230, s100, 2
	v_writelane_b32 v230, s101, 3
	v_readfirstlane_b32 s98, v166
	v_readfirstlane_b32 s99, v167
	v_readfirstlane_b32 s100, v168
	v_readfirstlane_b32 s101, v169
	v_writelane_b32 v230, s98, 4
	v_writelane_b32 v230, s99, 5
	v_writelane_b32 v230, s100, 6
	v_writelane_b32 v230, s101, 7
	s_waitcnt vmcnt(16)
	v_pk_mul_f32 v[198:199], v[66:67], v[66:67]
	v_pk_mul_f32 v[200:201], v[68:69], v[68:69]
	v_pk_fma_f32 v[198:199], v[70:71], v[70:71], v[198:199]
	v_pk_fma_f32 v[200:201], v[72:73], v[72:73], v[200:201]
	v_pk_fma_f32 v[198:199], v[74:75], v[74:75], v[198:199]
	v_pk_fma_f32 v[200:201], v[76:77], v[76:77], v[200:201]
	v_pk_fma_f32 v[198:199], v[78:79], v[78:79], v[198:199]
	v_pk_fma_f32 v[200:201], v[80:81], v[80:81], v[200:201]
	v_pk_fma_f32 v[198:199], v[82:83], v[82:83], v[198:199]
	v_pk_fma_f32 v[200:201], v[84:85], v[84:85], v[200:201]
	v_pk_fma_f32 v[198:199], v[86:87], v[86:87], v[198:199]
	v_pk_fma_f32 v[200:201], v[88:89], v[88:89], v[200:201]
	v_pk_fma_f32 v[198:199], v[90:91], v[90:91], v[198:199]
	v_pk_fma_f32 v[200:201], v[92:93], v[92:93], v[200:201]
	v_pk_fma_f32 v[198:199], v[94:95], v[94:95], v[198:199]
	v_pk_fma_f32 v[200:201], v[96:97], v[96:97], v[200:201]
	v_pk_add_f32 v[198:199], v[198:199], v[200:201]
	v_add_f32_e32 v198, v198, v199
	s_nop 1
	v_add_f32_dpp v198, v198, v198 quad_perm:[1,0,3,2] row_mask:0xf bank_mask:0xf
	s_nop 1
	v_add_f32_dpp v198, v198, v198 quad_perm:[2,3,0,1] row_mask:0xf bank_mask:0xf
	s_nop 1
	v_add_f32_dpp v198, v198, v198 row_half_mirror row_mask:0xf bank_mask:0xf
	s_nop 1
	v_add_f32_dpp v198, v198, v198 row_mirror row_mask:0xf bank_mask:0xf
	v_mov_b32_e32 v199, v198
	s_nop 1
	v_permlane16_swap_b32 v199, v198
	v_add_f32_e32 v198, v198, v199
	v_mov_b32_e32 v199, v198
	s_nop 1
	v_permlane32_swap_b32 v199, v198
	v_add_f32_e32 v198, v198, v199
	ds_read_b128 v[130:133], v192
	ds_read_b128 v[134:137], v192 offset:1024
	ds_read_b128 v[138:141], v192 offset:2048
	ds_read_b128 v[142:145], v192 offset:3072
	ds_read_b128 v[146:149], v192 offset:4096
	ds_read_b128 v[150:153], v192 offset:5120
	ds_read_b128 v[154:157], v192 offset:6144
	ds_read_b128 v[158:161], v192 offset:7168
	ds_read_b128 v[178:181], v192 offset:8192
	ds_read_b128 v[182:185], v192 offset:9216
	v_fmamk_f32 v198, v198, 0x3a000000, v241
	v_mul_f32_e32 v199, 0x4b800000, v198
	v_cmp_gt_f32_e32 vcc, s17, v198
	s_nop 1
	v_cndmask_b32_e32 v198, v198, v199, vcc
	v_rsq_f32_e32 v198, v198
	s_nop 0
	v_mul_f32_e32 v199, 0x45800000, v198
	v_cndmask_b32_e32 v202, v198, v199, vcc
	v_pk_mul_f32 v[98:99], v[66:67], v[202:203] op_sel_hi:[1,0]
	v_pk_mul_f32 v[98:99], v[2:3], v[98:99]
	v_pk_mul_f32 v[100:101], v[68:69], v[202:203] op_sel_hi:[1,0]
	v_pk_mul_f32 v[100:101], v[4:5], v[100:101]
	v_cvt_pk_bf16_f32 v206, v98, v99
	v_cvt_pk_bf16_f32 v207, v100, v101
	global_store_dwordx2 v194, v[206:207], s[52:53]
	v_pk_mul_f32 v[102:103], v[70:71], v[202:203] op_sel_hi:[1,0]
	v_pk_mul_f32 v[102:103], v[6:7], v[102:103]
	v_pk_mul_f32 v[104:105], v[72:73], v[202:203] op_sel_hi:[1,0]
	v_pk_mul_f32 v[104:105], v[8:9], v[104:105]
	v_cvt_pk_bf16_f32 v206, v102, v103
	v_cvt_pk_bf16_f32 v207, v104, v105
	global_store_dwordx2 v194, v[206:207], s[52:53] offset:512
	v_pk_mul_f32 v[106:107], v[74:75], v[202:203] op_sel_hi:[1,0]
	v_pk_mul_f32 v[106:107], v[10:11], v[106:107]
	v_pk_mul_f32 v[108:109], v[76:77], v[202:203] op_sel_hi:[1,0]
	v_pk_mul_f32 v[108:109], v[12:13], v[108:109]
	v_cvt_pk_bf16_f32 v206, v106, v107
	v_cvt_pk_bf16_f32 v207, v108, v109
	global_store_dwordx2 v194, v[206:207], s[52:53] offset:1024
	v_pk_mul_f32 v[110:111], v[78:79], v[202:203] op_sel_hi:[1,0]
	v_pk_mul_f32 v[110:111], v[14:15], v[110:111]
	v_pk_mul_f32 v[112:113], v[80:81], v[202:203] op_sel_hi:[1,0]
	v_pk_mul_f32 v[112:113], v[16:17], v[112:113]
	v_cvt_pk_bf16_f32 v206, v110, v111
	v_cvt_pk_bf16_f32 v207, v112, v113
	global_store_dwordx2 v194, v[206:207], s[52:53] offset:1536
	v_pk_mul_f32 v[114:115], v[82:83], v[202:203] op_sel_hi:[1,0]
	v_pk_mul_f32 v[114:115], v[18:19], v[114:115]
	v_pk_mul_f32 v[116:117], v[84:85], v[202:203] op_sel_hi:[1,0]
	v_pk_mul_f32 v[116:117], v[20:21], v[116:117]
	v_cvt_pk_bf16_f32 v206, v114, v115
	v_cvt_pk_bf16_f32 v207, v116, v117
	global_store_dwordx2 v194, v[206:207], s[52:53] offset:2048
	v_pk_mul_f32 v[118:119], v[86:87], v[202:203] op_sel_hi:[1,0]
	v_pk_mul_f32 v[118:119], v[22:23], v[118:119]
	v_pk_mul_f32 v[120:121], v[88:89], v[202:203] op_sel_hi:[1,0]
	v_pk_mul_f32 v[120:121], v[24:25], v[120:121]
	v_cvt_pk_bf16_f32 v206, v118, v119
	v_cvt_pk_bf16_f32 v207, v120, v121
	global_store_dwordx2 v194, v[206:207], s[52:53] offset:2560
	v_pk_mul_f32 v[122:123], v[90:91], v[202:203] op_sel_hi:[1,0]
	v_pk_mul_f32 v[122:123], v[26:27], v[122:123]
	v_pk_mul_f32 v[124:125], v[92:93], v[202:203] op_sel_hi:[1,0]
	v_pk_mul_f32 v[124:125], v[28:29], v[124:125]
	v_cvt_pk_bf16_f32 v206, v122, v123
	v_cvt_pk_bf16_f32 v207, v124, v125
	global_store_dwordx2 v194, v[206:207], s[52:53] offset:3072
	v_pk_mul_f32 v[126:127], v[94:95], v[202:203] op_sel_hi:[1,0]
	v_pk_mul_f32 v[126:127], v[30:31], v[126:127]
	v_pk_mul_f32 v[128:129], v[96:97], v[202:203] op_sel_hi:[1,0]
	v_pk_mul_f32 v[128:129], v[32:33], v[128:129]
	v_cvt_pk_bf16_f32 v206, v126, v127
	v_cvt_pk_bf16_f32 v207, v128, v129
	global_store_dwordx2 v194, v[206:207], s[52:53] offset:3584
	v_add_u32_e32 v194, 0x800000, v194
	global_load_dwordx4 v[66:69], v193, s[12:13] offset:-4096 nt
	global_load_dwordx4 v[70:73], v193, s[12:13] offset:-3072 nt
	global_load_dwordx4 v[74:77], v193, s[12:13] offset:-2048 nt
	global_load_dwordx4 v[78:81], v193, s[12:13] offset:-1024 nt
	global_load_dwordx4 v[82:85], v193, s[12:13] offset:0 nt
	global_load_dwordx4 v[86:89], v193, s[12:13] offset:1024 nt
	global_load_dwordx4 v[90:93], v193, s[12:13] offset:2048 nt
	global_load_dwordx4 v[94:97], v193, s[12:13] offset:3072 nt
	v_add_u32_e32 v193, s0, v193
	s_waitcnt lgkmcnt(8)
	v_pk_mul_f32 v[162:163], v[130:131], v[98:99] op_sel_hi:[1,0]
	v_pk_mul_f32 v[164:165], v[132:133], v[98:99] op_sel_hi:[1,0]
	v_pk_mul_f32 v[166:167], v[134:135], v[98:99] op_sel_hi:[1,0]
	v_pk_mul_f32 v[168:169], v[136:137], v[98:99] op_sel_hi:[1,0]
	ds_read_b128 v[130:133], v192 offset:10240
	ds_read_b128 v[134:137], v192 offset:11264
	s_waitcnt lgkmcnt(8)
	v_pk_fma_f32 v[162:163], v[138:139], v[98:99], v[162:163] op_sel:[0,1,0] op_sel_hi:[1,1,1]
	v_pk_fma_f32 v[164:165], v[140:141], v[98:99], v[164:165] op_sel:[0,1,0] op_sel_hi:[1,1,1]
	v_pk_fma_f32 v[166:167], v[142:143], v[98:99], v[166:167] op_sel:[0,1,0] op_sel_hi:[1,1,1]
	v_pk_fma_f32 v[168:169], v[144:145], v[98:99], v[168:169] op_sel:[0,1,0] op_sel_hi:[1,1,1]
	ds_read_b128 v[138:141], v192 offset:12288
	ds_read_b128 v[142:145], v192 offset:13312
	s_waitcnt lgkmcnt(8)
	v_pk_fma_f32 v[162:163], v[146:147], v[100:101], v[162:163] op_sel_hi:[1,0,1]
	v_pk_fma_f32 v[164:165], v[148:149], v[100:101], v[164:165] op_sel_hi:[1,0,1]
	v_pk_fma_f32 v[166:167], v[150:151], v[100:101], v[166:167] op_sel_hi:[1,0,1]
	v_pk_fma_f32 v[168:169], v[152:153], v[100:101], v[168:169] op_sel_hi:[1,0,1]
	ds_read_b128 v[146:149], v192 offset:14336
	ds_read_b128 v[150:153], v192 offset:15360
	s_waitcnt lgkmcnt(8)
	v_pk_fma_f32 v[162:163], v[154:155], v[100:101], v[162:163] op_sel:[0,1,0] op_sel_hi:[1,1,1]
	v_pk_fma_f32 v[164:165], v[156:157], v[100:101], v[164:165] op_sel:[0,1,0] op_sel_hi:[1,1,1]
	v_pk_fma_f32 v[166:167], v[158:159], v[100:101], v[166:167] op_sel:[0,1,0] op_sel_hi:[1,1,1]
	v_pk_fma_f32 v[168:169], v[160:161], v[100:101], v[168:169] op_sel:[0,1,0] op_sel_hi:[1,1,1]
	ds_read_b128 v[154:157], v192 offset:16384
	ds_read_b128 v[158:161], v192 offset:17408
	s_waitcnt lgkmcnt(8)
	v_pk_fma_f32 v[162:163], v[178:179], v[102:103], v[162:163] op_sel_hi:[1,0,1]
	v_pk_fma_f32 v[164:165], v[180:181], v[102:103], v[164:165] op_sel_hi:[1,0,1]
	v_pk_fma_f32 v[166:167], v[182:183], v[102:103], v[166:167] op_sel_hi:[1,0,1]
	v_pk_fma_f32 v[168:169], v[184:185], v[102:103], v[168:169] op_sel_hi:[1,0,1]
	ds_read_b128 v[178:181], v192 offset:18432
	ds_read_b128 v[182:185], v192 offset:19456
	s_waitcnt lgkmcnt(8)
	v_pk_fma_f32 v[162:163], v[130:131], v[102:103], v[162:163] op_sel:[0,1,0] op_sel_hi:[1,1,1]
	v_pk_fma_f32 v[164:165], v[132:133], v[102:103], v[164:165] op_sel:[0,1,0] op_sel_hi:[1,1,1]
	v_pk_fma_f32 v[166:167], v[134:135], v[102:103], v[166:167] op_sel:[0,1,0] op_sel_hi:[1,1,1]
	v_pk_fma_f32 v[168:169], v[136:137], v[102:103], v[168:169] op_sel:[0,1,0] op_sel_hi:[1,1,1]
	ds_read_b128 v[130:133], v192 offset:20480
	ds_read_b128 v[134:137], v192 offset:21504
	s_waitcnt lgkmcnt(8)
	v_pk_fma_f32 v[162:163], v[138:139], v[104:105], v[162:163] op_sel_hi:[1,0,1]
	v_pk_fma_f32 v[164:165], v[140:141], v[104:105], v[164:165] op_sel_hi:[1,0,1]
	v_pk_fma_f32 v[166:167], v[142:143], v[104:105], v[166:167] op_sel_hi:[1,0,1]
	v_pk_fma_f32 v[168:169], v[144:145], v[104:105], v[168:169] op_sel_hi:[1,0,1]
	ds_read_b128 v[138:141], v192 offset:22528
	ds_read_b128 v[142:145], v192 offset:23552
	s_waitcnt lgkmcnt(8)
	v_pk_fma_f32 v[162:163], v[146:147], v[104:105], v[162:163] op_sel:[0,1,0] op_sel_hi:[1,1,1]
	v_pk_fma_f32 v[164:165], v[148:149], v[104:105], v[164:165] op_sel:[0,1,0] op_sel_hi:[1,1,1]
	v_pk_fma_f32 v[166:167], v[150:151], v[104:105], v[166:167] op_sel:[0,1,0] op_sel_hi:[1,1,1]
	v_pk_fma_f32 v[168:169], v[152:153], v[104:105], v[168:169] op_sel:[0,1,0] op_sel_hi:[1,1,1]
	ds_read_b128 v[146:149], v192 offset:24576
	ds_read_b128 v[150:153], v192 offset:25600
	s_waitcnt lgkmcnt(8)
	v_pk_fma_f32 v[162:163], v[154:155], v[106:107], v[162:163] op_sel_hi:[1,0,1]
	v_pk_fma_f32 v[164:165], v[156:157], v[106:107], v[164:165] op_sel_hi:[1,0,1]
	v_pk_fma_f32 v[166:167], v[158:159], v[106:107], v[166:167] op_sel_hi:[1,0,1]
	v_pk_fma_f32 v[168:169], v[160:161], v[106:107], v[168:169] op_sel_hi:[1,0,1]
	ds_read_b128 v[154:157], v192 offset:26624
	ds_read_b128 v[158:161], v192 offset:27648
	s_waitcnt lgkmcnt(8)
	v_pk_fma_f32 v[162:163], v[178:179], v[106:107], v[162:163] op_sel:[0,1,0] op_sel_hi:[1,1,1]
	v_pk_fma_f32 v[164:165], v[180:181], v[106:107], v[164:165] op_sel:[0,1,0] op_sel_hi:[1,1,1]
	v_pk_fma_f32 v[166:167], v[182:183], v[106:107], v[166:167] op_sel:[0,1,0] op_sel_hi:[1,1,1]
	v_pk_fma_f32 v[168:169], v[184:185], v[106:107], v[168:169] op_sel:[0,1,0] op_sel_hi:[1,1,1]
	ds_read_b128 v[178:181], v192 offset:28672
	ds_read_b128 v[182:185], v192 offset:29696
	s_waitcnt lgkmcnt(8)
	v_pk_fma_f32 v[162:163], v[130:131], v[108:109], v[162:163] op_sel_hi:[1,0,1]
	v_pk_fma_f32 v[164:165], v[132:133], v[108:109], v[164:165] op_sel_hi:[1,0,1]
	v_pk_fma_f32 v[166:167], v[134:135], v[108:109], v[166:167] op_sel_hi:[1,0,1]
	v_pk_fma_f32 v[168:169], v[136:137], v[108:109], v[168:169] op_sel_hi:[1,0,1]
	ds_read_b128 v[130:133], v192 offset:30720
	ds_read_b128 v[134:137], v192 offset:31744
	s_waitcnt lgkmcnt(8)
	v_pk_fma_f32 v[162:163], v[138:139], v[108:109], v[162:163] op_sel:[0,1,0] op_sel_hi:[1,1,1]
	v_pk_fma_f32 v[164:165], v[140:141], v[108:109], v[164:165] op_sel:[0,1,0] op_sel_hi:[1,1,1]
	v_pk_fma_f32 v[166:167], v[142:143], v[108:109], v[166:167] op_sel:[0,1,0] op_sel_hi:[1,1,1]
	v_pk_fma_f32 v[168:169], v[144:145], v[108:109], v[168:169] op_sel:[0,1,0] op_sel_hi:[1,1,1]
	ds_read_b128 v[138:141], v192 offset:32768
	ds_read_b128 v[142:145], v192 offset:33792
	s_waitcnt lgkmcnt(8)
	v_pk_fma_f32 v[162:163], v[146:147], v[110:111], v[162:163] op_sel_hi:[1,0,1]
	v_pk_fma_f32 v[164:165], v[148:149], v[110:111], v[164:165] op_sel_hi:[1,0,1]
	v_pk_fma_f32 v[166:167], v[150:151], v[110:111], v[166:167] op_sel_hi:[1,0,1]
	v_pk_fma_f32 v[168:169], v[152:153], v[110:111], v[168:169] op_sel_hi:[1,0,1]
	ds_read_b128 v[146:149], v192 offset:34816
	ds_read_b128 v[150:153], v192 offset:35840
	s_waitcnt lgkmcnt(8)
	v_pk_fma_f32 v[162:163], v[154:155], v[110:111], v[162:163] op_sel:[0,1,0] op_sel_hi:[1,1,1]
	v_pk_fma_f32 v[164:165], v[156:157], v[110:111], v[164:165] op_sel:[0,1,0] op_sel_hi:[1,1,1]
	v_pk_fma_f32 v[166:167], v[158:159], v[110:111], v[166:167] op_sel:[0,1,0] op_sel_hi:[1,1,1]
	v_pk_fma_f32 v[168:169], v[160:161], v[110:111], v[168:169] op_sel:[0,1,0] op_sel_hi:[1,1,1]
	ds_read_b128 v[154:157], v192 offset:36864
	ds_read_b128 v[158:161], v192 offset:37888
	s_waitcnt lgkmcnt(8)
	v_pk_fma_f32 v[162:163], v[178:179], v[112:113], v[162:163] op_sel_hi:[1,0,1]
	v_pk_fma_f32 v[164:165], v[180:181], v[112:113], v[164:165] op_sel_hi:[1,0,1]
	v_pk_fma_f32 v[166:167], v[182:183], v[112:113], v[166:167] op_sel_hi:[1,0,1]
	v_pk_fma_f32 v[168:169], v[184:185], v[112:113], v[168:169] op_sel_hi:[1,0,1]
	ds_read_b128 v[178:181], v192 offset:38912
	ds_read_b128 v[182:185], v192 offset:39936
	s_waitcnt lgkmcnt(8)
	v_pk_fma_f32 v[162:163], v[130:131], v[112:113], v[162:163] op_sel:[0,1,0] op_sel_hi:[1,1,1]
	v_pk_fma_f32 v[164:165], v[132:133], v[112:113], v[164:165] op_sel:[0,1,0] op_sel_hi:[1,1,1]
	v_pk_fma_f32 v[166:167], v[134:135], v[112:113], v[166:167] op_sel:[0,1,0] op_sel_hi:[1,1,1]
	v_pk_fma_f32 v[168:169], v[136:137], v[112:113], v[168:169] op_sel:[0,1,0] op_sel_hi:[1,1,1]
	ds_read_b128 v[130:133], v192 offset:40960
	ds_read_b128 v[134:137], v192 offset:41984
	s_waitcnt lgkmcnt(8)
	v_pk_fma_f32 v[162:163], v[138:139], v[114:115], v[162:163] op_sel_hi:[1,0,1]
	v_pk_fma_f32 v[164:165], v[140:141], v[114:115], v[164:165] op_sel_hi:[1,0,1]
	v_pk_fma_f32 v[166:167], v[142:143], v[114:115], v[166:167] op_sel_hi:[1,0,1]
	v_pk_fma_f32 v[168:169], v[144:145], v[114:115], v[168:169] op_sel_hi:[1,0,1]
	ds_read_b128 v[138:141], v192 offset:43008
	ds_read_b128 v[142:145], v192 offset:44032
	s_waitcnt lgkmcnt(8)
	v_pk_fma_f32 v[162:163], v[146:147], v[114:115], v[162:163] op_sel:[0,1,0] op_sel_hi:[1,1,1]
	v_pk_fma_f32 v[164:165], v[148:149], v[114:115], v[164:165] op_sel:[0,1,0] op_sel_hi:[1,1,1]
	v_pk_fma_f32 v[166:167], v[150:151], v[114:115], v[166:167] op_sel:[0,1,0] op_sel_hi:[1,1,1]
	v_pk_fma_f32 v[168:169], v[152:153], v[114:115], v[168:169] op_sel:[0,1,0] op_sel_hi:[1,1,1]
	ds_read_b128 v[146:149], v192 offset:45056
	ds_read_b128 v[150:153], v192 offset:46080
	s_waitcnt lgkmcnt(8)
	v_pk_fma_f32 v[162:163], v[154:155], v[116:117], v[162:163] op_sel_hi:[1,0,1]
	v_pk_fma_f32 v[164:165], v[156:157], v[116:117], v[164:165] op_sel_hi:[1,0,1]
	v_pk_fma_f32 v[166:167], v[158:159], v[116:117], v[166:167] op_sel_hi:[1,0,1]
	v_pk_fma_f32 v[168:169], v[160:161], v[116:117], v[168:169] op_sel_hi:[1,0,1]
	ds_read_b128 v[154:157], v192 offset:47104
	ds_read_b128 v[158:161], v192 offset:48128
	s_waitcnt lgkmcnt(8)
	v_pk_fma_f32 v[162:163], v[178:179], v[116:117], v[162:163] op_sel:[0,1,0] op_sel_hi:[1,1,1]
	v_pk_fma_f32 v[164:165], v[180:181], v[116:117], v[164:165] op_sel:[0,1,0] op_sel_hi:[1,1,1]
	v_pk_fma_f32 v[166:167], v[182:183], v[116:117], v[166:167] op_sel:[0,1,0] op_sel_hi:[1,1,1]
	v_pk_fma_f32 v[168:169], v[184:185], v[116:117], v[168:169] op_sel:[0,1,0] op_sel_hi:[1,1,1]
	ds_read_b128 v[178:181], v192 offset:49152
	ds_read_b128 v[182:185], v192 offset:50176
	s_waitcnt lgkmcnt(8)
	v_pk_fma_f32 v[162:163], v[130:131], v[118:119], v[162:163] op_sel_hi:[1,0,1]
	v_pk_fma_f32 v[164:165], v[132:133], v[118:119], v[164:165] op_sel_hi:[1,0,1]
	v_pk_fma_f32 v[166:167], v[134:135], v[118:119], v[166:167] op_sel_hi:[1,0,1]
	v_pk_fma_f32 v[168:169], v[136:137], v[118:119], v[168:169] op_sel_hi:[1,0,1]
	ds_read_b128 v[130:133], v192 offset:51200
	ds_read_b128 v[134:137], v192 offset:52224
	s_waitcnt lgkmcnt(8)
	v_pk_fma_f32 v[162:163], v[138:139], v[118:119], v[162:163] op_sel:[0,1,0] op_sel_hi:[1,1,1]
	v_pk_fma_f32 v[164:165], v[140:141], v[118:119], v[164:165] op_sel:[0,1,0] op_sel_hi:[1,1,1]
	v_pk_fma_f32 v[166:167], v[142:143], v[118:119], v[166:167] op_sel:[0,1,0] op_sel_hi:[1,1,1]
	v_pk_fma_f32 v[168:169], v[144:145], v[118:119], v[168:169] op_sel:[0,1,0] op_sel_hi:[1,1,1]
	ds_read_b128 v[138:141], v192 offset:53248
	ds_read_b128 v[142:145], v192 offset:54272
	s_waitcnt lgkmcnt(8)
	v_pk_fma_f32 v[162:163], v[146:147], v[120:121], v[162:163] op_sel_hi:[1,0,1]
	v_pk_fma_f32 v[164:165], v[148:149], v[120:121], v[164:165] op_sel_hi:[1,0,1]
	v_pk_fma_f32 v[166:167], v[150:151], v[120:121], v[166:167] op_sel_hi:[1,0,1]
	v_pk_fma_f32 v[168:169], v[152:153], v[120:121], v[168:169] op_sel_hi:[1,0,1]
	ds_read_b128 v[146:149], v192 offset:55296
	ds_read_b128 v[150:153], v192 offset:56320
	s_waitcnt lgkmcnt(8)
	v_pk_fma_f32 v[162:163], v[154:155], v[120:121], v[162:163] op_sel:[0,1,0] op_sel_hi:[1,1,1]
	v_pk_fma_f32 v[164:165], v[156:157], v[120:121], v[164:165] op_sel:[0,1,0] op_sel_hi:[1,1,1]
	v_pk_fma_f32 v[166:167], v[158:159], v[120:121], v[166:167] op_sel:[0,1,0] op_sel_hi:[1,1,1]
	v_pk_fma_f32 v[168:169], v[160:161], v[120:121], v[168:169] op_sel:[0,1,0] op_sel_hi:[1,1,1]
	ds_read_b128 v[154:157], v192 offset:57344
	ds_read_b128 v[158:161], v192 offset:58368
	s_waitcnt lgkmcnt(8)
	v_pk_fma_f32 v[162:163], v[178:179], v[122:123], v[162:163] op_sel_hi:[1,0,1]
	v_pk_fma_f32 v[164:165], v[180:181], v[122:123], v[164:165] op_sel_hi:[1,0,1]
	v_pk_fma_f32 v[166:167], v[182:183], v[122:123], v[166:167] op_sel_hi:[1,0,1]
	v_pk_fma_f32 v[168:169], v[184:185], v[122:123], v[168:169] op_sel_hi:[1,0,1]
	ds_read_b128 v[178:181], v192 offset:59392
	ds_read_b128 v[182:185], v192 offset:60416
	s_waitcnt lgkmcnt(8)
	v_pk_fma_f32 v[162:163], v[130:131], v[122:123], v[162:163] op_sel:[0,1,0] op_sel_hi:[1,1,1]
	v_pk_fma_f32 v[164:165], v[132:133], v[122:123], v[164:165] op_sel:[0,1,0] op_sel_hi:[1,1,1]
	v_pk_fma_f32 v[166:167], v[134:135], v[122:123], v[166:167] op_sel:[0,1,0] op_sel_hi:[1,1,1]
	v_pk_fma_f32 v[168:169], v[136:137], v[122:123], v[168:169] op_sel:[0,1,0] op_sel_hi:[1,1,1]
	ds_read_b128 v[130:133], v192 offset:61440
	ds_read_b128 v[134:137], v192 offset:62464
	s_waitcnt lgkmcnt(8)
	v_pk_fma_f32 v[162:163], v[138:139], v[124:125], v[162:163] op_sel_hi:[1,0,1]
	v_pk_fma_f32 v[164:165], v[140:141], v[124:125], v[164:165] op_sel_hi:[1,0,1]
	v_pk_fma_f32 v[166:167], v[142:143], v[124:125], v[166:167] op_sel_hi:[1,0,1]
	v_pk_fma_f32 v[168:169], v[144:145], v[124:125], v[168:169] op_sel_hi:[1,0,1]
	ds_read_b128 v[138:141], v192 offset:63488
	ds_read_b128 v[142:145], v192 offset:64512
	s_waitcnt lgkmcnt(8)
	v_pk_fma_f32 v[162:163], v[146:147], v[124:125], v[162:163] op_sel:[0,1,0] op_sel_hi:[1,1,1]
	v_pk_fma_f32 v[164:165], v[148:149], v[124:125], v[164:165] op_sel:[0,1,0] op_sel_hi:[1,1,1]
	v_pk_fma_f32 v[166:167], v[150:151], v[124:125], v[166:167] op_sel:[0,1,0] op_sel_hi:[1,1,1]
	v_pk_fma_f32 v[168:169], v[152:153], v[124:125], v[168:169] op_sel:[0,1,0] op_sel_hi:[1,1,1]
	s_waitcnt lgkmcnt(6)
	v_pk_fma_f32 v[162:163], v[154:155], v[126:127], v[162:163] op_sel_hi:[1,0,1]
	v_pk_fma_f32 v[164:165], v[156:157], v[126:127], v[164:165] op_sel_hi:[1,0,1]
	v_pk_fma_f32 v[166:167], v[158:159], v[126:127], v[166:167] op_sel_hi:[1,0,1]
	v_pk_fma_f32 v[168:169], v[160:161], v[126:127], v[168:169] op_sel_hi:[1,0,1]
	s_waitcnt lgkmcnt(4)
	v_pk_fma_f32 v[162:163], v[178:179], v[126:127], v[162:163] op_sel:[0,1,0] op_sel_hi:[1,1,1]
	v_pk_fma_f32 v[164:165], v[180:181], v[126:127], v[164:165] op_sel:[0,1,0] op_sel_hi:[1,1,1]
	v_pk_fma_f32 v[166:167], v[182:183], v[126:127], v[166:167] op_sel:[0,1,0] op_sel_hi:[1,1,1]
	v_pk_fma_f32 v[168:169], v[184:185], v[126:127], v[168:169] op_sel:[0,1,0] op_sel_hi:[1,1,1]
	s_waitcnt lgkmcnt(2)
	v_pk_fma_f32 v[162:163], v[130:131], v[128:129], v[162:163] op_sel_hi:[1,0,1]
	v_pk_fma_f32 v[164:165], v[132:133], v[128:129], v[164:165] op_sel_hi:[1,0,1]
	v_pk_fma_f32 v[166:167], v[134:135], v[128:129], v[166:167] op_sel_hi:[1,0,1]
	v_pk_fma_f32 v[168:169], v[136:137], v[128:129], v[168:169] op_sel_hi:[1,0,1]
	s_waitcnt lgkmcnt(0)
	v_pk_fma_f32 v[162:163], v[138:139], v[128:129], v[162:163] op_sel:[0,1,0] op_sel_hi:[1,1,1]
	v_pk_fma_f32 v[164:165], v[140:141], v[128:129], v[164:165] op_sel:[0,1,0] op_sel_hi:[1,1,1]
	v_pk_fma_f32 v[166:167], v[142:143], v[128:129], v[166:167] op_sel:[0,1,0] op_sel_hi:[1,1,1]
	v_pk_fma_f32 v[168:169], v[144:145], v[128:129], v[168:169] op_sel:[0,1,0] op_sel_hi:[1,1,1]
	s_nop 1
	v_add_f32_dpp v162, v162, v162 quad_perm:[1,0,3,2] row_mask:0xf bank_mask:0xf
	v_add_f32_dpp v163, v163, v163 quad_perm:[1,0,3,2] row_mask:0xf bank_mask:0xf
	v_add_f32_dpp v164, v164, v164 quad_perm:[1,0,3,2] row_mask:0xf bank_mask:0xf
	v_add_f32_dpp v165, v165, v165 quad_perm:[1,0,3,2] row_mask:0xf bank_mask:0xf
	v_add_f32_dpp v166, v166, v166 quad_perm:[1,0,3,2] row_mask:0xf bank_mask:0xf
	v_add_f32_dpp v167, v167, v167 quad_perm:[1,0,3,2] row_mask:0xf bank_mask:0xf
	v_add_f32_dpp v168, v168, v168 quad_perm:[1,0,3,2] row_mask:0xf bank_mask:0xf
	v_add_f32_dpp v169, v169, v169 quad_perm:[1,0,3,2] row_mask:0xf bank_mask:0xf
	v_add_f32_dpp v162, v162, v162 quad_perm:[2,3,0,1] row_mask:0xf bank_mask:0xf
	v_add_f32_dpp v163, v163, v163 quad_perm:[2,3,0,1] row_mask:0xf bank_mask:0xf
	v_add_f32_dpp v164, v164, v164 quad_perm:[2,3,0,1] row_mask:0xf bank_mask:0xf
	v_add_f32_dpp v165, v165, v165 quad_perm:[2,3,0,1] row_mask:0xf bank_mask:0xf
	v_add_f32_dpp v166, v166, v166 quad_perm:[2,3,0,1] row_mask:0xf bank_mask:0xf
	v_add_f32_dpp v167, v167, v167 quad_perm:[2,3,0,1] row_mask:0xf bank_mask:0xf
	v_add_f32_dpp v168, v168, v168 quad_perm:[2,3,0,1] row_mask:0xf bank_mask:0xf
	v_add_f32_dpp v169, v169, v169 quad_perm:[2,3,0,1] row_mask:0xf bank_mask:0xf
	v_add_f32_dpp v162, v162, v162 row_half_mirror row_mask:0xf bank_mask:0xf
	v_add_f32_dpp v163, v163, v163 row_half_mirror row_mask:0xf bank_mask:0xf
	v_add_f32_dpp v164, v164, v164 row_half_mirror row_mask:0xf bank_mask:0xf
	v_add_f32_dpp v165, v165, v165 row_half_mirror row_mask:0xf bank_mask:0xf
	v_add_f32_dpp v166, v166, v166 row_half_mirror row_mask:0xf bank_mask:0xf
	v_add_f32_dpp v167, v167, v167 row_half_mirror row_mask:0xf bank_mask:0xf
	v_add_f32_dpp v168, v168, v168 row_half_mirror row_mask:0xf bank_mask:0xf
	v_add_f32_dpp v169, v169, v169 row_half_mirror row_mask:0xf bank_mask:0xf
	v_add_f32_dpp v162, v162, v162 row_mirror row_mask:0xf bank_mask:0xf
	v_add_f32_dpp v163, v163, v163 row_mirror row_mask:0xf bank_mask:0xf
	v_add_f32_dpp v164, v164, v164 row_mirror row_mask:0xf bank_mask:0xf
	v_add_f32_dpp v165, v165, v165 row_mirror row_mask:0xf bank_mask:0xf
	v_add_f32_dpp v166, v166, v166 row_mirror row_mask:0xf bank_mask:0xf
	v_add_f32_dpp v167, v167, v167 row_mirror row_mask:0xf bank_mask:0xf
	v_add_f32_dpp v168, v168, v168 row_mirror row_mask:0xf bank_mask:0xf
	v_add_f32_dpp v169, v169, v169 row_mirror row_mask:0xf bank_mask:0xf
	v_mov_b32_e32 v170, v162
	v_mov_b32_e32 v171, v163
	v_mov_b32_e32 v172, v164
	v_mov_b32_e32 v173, v165
	v_mov_b32_e32 v174, v166
	v_mov_b32_e32 v175, v167
	v_mov_b32_e32 v176, v168
	v_mov_b32_e32 v177, v169
	v_permlane16_swap_b32 v170, v162
	v_permlane16_swap_b32 v171, v163
	v_permlane16_swap_b32 v172, v164
	v_permlane16_swap_b32 v173, v165
	v_permlane16_swap_b32 v174, v166
	v_permlane16_swap_b32 v175, v167
	v_permlane16_swap_b32 v176, v168
	v_permlane16_swap_b32 v177, v169
	v_add_f32_e32 v162, v162, v170
	v_add_f32_e32 v163, v163, v171
	v_add_f32_e32 v164, v164, v172
	v_add_f32_e32 v165, v165, v173
	v_add_f32_e32 v166, v166, v174
	v_add_f32_e32 v167, v167, v175
	v_add_f32_e32 v168, v168, v176
	v_add_f32_e32 v169, v169, v177
	v_mov_b32_e32 v170, v162
	v_mov_b32_e32 v171, v163
	v_mov_b32_e32 v172, v164
	v_mov_b32_e32 v173, v165
	v_mov_b32_e32 v174, v166
	v_mov_b32_e32 v175, v167
	v_mov_b32_e32 v176, v168
	v_mov_b32_e32 v177, v169
	v_permlane32_swap_b32 v170, v162
	v_permlane32_swap_b32 v171, v163
	v_permlane32_swap_b32 v172, v164
	v_permlane32_swap_b32 v173, v165
	v_permlane32_swap_b32 v174, v166
	v_permlane32_swap_b32 v175, v167
	v_permlane32_swap_b32 v176, v168
	v_permlane32_swap_b32 v177, v169
	v_add_f32_e32 v162, v162, v170
	v_add_f32_e32 v163, v163, v171
	v_add_f32_e32 v164, v164, v172
	v_add_f32_e32 v165, v165, v173
	v_add_f32_e32 v166, v166, v174
	v_add_f32_e32 v167, v167, v175
	v_add_f32_e32 v168, v168, v176
	v_add_f32_e32 v169, v169, v177
	v_readfirstlane_b32 s98, v162
	v_readfirstlane_b32 s99, v163
	v_readfirstlane_b32 s100, v164
	v_readfirstlane_b32 s101, v165
	v_writelane_b32 v230, s98, 8
	v_writelane_b32 v230, s99, 9
	v_writelane_b32 v230, s100, 10
	v_writelane_b32 v230, s101, 11
	v_readfirstlane_b32 s98, v166
	v_readfirstlane_b32 s99, v167
	v_readfirstlane_b32 s100, v168
	v_readfirstlane_b32 s101, v169
	v_writelane_b32 v230, s98, 12
	v_writelane_b32 v230, s99, 13
	v_writelane_b32 v230, s100, 14
	v_writelane_b32 v230, s101, 15
	s_waitcnt vmcnt(16)
	v_pk_mul_f32 v[198:199], v[34:35], v[34:35]
	v_pk_mul_f32 v[200:201], v[36:37], v[36:37]
	v_pk_fma_f32 v[198:199], v[38:39], v[38:39], v[198:199]
	v_pk_fma_f32 v[200:201], v[40:41], v[40:41], v[200:201]
	v_pk_fma_f32 v[198:199], v[42:43], v[42:43], v[198:199]
	v_pk_fma_f32 v[200:201], v[44:45], v[44:45], v[200:201]
	v_pk_fma_f32 v[198:199], v[46:47], v[46:47], v[198:199]
	v_pk_fma_f32 v[200:201], v[48:49], v[48:49], v[200:201]
	v_pk_fma_f32 v[198:199], v[50:51], v[50:51], v[198:199]
	v_pk_fma_f32 v[200:201], v[52:53], v[52:53], v[200:201]
	v_pk_fma_f32 v[198:199], v[54:55], v[54:55], v[198:199]
	v_pk_fma_f32 v[200:201], v[56:57], v[56:57], v[200:201]
	v_pk_fma_f32 v[198:199], v[58:59], v[58:59], v[198:199]
	v_pk_fma_f32 v[200:201], v[60:61], v[60:61], v[200:201]
	v_pk_fma_f32 v[198:199], v[62:63], v[62:63], v[198:199]
	v_pk_fma_f32 v[200:201], v[64:65], v[64:65], v[200:201]
	v_pk_add_f32 v[198:199], v[198:199], v[200:201]
	v_add_f32_e32 v198, v198, v199
	s_nop 1
	v_add_f32_dpp v198, v198, v198 quad_perm:[1,0,3,2] row_mask:0xf bank_mask:0xf
	s_nop 1
	v_add_f32_dpp v198, v198, v198 quad_perm:[2,3,0,1] row_mask:0xf bank_mask:0xf
	s_nop 1
	v_add_f32_dpp v198, v198, v198 row_half_mirror row_mask:0xf bank_mask:0xf
	s_nop 1
	v_add_f32_dpp v198, v198, v198 row_mirror row_mask:0xf bank_mask:0xf
	v_mov_b32_e32 v199, v198
	s_nop 1
	v_permlane16_swap_b32 v199, v198
	v_add_f32_e32 v198, v198, v199
	v_mov_b32_e32 v199, v198
	s_nop 1
	v_permlane32_swap_b32 v199, v198
	v_add_f32_e32 v198, v198, v199
	ds_read_b128 v[130:133], v192
	ds_read_b128 v[134:137], v192 offset:1024
	ds_read_b128 v[138:141], v192 offset:2048
	ds_read_b128 v[142:145], v192 offset:3072
	ds_read_b128 v[146:149], v192 offset:4096
	ds_read_b128 v[150:153], v192 offset:5120
	ds_read_b128 v[154:157], v192 offset:6144
	ds_read_b128 v[158:161], v192 offset:7168
	ds_read_b128 v[178:181], v192 offset:8192
	ds_read_b128 v[182:185], v192 offset:9216
	v_fmamk_f32 v198, v198, 0x3a000000, v241
	v_mul_f32_e32 v199, 0x4b800000, v198
	v_cmp_gt_f32_e32 vcc, s17, v198
	s_nop 1
	v_cndmask_b32_e32 v198, v198, v199, vcc
	v_rsq_f32_e32 v198, v198
	s_nop 0
	v_mul_f32_e32 v199, 0x45800000, v198
	v_cndmask_b32_e32 v202, v198, v199, vcc
	v_pk_mul_f32 v[98:99], v[34:35], v[202:203] op_sel_hi:[1,0]
	v_pk_mul_f32 v[98:99], v[2:3], v[98:99]
	v_pk_mul_f32 v[100:101], v[36:37], v[202:203] op_sel_hi:[1,0]
	v_pk_mul_f32 v[100:101], v[4:5], v[100:101]
	v_cvt_pk_bf16_f32 v206, v98, v99
	v_cvt_pk_bf16_f32 v207, v100, v101
	global_store_dwordx2 v194, v[206:207], s[52:53]
	v_pk_mul_f32 v[102:103], v[38:39], v[202:203] op_sel_hi:[1,0]
	v_pk_mul_f32 v[102:103], v[6:7], v[102:103]
	v_pk_mul_f32 v[104:105], v[40:41], v[202:203] op_sel_hi:[1,0]
	v_pk_mul_f32 v[104:105], v[8:9], v[104:105]
	v_cvt_pk_bf16_f32 v206, v102, v103
	v_cvt_pk_bf16_f32 v207, v104, v105
	global_store_dwordx2 v194, v[206:207], s[52:53] offset:512
	v_pk_mul_f32 v[106:107], v[42:43], v[202:203] op_sel_hi:[1,0]
	v_pk_mul_f32 v[106:107], v[10:11], v[106:107]
	v_pk_mul_f32 v[108:109], v[44:45], v[202:203] op_sel_hi:[1,0]
	v_pk_mul_f32 v[108:109], v[12:13], v[108:109]
	v_cvt_pk_bf16_f32 v206, v106, v107
	v_cvt_pk_bf16_f32 v207, v108, v109
	global_store_dwordx2 v194, v[206:207], s[52:53] offset:1024
	v_pk_mul_f32 v[110:111], v[46:47], v[202:203] op_sel_hi:[1,0]
	v_pk_mul_f32 v[110:111], v[14:15], v[110:111]
	v_pk_mul_f32 v[112:113], v[48:49], v[202:203] op_sel_hi:[1,0]
	v_pk_mul_f32 v[112:113], v[16:17], v[112:113]
	v_cvt_pk_bf16_f32 v206, v110, v111
	v_cvt_pk_bf16_f32 v207, v112, v113
	global_store_dwordx2 v194, v[206:207], s[52:53] offset:1536
	v_pk_mul_f32 v[114:115], v[50:51], v[202:203] op_sel_hi:[1,0]
	v_pk_mul_f32 v[114:115], v[18:19], v[114:115]
	v_pk_mul_f32 v[116:117], v[52:53], v[202:203] op_sel_hi:[1,0]
	v_pk_mul_f32 v[116:117], v[20:21], v[116:117]
	v_cvt_pk_bf16_f32 v206, v114, v115
	v_cvt_pk_bf16_f32 v207, v116, v117
	global_store_dwordx2 v194, v[206:207], s[52:53] offset:2048
	v_pk_mul_f32 v[118:119], v[54:55], v[202:203] op_sel_hi:[1,0]
	v_pk_mul_f32 v[118:119], v[22:23], v[118:119]
	v_pk_mul_f32 v[120:121], v[56:57], v[202:203] op_sel_hi:[1,0]
	v_pk_mul_f32 v[120:121], v[24:25], v[120:121]
	v_cvt_pk_bf16_f32 v206, v118, v119
	v_cvt_pk_bf16_f32 v207, v120, v121
	global_store_dwordx2 v194, v[206:207], s[52:53] offset:2560
	v_pk_mul_f32 v[122:123], v[58:59], v[202:203] op_sel_hi:[1,0]
	v_pk_mul_f32 v[122:123], v[26:27], v[122:123]
	v_pk_mul_f32 v[124:125], v[60:61], v[202:203] op_sel_hi:[1,0]
	v_pk_mul_f32 v[124:125], v[28:29], v[124:125]
	v_cvt_pk_bf16_f32 v206, v122, v123
	v_cvt_pk_bf16_f32 v207, v124, v125
	global_store_dwordx2 v194, v[206:207], s[52:53] offset:3072
	v_pk_mul_f32 v[126:127], v[62:63], v[202:203] op_sel_hi:[1,0]
	v_pk_mul_f32 v[126:127], v[30:31], v[126:127]
	v_pk_mul_f32 v[128:129], v[64:65], v[202:203] op_sel_hi:[1,0]
	v_pk_mul_f32 v[128:129], v[32:33], v[128:129]
	v_cvt_pk_bf16_f32 v206, v126, v127
	v_cvt_pk_bf16_f32 v207, v128, v129
	global_store_dwordx2 v194, v[206:207], s[52:53] offset:3584
	v_add_u32_e32 v194, 0x800000, v194
	global_load_dwordx4 v[34:37], v193, s[12:13] offset:-4096 nt
	global_load_dwordx4 v[38:41], v193, s[12:13] offset:-3072 nt
	global_load_dwordx4 v[42:45], v193, s[12:13] offset:-2048 nt
	global_load_dwordx4 v[46:49], v193, s[12:13] offset:-1024 nt
	global_load_dwordx4 v[50:53], v193, s[12:13] offset:0 nt
	global_load_dwordx4 v[54:57], v193, s[12:13] offset:1024 nt
	global_load_dwordx4 v[58:61], v193, s[12:13] offset:2048 nt
	global_load_dwordx4 v[62:65], v193, s[12:13] offset:3072 nt
	v_add_u32_e32 v193, s0, v193
	s_waitcnt lgkmcnt(8)
	v_pk_mul_f32 v[162:163], v[130:131], v[98:99] op_sel_hi:[1,0]
	v_pk_mul_f32 v[164:165], v[132:133], v[98:99] op_sel_hi:[1,0]
	v_pk_mul_f32 v[166:167], v[134:135], v[98:99] op_sel_hi:[1,0]
	v_pk_mul_f32 v[168:169], v[136:137], v[98:99] op_sel_hi:[1,0]
	ds_read_b128 v[130:133], v192 offset:10240
	ds_read_b128 v[134:137], v192 offset:11264
	s_waitcnt lgkmcnt(8)
	v_pk_fma_f32 v[162:163], v[138:139], v[98:99], v[162:163] op_sel:[0,1,0] op_sel_hi:[1,1,1]
	v_pk_fma_f32 v[164:165], v[140:141], v[98:99], v[164:165] op_sel:[0,1,0] op_sel_hi:[1,1,1]
	v_pk_fma_f32 v[166:167], v[142:143], v[98:99], v[166:167] op_sel:[0,1,0] op_sel_hi:[1,1,1]
	v_pk_fma_f32 v[168:169], v[144:145], v[98:99], v[168:169] op_sel:[0,1,0] op_sel_hi:[1,1,1]
	ds_read_b128 v[138:141], v192 offset:12288
	ds_read_b128 v[142:145], v192 offset:13312
	s_waitcnt lgkmcnt(8)
	v_pk_fma_f32 v[162:163], v[146:147], v[100:101], v[162:163] op_sel_hi:[1,0,1]
	v_pk_fma_f32 v[164:165], v[148:149], v[100:101], v[164:165] op_sel_hi:[1,0,1]
	v_pk_fma_f32 v[166:167], v[150:151], v[100:101], v[166:167] op_sel_hi:[1,0,1]
	v_pk_fma_f32 v[168:169], v[152:153], v[100:101], v[168:169] op_sel_hi:[1,0,1]
	ds_read_b128 v[146:149], v192 offset:14336
	ds_read_b128 v[150:153], v192 offset:15360
	s_waitcnt lgkmcnt(8)
	v_pk_fma_f32 v[162:163], v[154:155], v[100:101], v[162:163] op_sel:[0,1,0] op_sel_hi:[1,1,1]
	v_pk_fma_f32 v[164:165], v[156:157], v[100:101], v[164:165] op_sel:[0,1,0] op_sel_hi:[1,1,1]
	v_pk_fma_f32 v[166:167], v[158:159], v[100:101], v[166:167] op_sel:[0,1,0] op_sel_hi:[1,1,1]
	v_pk_fma_f32 v[168:169], v[160:161], v[100:101], v[168:169] op_sel:[0,1,0] op_sel_hi:[1,1,1]
	ds_read_b128 v[154:157], v192 offset:16384
	ds_read_b128 v[158:161], v192 offset:17408
	s_waitcnt lgkmcnt(8)
	v_pk_fma_f32 v[162:163], v[178:179], v[102:103], v[162:163] op_sel_hi:[1,0,1]
	v_pk_fma_f32 v[164:165], v[180:181], v[102:103], v[164:165] op_sel_hi:[1,0,1]
	v_pk_fma_f32 v[166:167], v[182:183], v[102:103], v[166:167] op_sel_hi:[1,0,1]
	v_pk_fma_f32 v[168:169], v[184:185], v[102:103], v[168:169] op_sel_hi:[1,0,1]
	ds_read_b128 v[178:181], v192 offset:18432
	ds_read_b128 v[182:185], v192 offset:19456
	s_waitcnt lgkmcnt(8)
	v_pk_fma_f32 v[162:163], v[130:131], v[102:103], v[162:163] op_sel:[0,1,0] op_sel_hi:[1,1,1]
	v_pk_fma_f32 v[164:165], v[132:133], v[102:103], v[164:165] op_sel:[0,1,0] op_sel_hi:[1,1,1]
	v_pk_fma_f32 v[166:167], v[134:135], v[102:103], v[166:167] op_sel:[0,1,0] op_sel_hi:[1,1,1]
	v_pk_fma_f32 v[168:169], v[136:137], v[102:103], v[168:169] op_sel:[0,1,0] op_sel_hi:[1,1,1]
	ds_read_b128 v[130:133], v192 offset:20480
	ds_read_b128 v[134:137], v192 offset:21504
	s_waitcnt lgkmcnt(8)
	v_pk_fma_f32 v[162:163], v[138:139], v[104:105], v[162:163] op_sel_hi:[1,0,1]
	v_pk_fma_f32 v[164:165], v[140:141], v[104:105], v[164:165] op_sel_hi:[1,0,1]
	v_pk_fma_f32 v[166:167], v[142:143], v[104:105], v[166:167] op_sel_hi:[1,0,1]
	v_pk_fma_f32 v[168:169], v[144:145], v[104:105], v[168:169] op_sel_hi:[1,0,1]
	ds_read_b128 v[138:141], v192 offset:22528
	ds_read_b128 v[142:145], v192 offset:23552
	s_waitcnt lgkmcnt(8)
	v_pk_fma_f32 v[162:163], v[146:147], v[104:105], v[162:163] op_sel:[0,1,0] op_sel_hi:[1,1,1]
	v_pk_fma_f32 v[164:165], v[148:149], v[104:105], v[164:165] op_sel:[0,1,0] op_sel_hi:[1,1,1]
	v_pk_fma_f32 v[166:167], v[150:151], v[104:105], v[166:167] op_sel:[0,1,0] op_sel_hi:[1,1,1]
	v_pk_fma_f32 v[168:169], v[152:153], v[104:105], v[168:169] op_sel:[0,1,0] op_sel_hi:[1,1,1]
	ds_read_b128 v[146:149], v192 offset:24576
	ds_read_b128 v[150:153], v192 offset:25600
	s_waitcnt lgkmcnt(8)
	v_pk_fma_f32 v[162:163], v[154:155], v[106:107], v[162:163] op_sel_hi:[1,0,1]
	v_pk_fma_f32 v[164:165], v[156:157], v[106:107], v[164:165] op_sel_hi:[1,0,1]
	v_pk_fma_f32 v[166:167], v[158:159], v[106:107], v[166:167] op_sel_hi:[1,0,1]
	v_pk_fma_f32 v[168:169], v[160:161], v[106:107], v[168:169] op_sel_hi:[1,0,1]
	ds_read_b128 v[154:157], v192 offset:26624
	ds_read_b128 v[158:161], v192 offset:27648
	s_waitcnt lgkmcnt(8)
	v_pk_fma_f32 v[162:163], v[178:179], v[106:107], v[162:163] op_sel:[0,1,0] op_sel_hi:[1,1,1]
	v_pk_fma_f32 v[164:165], v[180:181], v[106:107], v[164:165] op_sel:[0,1,0] op_sel_hi:[1,1,1]
	v_pk_fma_f32 v[166:167], v[182:183], v[106:107], v[166:167] op_sel:[0,1,0] op_sel_hi:[1,1,1]
	v_pk_fma_f32 v[168:169], v[184:185], v[106:107], v[168:169] op_sel:[0,1,0] op_sel_hi:[1,1,1]
	ds_read_b128 v[178:181], v192 offset:28672
	ds_read_b128 v[182:185], v192 offset:29696
	s_waitcnt lgkmcnt(8)
	v_pk_fma_f32 v[162:163], v[130:131], v[108:109], v[162:163] op_sel_hi:[1,0,1]
	v_pk_fma_f32 v[164:165], v[132:133], v[108:109], v[164:165] op_sel_hi:[1,0,1]
	v_pk_fma_f32 v[166:167], v[134:135], v[108:109], v[166:167] op_sel_hi:[1,0,1]
	v_pk_fma_f32 v[168:169], v[136:137], v[108:109], v[168:169] op_sel_hi:[1,0,1]
	ds_read_b128 v[130:133], v192 offset:30720
	ds_read_b128 v[134:137], v192 offset:31744
	s_waitcnt lgkmcnt(8)
	v_pk_fma_f32 v[162:163], v[138:139], v[108:109], v[162:163] op_sel:[0,1,0] op_sel_hi:[1,1,1]
	v_pk_fma_f32 v[164:165], v[140:141], v[108:109], v[164:165] op_sel:[0,1,0] op_sel_hi:[1,1,1]
	v_pk_fma_f32 v[166:167], v[142:143], v[108:109], v[166:167] op_sel:[0,1,0] op_sel_hi:[1,1,1]
	v_pk_fma_f32 v[168:169], v[144:145], v[108:109], v[168:169] op_sel:[0,1,0] op_sel_hi:[1,1,1]
	ds_read_b128 v[138:141], v192 offset:32768
	ds_read_b128 v[142:145], v192 offset:33792
	s_waitcnt lgkmcnt(8)
	v_pk_fma_f32 v[162:163], v[146:147], v[110:111], v[162:163] op_sel_hi:[1,0,1]
	v_pk_fma_f32 v[164:165], v[148:149], v[110:111], v[164:165] op_sel_hi:[1,0,1]
	v_pk_fma_f32 v[166:167], v[150:151], v[110:111], v[166:167] op_sel_hi:[1,0,1]
	v_pk_fma_f32 v[168:169], v[152:153], v[110:111], v[168:169] op_sel_hi:[1,0,1]
	ds_read_b128 v[146:149], v192 offset:34816
	ds_read_b128 v[150:153], v192 offset:35840
	s_waitcnt lgkmcnt(8)
	v_pk_fma_f32 v[162:163], v[154:155], v[110:111], v[162:163] op_sel:[0,1,0] op_sel_hi:[1,1,1]
	v_pk_fma_f32 v[164:165], v[156:157], v[110:111], v[164:165] op_sel:[0,1,0] op_sel_hi:[1,1,1]
	v_pk_fma_f32 v[166:167], v[158:159], v[110:111], v[166:167] op_sel:[0,1,0] op_sel_hi:[1,1,1]
	v_pk_fma_f32 v[168:169], v[160:161], v[110:111], v[168:169] op_sel:[0,1,0] op_sel_hi:[1,1,1]
	ds_read_b128 v[154:157], v192 offset:36864
	ds_read_b128 v[158:161], v192 offset:37888
	s_waitcnt lgkmcnt(8)
	v_pk_fma_f32 v[162:163], v[178:179], v[112:113], v[162:163] op_sel_hi:[1,0,1]
	v_pk_fma_f32 v[164:165], v[180:181], v[112:113], v[164:165] op_sel_hi:[1,0,1]
	v_pk_fma_f32 v[166:167], v[182:183], v[112:113], v[166:167] op_sel_hi:[1,0,1]
	v_pk_fma_f32 v[168:169], v[184:185], v[112:113], v[168:169] op_sel_hi:[1,0,1]
	ds_read_b128 v[178:181], v192 offset:38912
	ds_read_b128 v[182:185], v192 offset:39936
	s_waitcnt lgkmcnt(8)
	v_pk_fma_f32 v[162:163], v[130:131], v[112:113], v[162:163] op_sel:[0,1,0] op_sel_hi:[1,1,1]
	v_pk_fma_f32 v[164:165], v[132:133], v[112:113], v[164:165] op_sel:[0,1,0] op_sel_hi:[1,1,1]
	v_pk_fma_f32 v[166:167], v[134:135], v[112:113], v[166:167] op_sel:[0,1,0] op_sel_hi:[1,1,1]
	v_pk_fma_f32 v[168:169], v[136:137], v[112:113], v[168:169] op_sel:[0,1,0] op_sel_hi:[1,1,1]
	ds_read_b128 v[130:133], v192 offset:40960
	ds_read_b128 v[134:137], v192 offset:41984
	s_waitcnt lgkmcnt(8)
	v_pk_fma_f32 v[162:163], v[138:139], v[114:115], v[162:163] op_sel_hi:[1,0,1]
	v_pk_fma_f32 v[164:165], v[140:141], v[114:115], v[164:165] op_sel_hi:[1,0,1]
	v_pk_fma_f32 v[166:167], v[142:143], v[114:115], v[166:167] op_sel_hi:[1,0,1]
	v_pk_fma_f32 v[168:169], v[144:145], v[114:115], v[168:169] op_sel_hi:[1,0,1]
	ds_read_b128 v[138:141], v192 offset:43008
	ds_read_b128 v[142:145], v192 offset:44032
	s_waitcnt lgkmcnt(8)
	v_pk_fma_f32 v[162:163], v[146:147], v[114:115], v[162:163] op_sel:[0,1,0] op_sel_hi:[1,1,1]
	v_pk_fma_f32 v[164:165], v[148:149], v[114:115], v[164:165] op_sel:[0,1,0] op_sel_hi:[1,1,1]
	v_pk_fma_f32 v[166:167], v[150:151], v[114:115], v[166:167] op_sel:[0,1,0] op_sel_hi:[1,1,1]
	v_pk_fma_f32 v[168:169], v[152:153], v[114:115], v[168:169] op_sel:[0,1,0] op_sel_hi:[1,1,1]
	ds_read_b128 v[146:149], v192 offset:45056
	ds_read_b128 v[150:153], v192 offset:46080
	s_waitcnt lgkmcnt(8)
	v_pk_fma_f32 v[162:163], v[154:155], v[116:117], v[162:163] op_sel_hi:[1,0,1]
	v_pk_fma_f32 v[164:165], v[156:157], v[116:117], v[164:165] op_sel_hi:[1,0,1]
	v_pk_fma_f32 v[166:167], v[158:159], v[116:117], v[166:167] op_sel_hi:[1,0,1]
	v_pk_fma_f32 v[168:169], v[160:161], v[116:117], v[168:169] op_sel_hi:[1,0,1]
	ds_read_b128 v[154:157], v192 offset:47104
	ds_read_b128 v[158:161], v192 offset:48128
	s_waitcnt lgkmcnt(8)
	v_pk_fma_f32 v[162:163], v[178:179], v[116:117], v[162:163] op_sel:[0,1,0] op_sel_hi:[1,1,1]
	v_pk_fma_f32 v[164:165], v[180:181], v[116:117], v[164:165] op_sel:[0,1,0] op_sel_hi:[1,1,1]
	v_pk_fma_f32 v[166:167], v[182:183], v[116:117], v[166:167] op_sel:[0,1,0] op_sel_hi:[1,1,1]
	v_pk_fma_f32 v[168:169], v[184:185], v[116:117], v[168:169] op_sel:[0,1,0] op_sel_hi:[1,1,1]
	ds_read_b128 v[178:181], v192 offset:49152
	ds_read_b128 v[182:185], v192 offset:50176
	s_waitcnt lgkmcnt(8)
	v_pk_fma_f32 v[162:163], v[130:131], v[118:119], v[162:163] op_sel_hi:[1,0,1]
	v_pk_fma_f32 v[164:165], v[132:133], v[118:119], v[164:165] op_sel_hi:[1,0,1]
	v_pk_fma_f32 v[166:167], v[134:135], v[118:119], v[166:167] op_sel_hi:[1,0,1]
	v_pk_fma_f32 v[168:169], v[136:137], v[118:119], v[168:169] op_sel_hi:[1,0,1]
	ds_read_b128 v[130:133], v192 offset:51200
	ds_read_b128 v[134:137], v192 offset:52224
	s_waitcnt lgkmcnt(8)
	v_pk_fma_f32 v[162:163], v[138:139], v[118:119], v[162:163] op_sel:[0,1,0] op_sel_hi:[1,1,1]
	v_pk_fma_f32 v[164:165], v[140:141], v[118:119], v[164:165] op_sel:[0,1,0] op_sel_hi:[1,1,1]
	v_pk_fma_f32 v[166:167], v[142:143], v[118:119], v[166:167] op_sel:[0,1,0] op_sel_hi:[1,1,1]
	v_pk_fma_f32 v[168:169], v[144:145], v[118:119], v[168:169] op_sel:[0,1,0] op_sel_hi:[1,1,1]
	ds_read_b128 v[138:141], v192 offset:53248
	ds_read_b128 v[142:145], v192 offset:54272
	s_waitcnt lgkmcnt(8)
	v_pk_fma_f32 v[162:163], v[146:147], v[120:121], v[162:163] op_sel_hi:[1,0,1]
	v_pk_fma_f32 v[164:165], v[148:149], v[120:121], v[164:165] op_sel_hi:[1,0,1]
	v_pk_fma_f32 v[166:167], v[150:151], v[120:121], v[166:167] op_sel_hi:[1,0,1]
	v_pk_fma_f32 v[168:169], v[152:153], v[120:121], v[168:169] op_sel_hi:[1,0,1]
	ds_read_b128 v[146:149], v192 offset:55296
	ds_read_b128 v[150:153], v192 offset:56320
	s_waitcnt lgkmcnt(8)
	v_pk_fma_f32 v[162:163], v[154:155], v[120:121], v[162:163] op_sel:[0,1,0] op_sel_hi:[1,1,1]
	v_pk_fma_f32 v[164:165], v[156:157], v[120:121], v[164:165] op_sel:[0,1,0] op_sel_hi:[1,1,1]
	v_pk_fma_f32 v[166:167], v[158:159], v[120:121], v[166:167] op_sel:[0,1,0] op_sel_hi:[1,1,1]
	v_pk_fma_f32 v[168:169], v[160:161], v[120:121], v[168:169] op_sel:[0,1,0] op_sel_hi:[1,1,1]
	ds_read_b128 v[154:157], v192 offset:57344
	ds_read_b128 v[158:161], v192 offset:58368
	s_waitcnt lgkmcnt(8)
	v_pk_fma_f32 v[162:163], v[178:179], v[122:123], v[162:163] op_sel_hi:[1,0,1]
	v_pk_fma_f32 v[164:165], v[180:181], v[122:123], v[164:165] op_sel_hi:[1,0,1]
	v_pk_fma_f32 v[166:167], v[182:183], v[122:123], v[166:167] op_sel_hi:[1,0,1]
	v_pk_fma_f32 v[168:169], v[184:185], v[122:123], v[168:169] op_sel_hi:[1,0,1]
	ds_read_b128 v[178:181], v192 offset:59392
	ds_read_b128 v[182:185], v192 offset:60416
	s_waitcnt lgkmcnt(8)
	v_pk_fma_f32 v[162:163], v[130:131], v[122:123], v[162:163] op_sel:[0,1,0] op_sel_hi:[1,1,1]
	v_pk_fma_f32 v[164:165], v[132:133], v[122:123], v[164:165] op_sel:[0,1,0] op_sel_hi:[1,1,1]
	v_pk_fma_f32 v[166:167], v[134:135], v[122:123], v[166:167] op_sel:[0,1,0] op_sel_hi:[1,1,1]
	v_pk_fma_f32 v[168:169], v[136:137], v[122:123], v[168:169] op_sel:[0,1,0] op_sel_hi:[1,1,1]
	ds_read_b128 v[130:133], v192 offset:61440
	ds_read_b128 v[134:137], v192 offset:62464
	s_waitcnt lgkmcnt(8)
	v_pk_fma_f32 v[162:163], v[138:139], v[124:125], v[162:163] op_sel_hi:[1,0,1]
	v_pk_fma_f32 v[164:165], v[140:141], v[124:125], v[164:165] op_sel_hi:[1,0,1]
	v_pk_fma_f32 v[166:167], v[142:143], v[124:125], v[166:167] op_sel_hi:[1,0,1]
	v_pk_fma_f32 v[168:169], v[144:145], v[124:125], v[168:169] op_sel_hi:[1,0,1]
	ds_read_b128 v[138:141], v192 offset:63488
	ds_read_b128 v[142:145], v192 offset:64512
	s_waitcnt lgkmcnt(8)
	v_pk_fma_f32 v[162:163], v[146:147], v[124:125], v[162:163] op_sel:[0,1,0] op_sel_hi:[1,1,1]
	v_pk_fma_f32 v[164:165], v[148:149], v[124:125], v[164:165] op_sel:[0,1,0] op_sel_hi:[1,1,1]
	v_pk_fma_f32 v[166:167], v[150:151], v[124:125], v[166:167] op_sel:[0,1,0] op_sel_hi:[1,1,1]
	v_pk_fma_f32 v[168:169], v[152:153], v[124:125], v[168:169] op_sel:[0,1,0] op_sel_hi:[1,1,1]
	s_waitcnt lgkmcnt(6)
	v_pk_fma_f32 v[162:163], v[154:155], v[126:127], v[162:163] op_sel_hi:[1,0,1]
	v_pk_fma_f32 v[164:165], v[156:157], v[126:127], v[164:165] op_sel_hi:[1,0,1]
	v_pk_fma_f32 v[166:167], v[158:159], v[126:127], v[166:167] op_sel_hi:[1,0,1]
	v_pk_fma_f32 v[168:169], v[160:161], v[126:127], v[168:169] op_sel_hi:[1,0,1]
	s_waitcnt lgkmcnt(4)
	v_pk_fma_f32 v[162:163], v[178:179], v[126:127], v[162:163] op_sel:[0,1,0] op_sel_hi:[1,1,1]
	v_pk_fma_f32 v[164:165], v[180:181], v[126:127], v[164:165] op_sel:[0,1,0] op_sel_hi:[1,1,1]
	v_pk_fma_f32 v[166:167], v[182:183], v[126:127], v[166:167] op_sel:[0,1,0] op_sel_hi:[1,1,1]
	v_pk_fma_f32 v[168:169], v[184:185], v[126:127], v[168:169] op_sel:[0,1,0] op_sel_hi:[1,1,1]
	s_waitcnt lgkmcnt(2)
	v_pk_fma_f32 v[162:163], v[130:131], v[128:129], v[162:163] op_sel_hi:[1,0,1]
	v_pk_fma_f32 v[164:165], v[132:133], v[128:129], v[164:165] op_sel_hi:[1,0,1]
	v_pk_fma_f32 v[166:167], v[134:135], v[128:129], v[166:167] op_sel_hi:[1,0,1]
	v_pk_fma_f32 v[168:169], v[136:137], v[128:129], v[168:169] op_sel_hi:[1,0,1]
	s_waitcnt lgkmcnt(0)
	v_pk_fma_f32 v[162:163], v[138:139], v[128:129], v[162:163] op_sel:[0,1,0] op_sel_hi:[1,1,1]
	v_pk_fma_f32 v[164:165], v[140:141], v[128:129], v[164:165] op_sel:[0,1,0] op_sel_hi:[1,1,1]
	v_pk_fma_f32 v[166:167], v[142:143], v[128:129], v[166:167] op_sel:[0,1,0] op_sel_hi:[1,1,1]
	v_pk_fma_f32 v[168:169], v[144:145], v[128:129], v[168:169] op_sel:[0,1,0] op_sel_hi:[1,1,1]
	s_nop 1
	v_add_f32_dpp v162, v162, v162 quad_perm:[1,0,3,2] row_mask:0xf bank_mask:0xf
	v_add_f32_dpp v163, v163, v163 quad_perm:[1,0,3,2] row_mask:0xf bank_mask:0xf
	v_add_f32_dpp v164, v164, v164 quad_perm:[1,0,3,2] row_mask:0xf bank_mask:0xf
	v_add_f32_dpp v165, v165, v165 quad_perm:[1,0,3,2] row_mask:0xf bank_mask:0xf
	v_add_f32_dpp v166, v166, v166 quad_perm:[1,0,3,2] row_mask:0xf bank_mask:0xf
	v_add_f32_dpp v167, v167, v167 quad_perm:[1,0,3,2] row_mask:0xf bank_mask:0xf
	v_add_f32_dpp v168, v168, v168 quad_perm:[1,0,3,2] row_mask:0xf bank_mask:0xf
	v_add_f32_dpp v169, v169, v169 quad_perm:[1,0,3,2] row_mask:0xf bank_mask:0xf
	v_add_f32_dpp v162, v162, v162 quad_perm:[2,3,0,1] row_mask:0xf bank_mask:0xf
	v_add_f32_dpp v163, v163, v163 quad_perm:[2,3,0,1] row_mask:0xf bank_mask:0xf
	v_add_f32_dpp v164, v164, v164 quad_perm:[2,3,0,1] row_mask:0xf bank_mask:0xf
	v_add_f32_dpp v165, v165, v165 quad_perm:[2,3,0,1] row_mask:0xf bank_mask:0xf
	v_add_f32_dpp v166, v166, v166 quad_perm:[2,3,0,1] row_mask:0xf bank_mask:0xf
	v_add_f32_dpp v167, v167, v167 quad_perm:[2,3,0,1] row_mask:0xf bank_mask:0xf
	v_add_f32_dpp v168, v168, v168 quad_perm:[2,3,0,1] row_mask:0xf bank_mask:0xf
	v_add_f32_dpp v169, v169, v169 quad_perm:[2,3,0,1] row_mask:0xf bank_mask:0xf
	v_add_f32_dpp v162, v162, v162 row_half_mirror row_mask:0xf bank_mask:0xf
	v_add_f32_dpp v163, v163, v163 row_half_mirror row_mask:0xf bank_mask:0xf
	v_add_f32_dpp v164, v164, v164 row_half_mirror row_mask:0xf bank_mask:0xf
	v_add_f32_dpp v165, v165, v165 row_half_mirror row_mask:0xf bank_mask:0xf
	v_add_f32_dpp v166, v166, v166 row_half_mirror row_mask:0xf bank_mask:0xf
	v_add_f32_dpp v167, v167, v167 row_half_mirror row_mask:0xf bank_mask:0xf
	v_add_f32_dpp v168, v168, v168 row_half_mirror row_mask:0xf bank_mask:0xf
	v_add_f32_dpp v169, v169, v169 row_half_mirror row_mask:0xf bank_mask:0xf
	v_add_f32_dpp v162, v162, v162 row_mirror row_mask:0xf bank_mask:0xf
	v_add_f32_dpp v163, v163, v163 row_mirror row_mask:0xf bank_mask:0xf
	v_add_f32_dpp v164, v164, v164 row_mirror row_mask:0xf bank_mask:0xf
	v_add_f32_dpp v165, v165, v165 row_mirror row_mask:0xf bank_mask:0xf
	v_add_f32_dpp v166, v166, v166 row_mirror row_mask:0xf bank_mask:0xf
	v_add_f32_dpp v167, v167, v167 row_mirror row_mask:0xf bank_mask:0xf
	v_add_f32_dpp v168, v168, v168 row_mirror row_mask:0xf bank_mask:0xf
	v_add_f32_dpp v169, v169, v169 row_mirror row_mask:0xf bank_mask:0xf
	v_mov_b32_e32 v170, v162
	v_mov_b32_e32 v171, v163
	v_mov_b32_e32 v172, v164
	v_mov_b32_e32 v173, v165
	v_mov_b32_e32 v174, v166
	v_mov_b32_e32 v175, v167
	v_mov_b32_e32 v176, v168
	v_mov_b32_e32 v177, v169
	v_permlane16_swap_b32 v170, v162
	v_permlane16_swap_b32 v171, v163
	v_permlane16_swap_b32 v172, v164
	v_permlane16_swap_b32 v173, v165
	v_permlane16_swap_b32 v174, v166
	v_permlane16_swap_b32 v175, v167
	v_permlane16_swap_b32 v176, v168
	v_permlane16_swap_b32 v177, v169
	v_add_f32_e32 v162, v162, v170
	v_add_f32_e32 v163, v163, v171
	v_add_f32_e32 v164, v164, v172
	v_add_f32_e32 v165, v165, v173
	v_add_f32_e32 v166, v166, v174
	v_add_f32_e32 v167, v167, v175
	v_add_f32_e32 v168, v168, v176
	v_add_f32_e32 v169, v169, v177
	v_mov_b32_e32 v170, v162
	v_mov_b32_e32 v171, v163
	v_mov_b32_e32 v172, v164
	v_mov_b32_e32 v173, v165
	v_mov_b32_e32 v174, v166
	v_mov_b32_e32 v175, v167
	v_mov_b32_e32 v176, v168
	v_mov_b32_e32 v177, v169
	v_permlane32_swap_b32 v170, v162
	v_permlane32_swap_b32 v171, v163
	v_permlane32_swap_b32 v172, v164
	v_permlane32_swap_b32 v173, v165
	v_permlane32_swap_b32 v174, v166
	v_permlane32_swap_b32 v175, v167
	v_permlane32_swap_b32 v176, v168
	v_permlane32_swap_b32 v177, v169
	v_add_f32_e32 v162, v162, v170
	v_add_f32_e32 v163, v163, v171
	v_add_f32_e32 v164, v164, v172
	v_add_f32_e32 v165, v165, v173
	v_add_f32_e32 v166, v166, v174
	v_add_f32_e32 v167, v167, v175
	v_add_f32_e32 v168, v168, v176
	v_add_f32_e32 v169, v169, v177
	v_readfirstlane_b32 s98, v162
	v_readfirstlane_b32 s99, v163
	v_readfirstlane_b32 s100, v164
	v_readfirstlane_b32 s101, v165
	v_writelane_b32 v230, s98, 16
	v_writelane_b32 v230, s99, 17
	v_writelane_b32 v230, s100, 18
	v_writelane_b32 v230, s101, 19
	v_readfirstlane_b32 s98, v166
	v_readfirstlane_b32 s99, v167
	v_readfirstlane_b32 s100, v168
	v_readfirstlane_b32 s101, v169
	v_writelane_b32 v230, s98, 20
	v_writelane_b32 v230, s99, 21
	v_writelane_b32 v230, s100, 22
	v_writelane_b32 v230, s101, 23
	s_waitcnt vmcnt(16)
	v_pk_mul_f32 v[198:199], v[66:67], v[66:67]
	v_pk_mul_f32 v[200:201], v[68:69], v[68:69]
	v_pk_fma_f32 v[198:199], v[70:71], v[70:71], v[198:199]
	v_pk_fma_f32 v[200:201], v[72:73], v[72:73], v[200:201]
	v_pk_fma_f32 v[198:199], v[74:75], v[74:75], v[198:199]
	v_pk_fma_f32 v[200:201], v[76:77], v[76:77], v[200:201]
	v_pk_fma_f32 v[198:199], v[78:79], v[78:79], v[198:199]
	v_pk_fma_f32 v[200:201], v[80:81], v[80:81], v[200:201]
	v_pk_fma_f32 v[198:199], v[82:83], v[82:83], v[198:199]
	v_pk_fma_f32 v[200:201], v[84:85], v[84:85], v[200:201]
	v_pk_fma_f32 v[198:199], v[86:87], v[86:87], v[198:199]
	v_pk_fma_f32 v[200:201], v[88:89], v[88:89], v[200:201]
	v_pk_fma_f32 v[198:199], v[90:91], v[90:91], v[198:199]
	v_pk_fma_f32 v[200:201], v[92:93], v[92:93], v[200:201]
	v_pk_fma_f32 v[198:199], v[94:95], v[94:95], v[198:199]
	v_pk_fma_f32 v[200:201], v[96:97], v[96:97], v[200:201]
	v_pk_add_f32 v[198:199], v[198:199], v[200:201]
	v_add_f32_e32 v198, v198, v199
	s_nop 1
	v_add_f32_dpp v198, v198, v198 quad_perm:[1,0,3,2] row_mask:0xf bank_mask:0xf
	s_nop 1
	v_add_f32_dpp v198, v198, v198 quad_perm:[2,3,0,1] row_mask:0xf bank_mask:0xf
	s_nop 1
	v_add_f32_dpp v198, v198, v198 row_half_mirror row_mask:0xf bank_mask:0xf
	s_nop 1
	v_add_f32_dpp v198, v198, v198 row_mirror row_mask:0xf bank_mask:0xf
	v_mov_b32_e32 v199, v198
	s_nop 1
	v_permlane16_swap_b32 v199, v198
	v_add_f32_e32 v198, v198, v199
	v_mov_b32_e32 v199, v198
	s_nop 1
	v_permlane32_swap_b32 v199, v198
	v_add_f32_e32 v198, v198, v199
	ds_read_b128 v[130:133], v192
	ds_read_b128 v[134:137], v192 offset:1024
	ds_read_b128 v[138:141], v192 offset:2048
	ds_read_b128 v[142:145], v192 offset:3072
	ds_read_b128 v[146:149], v192 offset:4096
	ds_read_b128 v[150:153], v192 offset:5120
	ds_read_b128 v[154:157], v192 offset:6144
	ds_read_b128 v[158:161], v192 offset:7168
	ds_read_b128 v[178:181], v192 offset:8192
	ds_read_b128 v[182:185], v192 offset:9216
	v_fmamk_f32 v198, v198, 0x3a000000, v241
	v_mul_f32_e32 v199, 0x4b800000, v198
	v_cmp_gt_f32_e32 vcc, s17, v198
	s_nop 1
	v_cndmask_b32_e32 v198, v198, v199, vcc
	v_rsq_f32_e32 v198, v198
	s_nop 0
	v_mul_f32_e32 v199, 0x45800000, v198
	v_cndmask_b32_e32 v202, v198, v199, vcc
	v_pk_mul_f32 v[98:99], v[66:67], v[202:203] op_sel_hi:[1,0]
	v_pk_mul_f32 v[98:99], v[2:3], v[98:99]
	v_pk_mul_f32 v[100:101], v[68:69], v[202:203] op_sel_hi:[1,0]
	v_pk_mul_f32 v[100:101], v[4:5], v[100:101]
	v_cvt_pk_bf16_f32 v206, v98, v99
	v_cvt_pk_bf16_f32 v207, v100, v101
	global_store_dwordx2 v194, v[206:207], s[52:53]
	v_pk_mul_f32 v[102:103], v[70:71], v[202:203] op_sel_hi:[1,0]
	v_pk_mul_f32 v[102:103], v[6:7], v[102:103]
	v_pk_mul_f32 v[104:105], v[72:73], v[202:203] op_sel_hi:[1,0]
	v_pk_mul_f32 v[104:105], v[8:9], v[104:105]
	v_cvt_pk_bf16_f32 v206, v102, v103
	v_cvt_pk_bf16_f32 v207, v104, v105
	global_store_dwordx2 v194, v[206:207], s[52:53] offset:512
	v_pk_mul_f32 v[106:107], v[74:75], v[202:203] op_sel_hi:[1,0]
	v_pk_mul_f32 v[106:107], v[10:11], v[106:107]
	v_pk_mul_f32 v[108:109], v[76:77], v[202:203] op_sel_hi:[1,0]
	v_pk_mul_f32 v[108:109], v[12:13], v[108:109]
	v_cvt_pk_bf16_f32 v206, v106, v107
	v_cvt_pk_bf16_f32 v207, v108, v109
	global_store_dwordx2 v194, v[206:207], s[52:53] offset:1024
	v_pk_mul_f32 v[110:111], v[78:79], v[202:203] op_sel_hi:[1,0]
	v_pk_mul_f32 v[110:111], v[14:15], v[110:111]
	v_pk_mul_f32 v[112:113], v[80:81], v[202:203] op_sel_hi:[1,0]
	v_pk_mul_f32 v[112:113], v[16:17], v[112:113]
	v_cvt_pk_bf16_f32 v206, v110, v111
	v_cvt_pk_bf16_f32 v207, v112, v113
	global_store_dwordx2 v194, v[206:207], s[52:53] offset:1536
	v_pk_mul_f32 v[114:115], v[82:83], v[202:203] op_sel_hi:[1,0]
	v_pk_mul_f32 v[114:115], v[18:19], v[114:115]
	v_pk_mul_f32 v[116:117], v[84:85], v[202:203] op_sel_hi:[1,0]
	v_pk_mul_f32 v[116:117], v[20:21], v[116:117]
	v_cvt_pk_bf16_f32 v206, v114, v115
	v_cvt_pk_bf16_f32 v207, v116, v117
	global_store_dwordx2 v194, v[206:207], s[52:53] offset:2048
	v_pk_mul_f32 v[118:119], v[86:87], v[202:203] op_sel_hi:[1,0]
	v_pk_mul_f32 v[118:119], v[22:23], v[118:119]
	v_pk_mul_f32 v[120:121], v[88:89], v[202:203] op_sel_hi:[1,0]
	v_pk_mul_f32 v[120:121], v[24:25], v[120:121]
	v_cvt_pk_bf16_f32 v206, v118, v119
	v_cvt_pk_bf16_f32 v207, v120, v121
	global_store_dwordx2 v194, v[206:207], s[52:53] offset:2560
	v_pk_mul_f32 v[122:123], v[90:91], v[202:203] op_sel_hi:[1,0]
	v_pk_mul_f32 v[122:123], v[26:27], v[122:123]
	v_pk_mul_f32 v[124:125], v[92:93], v[202:203] op_sel_hi:[1,0]
	v_pk_mul_f32 v[124:125], v[28:29], v[124:125]
	v_cvt_pk_bf16_f32 v206, v122, v123
	v_cvt_pk_bf16_f32 v207, v124, v125
	global_store_dwordx2 v194, v[206:207], s[52:53] offset:3072
	v_pk_mul_f32 v[126:127], v[94:95], v[202:203] op_sel_hi:[1,0]
	v_pk_mul_f32 v[126:127], v[30:31], v[126:127]
	v_pk_mul_f32 v[128:129], v[96:97], v[202:203] op_sel_hi:[1,0]
	v_pk_mul_f32 v[128:129], v[32:33], v[128:129]
	v_cvt_pk_bf16_f32 v206, v126, v127
	v_cvt_pk_bf16_f32 v207, v128, v129
	global_store_dwordx2 v194, v[206:207], s[52:53] offset:3584
	v_add_u32_e32 v194, 0x800000, v194
	global_load_dwordx4 v[66:69], v193, s[12:13] offset:-4096 nt
	global_load_dwordx4 v[70:73], v193, s[12:13] offset:-3072 nt
	global_load_dwordx4 v[74:77], v193, s[12:13] offset:-2048 nt
	global_load_dwordx4 v[78:81], v193, s[12:13] offset:-1024 nt
	global_load_dwordx4 v[82:85], v193, s[12:13] offset:0 nt
	global_load_dwordx4 v[86:89], v193, s[12:13] offset:1024 nt
	global_load_dwordx4 v[90:93], v193, s[12:13] offset:2048 nt
	global_load_dwordx4 v[94:97], v193, s[12:13] offset:3072 nt
	v_add_u32_e32 v193, s0, v193
	s_waitcnt lgkmcnt(8)
	v_pk_mul_f32 v[162:163], v[130:131], v[98:99] op_sel_hi:[1,0]
	v_pk_mul_f32 v[164:165], v[132:133], v[98:99] op_sel_hi:[1,0]
	v_pk_mul_f32 v[166:167], v[134:135], v[98:99] op_sel_hi:[1,0]
	v_pk_mul_f32 v[168:169], v[136:137], v[98:99] op_sel_hi:[1,0]
	ds_read_b128 v[130:133], v192 offset:10240
	ds_read_b128 v[134:137], v192 offset:11264
	s_waitcnt lgkmcnt(8)
	v_pk_fma_f32 v[162:163], v[138:139], v[98:99], v[162:163] op_sel:[0,1,0] op_sel_hi:[1,1,1]
	v_pk_fma_f32 v[164:165], v[140:141], v[98:99], v[164:165] op_sel:[0,1,0] op_sel_hi:[1,1,1]
	v_pk_fma_f32 v[166:167], v[142:143], v[98:99], v[166:167] op_sel:[0,1,0] op_sel_hi:[1,1,1]
	v_pk_fma_f32 v[168:169], v[144:145], v[98:99], v[168:169] op_sel:[0,1,0] op_sel_hi:[1,1,1]
	ds_read_b128 v[138:141], v192 offset:12288
	ds_read_b128 v[142:145], v192 offset:13312
	s_waitcnt lgkmcnt(8)
	v_pk_fma_f32 v[162:163], v[146:147], v[100:101], v[162:163] op_sel_hi:[1,0,1]
	v_pk_fma_f32 v[164:165], v[148:149], v[100:101], v[164:165] op_sel_hi:[1,0,1]
	v_pk_fma_f32 v[166:167], v[150:151], v[100:101], v[166:167] op_sel_hi:[1,0,1]
	v_pk_fma_f32 v[168:169], v[152:153], v[100:101], v[168:169] op_sel_hi:[1,0,1]
	ds_read_b128 v[146:149], v192 offset:14336
	ds_read_b128 v[150:153], v192 offset:15360
	s_waitcnt lgkmcnt(8)
	v_pk_fma_f32 v[162:163], v[154:155], v[100:101], v[162:163] op_sel:[0,1,0] op_sel_hi:[1,1,1]
	v_pk_fma_f32 v[164:165], v[156:157], v[100:101], v[164:165] op_sel:[0,1,0] op_sel_hi:[1,1,1]
	v_pk_fma_f32 v[166:167], v[158:159], v[100:101], v[166:167] op_sel:[0,1,0] op_sel_hi:[1,1,1]
	v_pk_fma_f32 v[168:169], v[160:161], v[100:101], v[168:169] op_sel:[0,1,0] op_sel_hi:[1,1,1]
	ds_read_b128 v[154:157], v192 offset:16384
	ds_read_b128 v[158:161], v192 offset:17408
	s_waitcnt lgkmcnt(8)
	v_pk_fma_f32 v[162:163], v[178:179], v[102:103], v[162:163] op_sel_hi:[1,0,1]
	v_pk_fma_f32 v[164:165], v[180:181], v[102:103], v[164:165] op_sel_hi:[1,0,1]
	v_pk_fma_f32 v[166:167], v[182:183], v[102:103], v[166:167] op_sel_hi:[1,0,1]
	v_pk_fma_f32 v[168:169], v[184:185], v[102:103], v[168:169] op_sel_hi:[1,0,1]
	ds_read_b128 v[178:181], v192 offset:18432
	ds_read_b128 v[182:185], v192 offset:19456
	s_waitcnt lgkmcnt(8)
	v_pk_fma_f32 v[162:163], v[130:131], v[102:103], v[162:163] op_sel:[0,1,0] op_sel_hi:[1,1,1]
	v_pk_fma_f32 v[164:165], v[132:133], v[102:103], v[164:165] op_sel:[0,1,0] op_sel_hi:[1,1,1]
	v_pk_fma_f32 v[166:167], v[134:135], v[102:103], v[166:167] op_sel:[0,1,0] op_sel_hi:[1,1,1]
	v_pk_fma_f32 v[168:169], v[136:137], v[102:103], v[168:169] op_sel:[0,1,0] op_sel_hi:[1,1,1]
	ds_read_b128 v[130:133], v192 offset:20480
	ds_read_b128 v[134:137], v192 offset:21504
	s_waitcnt lgkmcnt(8)
	v_pk_fma_f32 v[162:163], v[138:139], v[104:105], v[162:163] op_sel_hi:[1,0,1]
	v_pk_fma_f32 v[164:165], v[140:141], v[104:105], v[164:165] op_sel_hi:[1,0,1]
	v_pk_fma_f32 v[166:167], v[142:143], v[104:105], v[166:167] op_sel_hi:[1,0,1]
	v_pk_fma_f32 v[168:169], v[144:145], v[104:105], v[168:169] op_sel_hi:[1,0,1]
	ds_read_b128 v[138:141], v192 offset:22528
	ds_read_b128 v[142:145], v192 offset:23552
	s_waitcnt lgkmcnt(8)
	v_pk_fma_f32 v[162:163], v[146:147], v[104:105], v[162:163] op_sel:[0,1,0] op_sel_hi:[1,1,1]
	v_pk_fma_f32 v[164:165], v[148:149], v[104:105], v[164:165] op_sel:[0,1,0] op_sel_hi:[1,1,1]
	v_pk_fma_f32 v[166:167], v[150:151], v[104:105], v[166:167] op_sel:[0,1,0] op_sel_hi:[1,1,1]
	v_pk_fma_f32 v[168:169], v[152:153], v[104:105], v[168:169] op_sel:[0,1,0] op_sel_hi:[1,1,1]
	ds_read_b128 v[146:149], v192 offset:24576
	ds_read_b128 v[150:153], v192 offset:25600
	s_waitcnt lgkmcnt(8)
	v_pk_fma_f32 v[162:163], v[154:155], v[106:107], v[162:163] op_sel_hi:[1,0,1]
	v_pk_fma_f32 v[164:165], v[156:157], v[106:107], v[164:165] op_sel_hi:[1,0,1]
	v_pk_fma_f32 v[166:167], v[158:159], v[106:107], v[166:167] op_sel_hi:[1,0,1]
	v_pk_fma_f32 v[168:169], v[160:161], v[106:107], v[168:169] op_sel_hi:[1,0,1]
	ds_read_b128 v[154:157], v192 offset:26624
	ds_read_b128 v[158:161], v192 offset:27648
	s_waitcnt lgkmcnt(8)
	v_pk_fma_f32 v[162:163], v[178:179], v[106:107], v[162:163] op_sel:[0,1,0] op_sel_hi:[1,1,1]
	v_pk_fma_f32 v[164:165], v[180:181], v[106:107], v[164:165] op_sel:[0,1,0] op_sel_hi:[1,1,1]
	v_pk_fma_f32 v[166:167], v[182:183], v[106:107], v[166:167] op_sel:[0,1,0] op_sel_hi:[1,1,1]
	v_pk_fma_f32 v[168:169], v[184:185], v[106:107], v[168:169] op_sel:[0,1,0] op_sel_hi:[1,1,1]
	ds_read_b128 v[178:181], v192 offset:28672
	ds_read_b128 v[182:185], v192 offset:29696
	s_waitcnt lgkmcnt(8)
	v_pk_fma_f32 v[162:163], v[130:131], v[108:109], v[162:163] op_sel_hi:[1,0,1]
	v_pk_fma_f32 v[164:165], v[132:133], v[108:109], v[164:165] op_sel_hi:[1,0,1]
	v_pk_fma_f32 v[166:167], v[134:135], v[108:109], v[166:167] op_sel_hi:[1,0,1]
	v_pk_fma_f32 v[168:169], v[136:137], v[108:109], v[168:169] op_sel_hi:[1,0,1]
	ds_read_b128 v[130:133], v192 offset:30720
	ds_read_b128 v[134:137], v192 offset:31744
	s_waitcnt lgkmcnt(8)
	v_pk_fma_f32 v[162:163], v[138:139], v[108:109], v[162:163] op_sel:[0,1,0] op_sel_hi:[1,1,1]
	v_pk_fma_f32 v[164:165], v[140:141], v[108:109], v[164:165] op_sel:[0,1,0] op_sel_hi:[1,1,1]
	v_pk_fma_f32 v[166:167], v[142:143], v[108:109], v[166:167] op_sel:[0,1,0] op_sel_hi:[1,1,1]
	v_pk_fma_f32 v[168:169], v[144:145], v[108:109], v[168:169] op_sel:[0,1,0] op_sel_hi:[1,1,1]
	ds_read_b128 v[138:141], v192 offset:32768
	ds_read_b128 v[142:145], v192 offset:33792
	s_waitcnt lgkmcnt(8)
	v_pk_fma_f32 v[162:163], v[146:147], v[110:111], v[162:163] op_sel_hi:[1,0,1]
	v_pk_fma_f32 v[164:165], v[148:149], v[110:111], v[164:165] op_sel_hi:[1,0,1]
	v_pk_fma_f32 v[166:167], v[150:151], v[110:111], v[166:167] op_sel_hi:[1,0,1]
	v_pk_fma_f32 v[168:169], v[152:153], v[110:111], v[168:169] op_sel_hi:[1,0,1]
	ds_read_b128 v[146:149], v192 offset:34816
	ds_read_b128 v[150:153], v192 offset:35840
	s_waitcnt lgkmcnt(8)
	v_pk_fma_f32 v[162:163], v[154:155], v[110:111], v[162:163] op_sel:[0,1,0] op_sel_hi:[1,1,1]
	v_pk_fma_f32 v[164:165], v[156:157], v[110:111], v[164:165] op_sel:[0,1,0] op_sel_hi:[1,1,1]
	v_pk_fma_f32 v[166:167], v[158:159], v[110:111], v[166:167] op_sel:[0,1,0] op_sel_hi:[1,1,1]
	v_pk_fma_f32 v[168:169], v[160:161], v[110:111], v[168:169] op_sel:[0,1,0] op_sel_hi:[1,1,1]
	ds_read_b128 v[154:157], v192 offset:36864
	ds_read_b128 v[158:161], v192 offset:37888
	s_waitcnt lgkmcnt(8)
	v_pk_fma_f32 v[162:163], v[178:179], v[112:113], v[162:163] op_sel_hi:[1,0,1]
	v_pk_fma_f32 v[164:165], v[180:181], v[112:113], v[164:165] op_sel_hi:[1,0,1]
	v_pk_fma_f32 v[166:167], v[182:183], v[112:113], v[166:167] op_sel_hi:[1,0,1]
	v_pk_fma_f32 v[168:169], v[184:185], v[112:113], v[168:169] op_sel_hi:[1,0,1]
	ds_read_b128 v[178:181], v192 offset:38912
	ds_read_b128 v[182:185], v192 offset:39936
	s_waitcnt lgkmcnt(8)
	v_pk_fma_f32 v[162:163], v[130:131], v[112:113], v[162:163] op_sel:[0,1,0] op_sel_hi:[1,1,1]
	v_pk_fma_f32 v[164:165], v[132:133], v[112:113], v[164:165] op_sel:[0,1,0] op_sel_hi:[1,1,1]
	v_pk_fma_f32 v[166:167], v[134:135], v[112:113], v[166:167] op_sel:[0,1,0] op_sel_hi:[1,1,1]
	v_pk_fma_f32 v[168:169], v[136:137], v[112:113], v[168:169] op_sel:[0,1,0] op_sel_hi:[1,1,1]
	ds_read_b128 v[130:133], v192 offset:40960
	ds_read_b128 v[134:137], v192 offset:41984
	s_waitcnt lgkmcnt(8)
	v_pk_fma_f32 v[162:163], v[138:139], v[114:115], v[162:163] op_sel_hi:[1,0,1]
	v_pk_fma_f32 v[164:165], v[140:141], v[114:115], v[164:165] op_sel_hi:[1,0,1]
	v_pk_fma_f32 v[166:167], v[142:143], v[114:115], v[166:167] op_sel_hi:[1,0,1]
	v_pk_fma_f32 v[168:169], v[144:145], v[114:115], v[168:169] op_sel_hi:[1,0,1]
	ds_read_b128 v[138:141], v192 offset:43008
	ds_read_b128 v[142:145], v192 offset:44032
	s_waitcnt lgkmcnt(8)
	v_pk_fma_f32 v[162:163], v[146:147], v[114:115], v[162:163] op_sel:[0,1,0] op_sel_hi:[1,1,1]
	v_pk_fma_f32 v[164:165], v[148:149], v[114:115], v[164:165] op_sel:[0,1,0] op_sel_hi:[1,1,1]
	v_pk_fma_f32 v[166:167], v[150:151], v[114:115], v[166:167] op_sel:[0,1,0] op_sel_hi:[1,1,1]
	v_pk_fma_f32 v[168:169], v[152:153], v[114:115], v[168:169] op_sel:[0,1,0] op_sel_hi:[1,1,1]
	ds_read_b128 v[146:149], v192 offset:45056
	ds_read_b128 v[150:153], v192 offset:46080
	s_waitcnt lgkmcnt(8)
	v_pk_fma_f32 v[162:163], v[154:155], v[116:117], v[162:163] op_sel_hi:[1,0,1]
	v_pk_fma_f32 v[164:165], v[156:157], v[116:117], v[164:165] op_sel_hi:[1,0,1]
	v_pk_fma_f32 v[166:167], v[158:159], v[116:117], v[166:167] op_sel_hi:[1,0,1]
	v_pk_fma_f32 v[168:169], v[160:161], v[116:117], v[168:169] op_sel_hi:[1,0,1]
	ds_read_b128 v[154:157], v192 offset:47104
	ds_read_b128 v[158:161], v192 offset:48128
	s_waitcnt lgkmcnt(8)
	v_pk_fma_f32 v[162:163], v[178:179], v[116:117], v[162:163] op_sel:[0,1,0] op_sel_hi:[1,1,1]
	v_pk_fma_f32 v[164:165], v[180:181], v[116:117], v[164:165] op_sel:[0,1,0] op_sel_hi:[1,1,1]
	v_pk_fma_f32 v[166:167], v[182:183], v[116:117], v[166:167] op_sel:[0,1,0] op_sel_hi:[1,1,1]
	v_pk_fma_f32 v[168:169], v[184:185], v[116:117], v[168:169] op_sel:[0,1,0] op_sel_hi:[1,1,1]
	ds_read_b128 v[178:181], v192 offset:49152
	ds_read_b128 v[182:185], v192 offset:50176
	s_waitcnt lgkmcnt(8)
	v_pk_fma_f32 v[162:163], v[130:131], v[118:119], v[162:163] op_sel_hi:[1,0,1]
	v_pk_fma_f32 v[164:165], v[132:133], v[118:119], v[164:165] op_sel_hi:[1,0,1]
	v_pk_fma_f32 v[166:167], v[134:135], v[118:119], v[166:167] op_sel_hi:[1,0,1]
	v_pk_fma_f32 v[168:169], v[136:137], v[118:119], v[168:169] op_sel_hi:[1,0,1]
	ds_read_b128 v[130:133], v192 offset:51200
	ds_read_b128 v[134:137], v192 offset:52224
	s_waitcnt lgkmcnt(8)
	v_pk_fma_f32 v[162:163], v[138:139], v[118:119], v[162:163] op_sel:[0,1,0] op_sel_hi:[1,1,1]
	v_pk_fma_f32 v[164:165], v[140:141], v[118:119], v[164:165] op_sel:[0,1,0] op_sel_hi:[1,1,1]
	v_pk_fma_f32 v[166:167], v[142:143], v[118:119], v[166:167] op_sel:[0,1,0] op_sel_hi:[1,1,1]
	v_pk_fma_f32 v[168:169], v[144:145], v[118:119], v[168:169] op_sel:[0,1,0] op_sel_hi:[1,1,1]
	ds_read_b128 v[138:141], v192 offset:53248
	ds_read_b128 v[142:145], v192 offset:54272
	s_waitcnt lgkmcnt(8)
	v_pk_fma_f32 v[162:163], v[146:147], v[120:121], v[162:163] op_sel_hi:[1,0,1]
	v_pk_fma_f32 v[164:165], v[148:149], v[120:121], v[164:165] op_sel_hi:[1,0,1]
	v_pk_fma_f32 v[166:167], v[150:151], v[120:121], v[166:167] op_sel_hi:[1,0,1]
	v_pk_fma_f32 v[168:169], v[152:153], v[120:121], v[168:169] op_sel_hi:[1,0,1]
	ds_read_b128 v[146:149], v192 offset:55296
	ds_read_b128 v[150:153], v192 offset:56320
	s_waitcnt lgkmcnt(8)
	v_pk_fma_f32 v[162:163], v[154:155], v[120:121], v[162:163] op_sel:[0,1,0] op_sel_hi:[1,1,1]
	v_pk_fma_f32 v[164:165], v[156:157], v[120:121], v[164:165] op_sel:[0,1,0] op_sel_hi:[1,1,1]
	v_pk_fma_f32 v[166:167], v[158:159], v[120:121], v[166:167] op_sel:[0,1,0] op_sel_hi:[1,1,1]
	v_pk_fma_f32 v[168:169], v[160:161], v[120:121], v[168:169] op_sel:[0,1,0] op_sel_hi:[1,1,1]
	ds_read_b128 v[154:157], v192 offset:57344
	ds_read_b128 v[158:161], v192 offset:58368
	s_waitcnt lgkmcnt(8)
	v_pk_fma_f32 v[162:163], v[178:179], v[122:123], v[162:163] op_sel_hi:[1,0,1]
	v_pk_fma_f32 v[164:165], v[180:181], v[122:123], v[164:165] op_sel_hi:[1,0,1]
	v_pk_fma_f32 v[166:167], v[182:183], v[122:123], v[166:167] op_sel_hi:[1,0,1]
	v_pk_fma_f32 v[168:169], v[184:185], v[122:123], v[168:169] op_sel_hi:[1,0,1]
	ds_read_b128 v[178:181], v192 offset:59392
	ds_read_b128 v[182:185], v192 offset:60416
	s_waitcnt lgkmcnt(8)
	v_pk_fma_f32 v[162:163], v[130:131], v[122:123], v[162:163] op_sel:[0,1,0] op_sel_hi:[1,1,1]
	v_pk_fma_f32 v[164:165], v[132:133], v[122:123], v[164:165] op_sel:[0,1,0] op_sel_hi:[1,1,1]
	v_pk_fma_f32 v[166:167], v[134:135], v[122:123], v[166:167] op_sel:[0,1,0] op_sel_hi:[1,1,1]
	v_pk_fma_f32 v[168:169], v[136:137], v[122:123], v[168:169] op_sel:[0,1,0] op_sel_hi:[1,1,1]
	ds_read_b128 v[130:133], v192 offset:61440
	ds_read_b128 v[134:137], v192 offset:62464
	s_waitcnt lgkmcnt(8)
	v_pk_fma_f32 v[162:163], v[138:139], v[124:125], v[162:163] op_sel_hi:[1,0,1]
	v_pk_fma_f32 v[164:165], v[140:141], v[124:125], v[164:165] op_sel_hi:[1,0,1]
	v_pk_fma_f32 v[166:167], v[142:143], v[124:125], v[166:167] op_sel_hi:[1,0,1]
	v_pk_fma_f32 v[168:169], v[144:145], v[124:125], v[168:169] op_sel_hi:[1,0,1]
	ds_read_b128 v[138:141], v192 offset:63488
	ds_read_b128 v[142:145], v192 offset:64512
	s_waitcnt lgkmcnt(8)
	v_pk_fma_f32 v[162:163], v[146:147], v[124:125], v[162:163] op_sel:[0,1,0] op_sel_hi:[1,1,1]
	v_pk_fma_f32 v[164:165], v[148:149], v[124:125], v[164:165] op_sel:[0,1,0] op_sel_hi:[1,1,1]
	v_pk_fma_f32 v[166:167], v[150:151], v[124:125], v[166:167] op_sel:[0,1,0] op_sel_hi:[1,1,1]
	v_pk_fma_f32 v[168:169], v[152:153], v[124:125], v[168:169] op_sel:[0,1,0] op_sel_hi:[1,1,1]
	s_waitcnt lgkmcnt(6)
	v_pk_fma_f32 v[162:163], v[154:155], v[126:127], v[162:163] op_sel_hi:[1,0,1]
	v_pk_fma_f32 v[164:165], v[156:157], v[126:127], v[164:165] op_sel_hi:[1,0,1]
	v_pk_fma_f32 v[166:167], v[158:159], v[126:127], v[166:167] op_sel_hi:[1,0,1]
	v_pk_fma_f32 v[168:169], v[160:161], v[126:127], v[168:169] op_sel_hi:[1,0,1]
	s_waitcnt lgkmcnt(4)
	v_pk_fma_f32 v[162:163], v[178:179], v[126:127], v[162:163] op_sel:[0,1,0] op_sel_hi:[1,1,1]
	v_pk_fma_f32 v[164:165], v[180:181], v[126:127], v[164:165] op_sel:[0,1,0] op_sel_hi:[1,1,1]
	v_pk_fma_f32 v[166:167], v[182:183], v[126:127], v[166:167] op_sel:[0,1,0] op_sel_hi:[1,1,1]
	v_pk_fma_f32 v[168:169], v[184:185], v[126:127], v[168:169] op_sel:[0,1,0] op_sel_hi:[1,1,1]
	s_waitcnt lgkmcnt(2)
	v_pk_fma_f32 v[162:163], v[130:131], v[128:129], v[162:163] op_sel_hi:[1,0,1]
	v_pk_fma_f32 v[164:165], v[132:133], v[128:129], v[164:165] op_sel_hi:[1,0,1]
	v_pk_fma_f32 v[166:167], v[134:135], v[128:129], v[166:167] op_sel_hi:[1,0,1]
	v_pk_fma_f32 v[168:169], v[136:137], v[128:129], v[168:169] op_sel_hi:[1,0,1]
	s_waitcnt lgkmcnt(0)
	v_pk_fma_f32 v[162:163], v[138:139], v[128:129], v[162:163] op_sel:[0,1,0] op_sel_hi:[1,1,1]
	v_pk_fma_f32 v[164:165], v[140:141], v[128:129], v[164:165] op_sel:[0,1,0] op_sel_hi:[1,1,1]
	v_pk_fma_f32 v[166:167], v[142:143], v[128:129], v[166:167] op_sel:[0,1,0] op_sel_hi:[1,1,1]
	v_pk_fma_f32 v[168:169], v[144:145], v[128:129], v[168:169] op_sel:[0,1,0] op_sel_hi:[1,1,1]
	s_nop 1
	v_add_f32_dpp v162, v162, v162 quad_perm:[1,0,3,2] row_mask:0xf bank_mask:0xf
	v_add_f32_dpp v163, v163, v163 quad_perm:[1,0,3,2] row_mask:0xf bank_mask:0xf
	v_add_f32_dpp v164, v164, v164 quad_perm:[1,0,3,2] row_mask:0xf bank_mask:0xf
	v_add_f32_dpp v165, v165, v165 quad_perm:[1,0,3,2] row_mask:0xf bank_mask:0xf
	v_add_f32_dpp v166, v166, v166 quad_perm:[1,0,3,2] row_mask:0xf bank_mask:0xf
	v_add_f32_dpp v167, v167, v167 quad_perm:[1,0,3,2] row_mask:0xf bank_mask:0xf
	v_add_f32_dpp v168, v168, v168 quad_perm:[1,0,3,2] row_mask:0xf bank_mask:0xf
	v_add_f32_dpp v169, v169, v169 quad_perm:[1,0,3,2] row_mask:0xf bank_mask:0xf
	v_add_f32_dpp v162, v162, v162 quad_perm:[2,3,0,1] row_mask:0xf bank_mask:0xf
	v_add_f32_dpp v163, v163, v163 quad_perm:[2,3,0,1] row_mask:0xf bank_mask:0xf
	v_add_f32_dpp v164, v164, v164 quad_perm:[2,3,0,1] row_mask:0xf bank_mask:0xf
	v_add_f32_dpp v165, v165, v165 quad_perm:[2,3,0,1] row_mask:0xf bank_mask:0xf
	v_add_f32_dpp v166, v166, v166 quad_perm:[2,3,0,1] row_mask:0xf bank_mask:0xf
	v_add_f32_dpp v167, v167, v167 quad_perm:[2,3,0,1] row_mask:0xf bank_mask:0xf
	v_add_f32_dpp v168, v168, v168 quad_perm:[2,3,0,1] row_mask:0xf bank_mask:0xf
	v_add_f32_dpp v169, v169, v169 quad_perm:[2,3,0,1] row_mask:0xf bank_mask:0xf
	v_add_f32_dpp v162, v162, v162 row_half_mirror row_mask:0xf bank_mask:0xf
	v_add_f32_dpp v163, v163, v163 row_half_mirror row_mask:0xf bank_mask:0xf
	v_add_f32_dpp v164, v164, v164 row_half_mirror row_mask:0xf bank_mask:0xf
	v_add_f32_dpp v165, v165, v165 row_half_mirror row_mask:0xf bank_mask:0xf
	v_add_f32_dpp v166, v166, v166 row_half_mirror row_mask:0xf bank_mask:0xf
	v_add_f32_dpp v167, v167, v167 row_half_mirror row_mask:0xf bank_mask:0xf
	v_add_f32_dpp v168, v168, v168 row_half_mirror row_mask:0xf bank_mask:0xf
	v_add_f32_dpp v169, v169, v169 row_half_mirror row_mask:0xf bank_mask:0xf
	v_add_f32_dpp v162, v162, v162 row_mirror row_mask:0xf bank_mask:0xf
	v_add_f32_dpp v163, v163, v163 row_mirror row_mask:0xf bank_mask:0xf
	v_add_f32_dpp v164, v164, v164 row_mirror row_mask:0xf bank_mask:0xf
	v_add_f32_dpp v165, v165, v165 row_mirror row_mask:0xf bank_mask:0xf
	v_add_f32_dpp v166, v166, v166 row_mirror row_mask:0xf bank_mask:0xf
	v_add_f32_dpp v167, v167, v167 row_mirror row_mask:0xf bank_mask:0xf
	v_add_f32_dpp v168, v168, v168 row_mirror row_mask:0xf bank_mask:0xf
	v_add_f32_dpp v169, v169, v169 row_mirror row_mask:0xf bank_mask:0xf
	v_mov_b32_e32 v170, v162
	v_mov_b32_e32 v171, v163
	v_mov_b32_e32 v172, v164
	v_mov_b32_e32 v173, v165
	v_mov_b32_e32 v174, v166
	v_mov_b32_e32 v175, v167
	v_mov_b32_e32 v176, v168
	v_mov_b32_e32 v177, v169
	v_permlane16_swap_b32 v170, v162
	v_permlane16_swap_b32 v171, v163
	v_permlane16_swap_b32 v172, v164
	v_permlane16_swap_b32 v173, v165
	v_permlane16_swap_b32 v174, v166
	v_permlane16_swap_b32 v175, v167
	v_permlane16_swap_b32 v176, v168
	v_permlane16_swap_b32 v177, v169
	v_add_f32_e32 v162, v162, v170
	v_add_f32_e32 v163, v163, v171
	v_add_f32_e32 v164, v164, v172
	v_add_f32_e32 v165, v165, v173
	v_add_f32_e32 v166, v166, v174
	v_add_f32_e32 v167, v167, v175
	v_add_f32_e32 v168, v168, v176
	v_add_f32_e32 v169, v169, v177
	v_mov_b32_e32 v170, v162
	v_mov_b32_e32 v171, v163
	v_mov_b32_e32 v172, v164
	v_mov_b32_e32 v173, v165
	v_mov_b32_e32 v174, v166
	v_mov_b32_e32 v175, v167
	v_mov_b32_e32 v176, v168
	v_mov_b32_e32 v177, v169
	v_permlane32_swap_b32 v170, v162
	v_permlane32_swap_b32 v171, v163
	v_permlane32_swap_b32 v172, v164
	v_permlane32_swap_b32 v173, v165
	v_permlane32_swap_b32 v174, v166
	v_permlane32_swap_b32 v175, v167
	v_permlane32_swap_b32 v176, v168
	v_permlane32_swap_b32 v177, v169
	v_add_f32_e32 v162, v162, v170
	v_add_f32_e32 v163, v163, v171
	v_add_f32_e32 v164, v164, v172
	v_add_f32_e32 v165, v165, v173
	v_add_f32_e32 v166, v166, v174
	v_add_f32_e32 v167, v167, v175
	v_add_f32_e32 v168, v168, v176
	v_add_f32_e32 v169, v169, v177
	v_readfirstlane_b32 s98, v162
	v_readfirstlane_b32 s99, v163
	v_readfirstlane_b32 s100, v164
	v_readfirstlane_b32 s101, v165
	v_writelane_b32 v230, s98, 24
	v_writelane_b32 v230, s99, 25
	v_writelane_b32 v230, s100, 26
	v_writelane_b32 v230, s101, 27
	v_readfirstlane_b32 s98, v166
	v_readfirstlane_b32 s99, v167
	v_readfirstlane_b32 s100, v168
	v_readfirstlane_b32 s101, v169
	v_writelane_b32 v230, s98, 28
	v_writelane_b32 v230, s99, 29
	v_writelane_b32 v230, s100, 30
	v_writelane_b32 v230, s101, 31
	s_waitcnt vmcnt(16)
	v_pk_mul_f32 v[198:199], v[34:35], v[34:35]
	v_pk_mul_f32 v[200:201], v[36:37], v[36:37]
	v_pk_fma_f32 v[198:199], v[38:39], v[38:39], v[198:199]
	v_pk_fma_f32 v[200:201], v[40:41], v[40:41], v[200:201]
	v_pk_fma_f32 v[198:199], v[42:43], v[42:43], v[198:199]
	v_pk_fma_f32 v[200:201], v[44:45], v[44:45], v[200:201]
	v_pk_fma_f32 v[198:199], v[46:47], v[46:47], v[198:199]
	v_pk_fma_f32 v[200:201], v[48:49], v[48:49], v[200:201]
	v_pk_fma_f32 v[198:199], v[50:51], v[50:51], v[198:199]
	v_pk_fma_f32 v[200:201], v[52:53], v[52:53], v[200:201]
	v_pk_fma_f32 v[198:199], v[54:55], v[54:55], v[198:199]
	v_pk_fma_f32 v[200:201], v[56:57], v[56:57], v[200:201]
	v_pk_fma_f32 v[198:199], v[58:59], v[58:59], v[198:199]
	v_pk_fma_f32 v[200:201], v[60:61], v[60:61], v[200:201]
	v_pk_fma_f32 v[198:199], v[62:63], v[62:63], v[198:199]
	v_pk_fma_f32 v[200:201], v[64:65], v[64:65], v[200:201]
	v_pk_add_f32 v[198:199], v[198:199], v[200:201]
	v_add_f32_e32 v198, v198, v199
	s_nop 1
	v_add_f32_dpp v198, v198, v198 quad_perm:[1,0,3,2] row_mask:0xf bank_mask:0xf
	s_nop 1
	v_add_f32_dpp v198, v198, v198 quad_perm:[2,3,0,1] row_mask:0xf bank_mask:0xf
	s_nop 1
	v_add_f32_dpp v198, v198, v198 row_half_mirror row_mask:0xf bank_mask:0xf
	s_nop 1
	v_add_f32_dpp v198, v198, v198 row_mirror row_mask:0xf bank_mask:0xf
	v_mov_b32_e32 v199, v198
	s_nop 1
	v_permlane16_swap_b32 v199, v198
	v_add_f32_e32 v198, v198, v199
	v_mov_b32_e32 v199, v198
	s_nop 1
	v_permlane32_swap_b32 v199, v198
	v_add_f32_e32 v198, v198, v199
	ds_read_b128 v[130:133], v192
	ds_read_b128 v[134:137], v192 offset:1024
	ds_read_b128 v[138:141], v192 offset:2048
	ds_read_b128 v[142:145], v192 offset:3072
	ds_read_b128 v[146:149], v192 offset:4096
	ds_read_b128 v[150:153], v192 offset:5120
	ds_read_b128 v[154:157], v192 offset:6144
	ds_read_b128 v[158:161], v192 offset:7168
	ds_read_b128 v[178:181], v192 offset:8192
	ds_read_b128 v[182:185], v192 offset:9216
	v_fmamk_f32 v198, v198, 0x3a000000, v241
	v_mul_f32_e32 v199, 0x4b800000, v198
	v_cmp_gt_f32_e32 vcc, s17, v198
	s_nop 1
	v_cndmask_b32_e32 v198, v198, v199, vcc
	v_rsq_f32_e32 v198, v198
	s_nop 0
	v_mul_f32_e32 v199, 0x45800000, v198
	v_cndmask_b32_e32 v202, v198, v199, vcc
	v_pk_mul_f32 v[98:99], v[34:35], v[202:203] op_sel_hi:[1,0]
	v_pk_mul_f32 v[98:99], v[2:3], v[98:99]
	v_pk_mul_f32 v[100:101], v[36:37], v[202:203] op_sel_hi:[1,0]
	v_pk_mul_f32 v[100:101], v[4:5], v[100:101]
	v_cvt_pk_bf16_f32 v206, v98, v99
	v_cvt_pk_bf16_f32 v207, v100, v101
	global_store_dwordx2 v194, v[206:207], s[52:53]
	v_pk_mul_f32 v[102:103], v[38:39], v[202:203] op_sel_hi:[1,0]
	v_pk_mul_f32 v[102:103], v[6:7], v[102:103]
	v_pk_mul_f32 v[104:105], v[40:41], v[202:203] op_sel_hi:[1,0]
	v_pk_mul_f32 v[104:105], v[8:9], v[104:105]
	v_cvt_pk_bf16_f32 v206, v102, v103
	v_cvt_pk_bf16_f32 v207, v104, v105
	global_store_dwordx2 v194, v[206:207], s[52:53] offset:512
	v_pk_mul_f32 v[106:107], v[42:43], v[202:203] op_sel_hi:[1,0]
	v_pk_mul_f32 v[106:107], v[10:11], v[106:107]
	v_pk_mul_f32 v[108:109], v[44:45], v[202:203] op_sel_hi:[1,0]
	v_pk_mul_f32 v[108:109], v[12:13], v[108:109]
	v_cvt_pk_bf16_f32 v206, v106, v107
	v_cvt_pk_bf16_f32 v207, v108, v109
	global_store_dwordx2 v194, v[206:207], s[52:53] offset:1024
	v_pk_mul_f32 v[110:111], v[46:47], v[202:203] op_sel_hi:[1,0]
	v_pk_mul_f32 v[110:111], v[14:15], v[110:111]
	v_pk_mul_f32 v[112:113], v[48:49], v[202:203] op_sel_hi:[1,0]
	v_pk_mul_f32 v[112:113], v[16:17], v[112:113]
	v_cvt_pk_bf16_f32 v206, v110, v111
	v_cvt_pk_bf16_f32 v207, v112, v113
	global_store_dwordx2 v194, v[206:207], s[52:53] offset:1536
	v_pk_mul_f32 v[114:115], v[50:51], v[202:203] op_sel_hi:[1,0]
	v_pk_mul_f32 v[114:115], v[18:19], v[114:115]
	v_pk_mul_f32 v[116:117], v[52:53], v[202:203] op_sel_hi:[1,0]
	v_pk_mul_f32 v[116:117], v[20:21], v[116:117]
	v_cvt_pk_bf16_f32 v206, v114, v115
	v_cvt_pk_bf16_f32 v207, v116, v117
	global_store_dwordx2 v194, v[206:207], s[52:53] offset:2048
	v_pk_mul_f32 v[118:119], v[54:55], v[202:203] op_sel_hi:[1,0]
	v_pk_mul_f32 v[118:119], v[22:23], v[118:119]
	v_pk_mul_f32 v[120:121], v[56:57], v[202:203] op_sel_hi:[1,0]
	v_pk_mul_f32 v[120:121], v[24:25], v[120:121]
	v_cvt_pk_bf16_f32 v206, v118, v119
	v_cvt_pk_bf16_f32 v207, v120, v121
	global_store_dwordx2 v194, v[206:207], s[52:53] offset:2560
	v_pk_mul_f32 v[122:123], v[58:59], v[202:203] op_sel_hi:[1,0]
	v_pk_mul_f32 v[122:123], v[26:27], v[122:123]
	v_pk_mul_f32 v[124:125], v[60:61], v[202:203] op_sel_hi:[1,0]
	v_pk_mul_f32 v[124:125], v[28:29], v[124:125]
	v_cvt_pk_bf16_f32 v206, v122, v123
	v_cvt_pk_bf16_f32 v207, v124, v125
	global_store_dwordx2 v194, v[206:207], s[52:53] offset:3072
	v_pk_mul_f32 v[126:127], v[62:63], v[202:203] op_sel_hi:[1,0]
	v_pk_mul_f32 v[126:127], v[30:31], v[126:127]
	v_pk_mul_f32 v[128:129], v[64:65], v[202:203] op_sel_hi:[1,0]
	v_pk_mul_f32 v[128:129], v[32:33], v[128:129]
	v_cvt_pk_bf16_f32 v206, v126, v127
	v_cvt_pk_bf16_f32 v207, v128, v129
	global_store_dwordx2 v194, v[206:207], s[52:53] offset:3584
	v_add_u32_e32 v194, 0x800000, v194
	global_load_dwordx4 v[34:37], v193, s[12:13] offset:-4096 nt
	global_load_dwordx4 v[38:41], v193, s[12:13] offset:-3072 nt
	global_load_dwordx4 v[42:45], v193, s[12:13] offset:-2048 nt
	global_load_dwordx4 v[46:49], v193, s[12:13] offset:-1024 nt
	global_load_dwordx4 v[50:53], v193, s[12:13] offset:0 nt
	global_load_dwordx4 v[54:57], v193, s[12:13] offset:1024 nt
	global_load_dwordx4 v[58:61], v193, s[12:13] offset:2048 nt
	global_load_dwordx4 v[62:65], v193, s[12:13] offset:3072 nt
	v_add_u32_e32 v193, s0, v193
	s_waitcnt lgkmcnt(8)
	v_pk_mul_f32 v[162:163], v[130:131], v[98:99] op_sel_hi:[1,0]
	v_pk_mul_f32 v[164:165], v[132:133], v[98:99] op_sel_hi:[1,0]
	v_pk_mul_f32 v[166:167], v[134:135], v[98:99] op_sel_hi:[1,0]
	v_pk_mul_f32 v[168:169], v[136:137], v[98:99] op_sel_hi:[1,0]
	ds_read_b128 v[130:133], v192 offset:10240
	ds_read_b128 v[134:137], v192 offset:11264
	s_waitcnt lgkmcnt(8)
	v_pk_fma_f32 v[162:163], v[138:139], v[98:99], v[162:163] op_sel:[0,1,0] op_sel_hi:[1,1,1]
	v_pk_fma_f32 v[164:165], v[140:141], v[98:99], v[164:165] op_sel:[0,1,0] op_sel_hi:[1,1,1]
	v_pk_fma_f32 v[166:167], v[142:143], v[98:99], v[166:167] op_sel:[0,1,0] op_sel_hi:[1,1,1]
	v_pk_fma_f32 v[168:169], v[144:145], v[98:99], v[168:169] op_sel:[0,1,0] op_sel_hi:[1,1,1]
	ds_read_b128 v[138:141], v192 offset:12288
	ds_read_b128 v[142:145], v192 offset:13312
	s_waitcnt lgkmcnt(8)
	v_pk_fma_f32 v[162:163], v[146:147], v[100:101], v[162:163] op_sel_hi:[1,0,1]
	v_pk_fma_f32 v[164:165], v[148:149], v[100:101], v[164:165] op_sel_hi:[1,0,1]
	v_pk_fma_f32 v[166:167], v[150:151], v[100:101], v[166:167] op_sel_hi:[1,0,1]
	v_pk_fma_f32 v[168:169], v[152:153], v[100:101], v[168:169] op_sel_hi:[1,0,1]
	ds_read_b128 v[146:149], v192 offset:14336
	ds_read_b128 v[150:153], v192 offset:15360
	s_waitcnt lgkmcnt(8)
	v_pk_fma_f32 v[162:163], v[154:155], v[100:101], v[162:163] op_sel:[0,1,0] op_sel_hi:[1,1,1]
	v_pk_fma_f32 v[164:165], v[156:157], v[100:101], v[164:165] op_sel:[0,1,0] op_sel_hi:[1,1,1]
	v_pk_fma_f32 v[166:167], v[158:159], v[100:101], v[166:167] op_sel:[0,1,0] op_sel_hi:[1,1,1]
	v_pk_fma_f32 v[168:169], v[160:161], v[100:101], v[168:169] op_sel:[0,1,0] op_sel_hi:[1,1,1]
	ds_read_b128 v[154:157], v192 offset:16384
	ds_read_b128 v[158:161], v192 offset:17408
	s_waitcnt lgkmcnt(8)
	v_pk_fma_f32 v[162:163], v[178:179], v[102:103], v[162:163] op_sel_hi:[1,0,1]
	v_pk_fma_f32 v[164:165], v[180:181], v[102:103], v[164:165] op_sel_hi:[1,0,1]
	v_pk_fma_f32 v[166:167], v[182:183], v[102:103], v[166:167] op_sel_hi:[1,0,1]
	v_pk_fma_f32 v[168:169], v[184:185], v[102:103], v[168:169] op_sel_hi:[1,0,1]
	ds_read_b128 v[178:181], v192 offset:18432
	ds_read_b128 v[182:185], v192 offset:19456
	s_waitcnt lgkmcnt(8)
	v_pk_fma_f32 v[162:163], v[130:131], v[102:103], v[162:163] op_sel:[0,1,0] op_sel_hi:[1,1,1]
	v_pk_fma_f32 v[164:165], v[132:133], v[102:103], v[164:165] op_sel:[0,1,0] op_sel_hi:[1,1,1]
	v_pk_fma_f32 v[166:167], v[134:135], v[102:103], v[166:167] op_sel:[0,1,0] op_sel_hi:[1,1,1]
	v_pk_fma_f32 v[168:169], v[136:137], v[102:103], v[168:169] op_sel:[0,1,0] op_sel_hi:[1,1,1]
	ds_read_b128 v[130:133], v192 offset:20480
	ds_read_b128 v[134:137], v192 offset:21504
	s_waitcnt lgkmcnt(8)
	v_pk_fma_f32 v[162:163], v[138:139], v[104:105], v[162:163] op_sel_hi:[1,0,1]
	v_pk_fma_f32 v[164:165], v[140:141], v[104:105], v[164:165] op_sel_hi:[1,0,1]
	v_pk_fma_f32 v[166:167], v[142:143], v[104:105], v[166:167] op_sel_hi:[1,0,1]
	v_pk_fma_f32 v[168:169], v[144:145], v[104:105], v[168:169] op_sel_hi:[1,0,1]
	ds_read_b128 v[138:141], v192 offset:22528
	ds_read_b128 v[142:145], v192 offset:23552
	s_waitcnt lgkmcnt(8)
	v_pk_fma_f32 v[162:163], v[146:147], v[104:105], v[162:163] op_sel:[0,1,0] op_sel_hi:[1,1,1]
	v_pk_fma_f32 v[164:165], v[148:149], v[104:105], v[164:165] op_sel:[0,1,0] op_sel_hi:[1,1,1]
	v_pk_fma_f32 v[166:167], v[150:151], v[104:105], v[166:167] op_sel:[0,1,0] op_sel_hi:[1,1,1]
	v_pk_fma_f32 v[168:169], v[152:153], v[104:105], v[168:169] op_sel:[0,1,0] op_sel_hi:[1,1,1]
	ds_read_b128 v[146:149], v192 offset:24576
	ds_read_b128 v[150:153], v192 offset:25600
	s_waitcnt lgkmcnt(8)
	v_pk_fma_f32 v[162:163], v[154:155], v[106:107], v[162:163] op_sel_hi:[1,0,1]
	v_pk_fma_f32 v[164:165], v[156:157], v[106:107], v[164:165] op_sel_hi:[1,0,1]
	v_pk_fma_f32 v[166:167], v[158:159], v[106:107], v[166:167] op_sel_hi:[1,0,1]
	v_pk_fma_f32 v[168:169], v[160:161], v[106:107], v[168:169] op_sel_hi:[1,0,1]
	ds_read_b128 v[154:157], v192 offset:26624
	ds_read_b128 v[158:161], v192 offset:27648
	s_waitcnt lgkmcnt(8)
	v_pk_fma_f32 v[162:163], v[178:179], v[106:107], v[162:163] op_sel:[0,1,0] op_sel_hi:[1,1,1]
	v_pk_fma_f32 v[164:165], v[180:181], v[106:107], v[164:165] op_sel:[0,1,0] op_sel_hi:[1,1,1]
	v_pk_fma_f32 v[166:167], v[182:183], v[106:107], v[166:167] op_sel:[0,1,0] op_sel_hi:[1,1,1]
	v_pk_fma_f32 v[168:169], v[184:185], v[106:107], v[168:169] op_sel:[0,1,0] op_sel_hi:[1,1,1]
	ds_read_b128 v[178:181], v192 offset:28672
	ds_read_b128 v[182:185], v192 offset:29696
	s_waitcnt lgkmcnt(8)
	v_pk_fma_f32 v[162:163], v[130:131], v[108:109], v[162:163] op_sel_hi:[1,0,1]
	v_pk_fma_f32 v[164:165], v[132:133], v[108:109], v[164:165] op_sel_hi:[1,0,1]
	v_pk_fma_f32 v[166:167], v[134:135], v[108:109], v[166:167] op_sel_hi:[1,0,1]
	v_pk_fma_f32 v[168:169], v[136:137], v[108:109], v[168:169] op_sel_hi:[1,0,1]
	ds_read_b128 v[130:133], v192 offset:30720
	ds_read_b128 v[134:137], v192 offset:31744
	s_waitcnt lgkmcnt(8)
	v_pk_fma_f32 v[162:163], v[138:139], v[108:109], v[162:163] op_sel:[0,1,0] op_sel_hi:[1,1,1]
	v_pk_fma_f32 v[164:165], v[140:141], v[108:109], v[164:165] op_sel:[0,1,0] op_sel_hi:[1,1,1]
	v_pk_fma_f32 v[166:167], v[142:143], v[108:109], v[166:167] op_sel:[0,1,0] op_sel_hi:[1,1,1]
	v_pk_fma_f32 v[168:169], v[144:145], v[108:109], v[168:169] op_sel:[0,1,0] op_sel_hi:[1,1,1]
	ds_read_b128 v[138:141], v192 offset:32768
	ds_read_b128 v[142:145], v192 offset:33792
	s_waitcnt lgkmcnt(8)
	v_pk_fma_f32 v[162:163], v[146:147], v[110:111], v[162:163] op_sel_hi:[1,0,1]
	v_pk_fma_f32 v[164:165], v[148:149], v[110:111], v[164:165] op_sel_hi:[1,0,1]
	v_pk_fma_f32 v[166:167], v[150:151], v[110:111], v[166:167] op_sel_hi:[1,0,1]
	v_pk_fma_f32 v[168:169], v[152:153], v[110:111], v[168:169] op_sel_hi:[1,0,1]
	ds_read_b128 v[146:149], v192 offset:34816
	ds_read_b128 v[150:153], v192 offset:35840
	s_waitcnt lgkmcnt(8)
	v_pk_fma_f32 v[162:163], v[154:155], v[110:111], v[162:163] op_sel:[0,1,0] op_sel_hi:[1,1,1]
	v_pk_fma_f32 v[164:165], v[156:157], v[110:111], v[164:165] op_sel:[0,1,0] op_sel_hi:[1,1,1]
	v_pk_fma_f32 v[166:167], v[158:159], v[110:111], v[166:167] op_sel:[0,1,0] op_sel_hi:[1,1,1]
	v_pk_fma_f32 v[168:169], v[160:161], v[110:111], v[168:169] op_sel:[0,1,0] op_sel_hi:[1,1,1]
	ds_read_b128 v[154:157], v192 offset:36864
	ds_read_b128 v[158:161], v192 offset:37888
	s_waitcnt lgkmcnt(8)
	v_pk_fma_f32 v[162:163], v[178:179], v[112:113], v[162:163] op_sel_hi:[1,0,1]
	v_pk_fma_f32 v[164:165], v[180:181], v[112:113], v[164:165] op_sel_hi:[1,0,1]
	v_pk_fma_f32 v[166:167], v[182:183], v[112:113], v[166:167] op_sel_hi:[1,0,1]
	v_pk_fma_f32 v[168:169], v[184:185], v[112:113], v[168:169] op_sel_hi:[1,0,1]
	ds_read_b128 v[178:181], v192 offset:38912
	ds_read_b128 v[182:185], v192 offset:39936
	s_waitcnt lgkmcnt(8)
	v_pk_fma_f32 v[162:163], v[130:131], v[112:113], v[162:163] op_sel:[0,1,0] op_sel_hi:[1,1,1]
	v_pk_fma_f32 v[164:165], v[132:133], v[112:113], v[164:165] op_sel:[0,1,0] op_sel_hi:[1,1,1]
	v_pk_fma_f32 v[166:167], v[134:135], v[112:113], v[166:167] op_sel:[0,1,0] op_sel_hi:[1,1,1]
	v_pk_fma_f32 v[168:169], v[136:137], v[112:113], v[168:169] op_sel:[0,1,0] op_sel_hi:[1,1,1]
	ds_read_b128 v[130:133], v192 offset:40960
	ds_read_b128 v[134:137], v192 offset:41984
	s_waitcnt lgkmcnt(8)
	v_pk_fma_f32 v[162:163], v[138:139], v[114:115], v[162:163] op_sel_hi:[1,0,1]
	v_pk_fma_f32 v[164:165], v[140:141], v[114:115], v[164:165] op_sel_hi:[1,0,1]
	v_pk_fma_f32 v[166:167], v[142:143], v[114:115], v[166:167] op_sel_hi:[1,0,1]
	v_pk_fma_f32 v[168:169], v[144:145], v[114:115], v[168:169] op_sel_hi:[1,0,1]
	ds_read_b128 v[138:141], v192 offset:43008
	ds_read_b128 v[142:145], v192 offset:44032
	s_waitcnt lgkmcnt(8)
	v_pk_fma_f32 v[162:163], v[146:147], v[114:115], v[162:163] op_sel:[0,1,0] op_sel_hi:[1,1,1]
	v_pk_fma_f32 v[164:165], v[148:149], v[114:115], v[164:165] op_sel:[0,1,0] op_sel_hi:[1,1,1]
	v_pk_fma_f32 v[166:167], v[150:151], v[114:115], v[166:167] op_sel:[0,1,0] op_sel_hi:[1,1,1]
	v_pk_fma_f32 v[168:169], v[152:153], v[114:115], v[168:169] op_sel:[0,1,0] op_sel_hi:[1,1,1]
	ds_read_b128 v[146:149], v192 offset:45056
	ds_read_b128 v[150:153], v192 offset:46080
	s_waitcnt lgkmcnt(8)
	v_pk_fma_f32 v[162:163], v[154:155], v[116:117], v[162:163] op_sel_hi:[1,0,1]
	v_pk_fma_f32 v[164:165], v[156:157], v[116:117], v[164:165] op_sel_hi:[1,0,1]
	v_pk_fma_f32 v[166:167], v[158:159], v[116:117], v[166:167] op_sel_hi:[1,0,1]
	v_pk_fma_f32 v[168:169], v[160:161], v[116:117], v[168:169] op_sel_hi:[1,0,1]
	ds_read_b128 v[154:157], v192 offset:47104
	ds_read_b128 v[158:161], v192 offset:48128
	s_waitcnt lgkmcnt(8)
	v_pk_fma_f32 v[162:163], v[178:179], v[116:117], v[162:163] op_sel:[0,1,0] op_sel_hi:[1,1,1]
	v_pk_fma_f32 v[164:165], v[180:181], v[116:117], v[164:165] op_sel:[0,1,0] op_sel_hi:[1,1,1]
	v_pk_fma_f32 v[166:167], v[182:183], v[116:117], v[166:167] op_sel:[0,1,0] op_sel_hi:[1,1,1]
	v_pk_fma_f32 v[168:169], v[184:185], v[116:117], v[168:169] op_sel:[0,1,0] op_sel_hi:[1,1,1]
	ds_read_b128 v[178:181], v192 offset:49152
	ds_read_b128 v[182:185], v192 offset:50176
	s_waitcnt lgkmcnt(8)
	v_pk_fma_f32 v[162:163], v[130:131], v[118:119], v[162:163] op_sel_hi:[1,0,1]
	v_pk_fma_f32 v[164:165], v[132:133], v[118:119], v[164:165] op_sel_hi:[1,0,1]
	v_pk_fma_f32 v[166:167], v[134:135], v[118:119], v[166:167] op_sel_hi:[1,0,1]
	v_pk_fma_f32 v[168:169], v[136:137], v[118:119], v[168:169] op_sel_hi:[1,0,1]
	ds_read_b128 v[130:133], v192 offset:51200
	ds_read_b128 v[134:137], v192 offset:52224
	s_waitcnt lgkmcnt(8)
	v_pk_fma_f32 v[162:163], v[138:139], v[118:119], v[162:163] op_sel:[0,1,0] op_sel_hi:[1,1,1]
	v_pk_fma_f32 v[164:165], v[140:141], v[118:119], v[164:165] op_sel:[0,1,0] op_sel_hi:[1,1,1]
	v_pk_fma_f32 v[166:167], v[142:143], v[118:119], v[166:167] op_sel:[0,1,0] op_sel_hi:[1,1,1]
	v_pk_fma_f32 v[168:169], v[144:145], v[118:119], v[168:169] op_sel:[0,1,0] op_sel_hi:[1,1,1]
	ds_read_b128 v[138:141], v192 offset:53248
	ds_read_b128 v[142:145], v192 offset:54272
	s_waitcnt lgkmcnt(8)
	v_pk_fma_f32 v[162:163], v[146:147], v[120:121], v[162:163] op_sel_hi:[1,0,1]
	v_pk_fma_f32 v[164:165], v[148:149], v[120:121], v[164:165] op_sel_hi:[1,0,1]
	v_pk_fma_f32 v[166:167], v[150:151], v[120:121], v[166:167] op_sel_hi:[1,0,1]
	v_pk_fma_f32 v[168:169], v[152:153], v[120:121], v[168:169] op_sel_hi:[1,0,1]
	ds_read_b128 v[146:149], v192 offset:55296
	ds_read_b128 v[150:153], v192 offset:56320
	s_waitcnt lgkmcnt(8)
	v_pk_fma_f32 v[162:163], v[154:155], v[120:121], v[162:163] op_sel:[0,1,0] op_sel_hi:[1,1,1]
	v_pk_fma_f32 v[164:165], v[156:157], v[120:121], v[164:165] op_sel:[0,1,0] op_sel_hi:[1,1,1]
	v_pk_fma_f32 v[166:167], v[158:159], v[120:121], v[166:167] op_sel:[0,1,0] op_sel_hi:[1,1,1]
	v_pk_fma_f32 v[168:169], v[160:161], v[120:121], v[168:169] op_sel:[0,1,0] op_sel_hi:[1,1,1]
	ds_read_b128 v[154:157], v192 offset:57344
	ds_read_b128 v[158:161], v192 offset:58368
	s_waitcnt lgkmcnt(8)
	v_pk_fma_f32 v[162:163], v[178:179], v[122:123], v[162:163] op_sel_hi:[1,0,1]
	v_pk_fma_f32 v[164:165], v[180:181], v[122:123], v[164:165] op_sel_hi:[1,0,1]
	v_pk_fma_f32 v[166:167], v[182:183], v[122:123], v[166:167] op_sel_hi:[1,0,1]
	v_pk_fma_f32 v[168:169], v[184:185], v[122:123], v[168:169] op_sel_hi:[1,0,1]
	ds_read_b128 v[178:181], v192 offset:59392
	ds_read_b128 v[182:185], v192 offset:60416
	s_waitcnt lgkmcnt(8)
	v_pk_fma_f32 v[162:163], v[130:131], v[122:123], v[162:163] op_sel:[0,1,0] op_sel_hi:[1,1,1]
	v_pk_fma_f32 v[164:165], v[132:133], v[122:123], v[164:165] op_sel:[0,1,0] op_sel_hi:[1,1,1]
	v_pk_fma_f32 v[166:167], v[134:135], v[122:123], v[166:167] op_sel:[0,1,0] op_sel_hi:[1,1,1]
	v_pk_fma_f32 v[168:169], v[136:137], v[122:123], v[168:169] op_sel:[0,1,0] op_sel_hi:[1,1,1]
	ds_read_b128 v[130:133], v192 offset:61440
	ds_read_b128 v[134:137], v192 offset:62464
	s_waitcnt lgkmcnt(8)
	v_pk_fma_f32 v[162:163], v[138:139], v[124:125], v[162:163] op_sel_hi:[1,0,1]
	v_pk_fma_f32 v[164:165], v[140:141], v[124:125], v[164:165] op_sel_hi:[1,0,1]
	v_pk_fma_f32 v[166:167], v[142:143], v[124:125], v[166:167] op_sel_hi:[1,0,1]
	v_pk_fma_f32 v[168:169], v[144:145], v[124:125], v[168:169] op_sel_hi:[1,0,1]
	ds_read_b128 v[138:141], v192 offset:63488
	ds_read_b128 v[142:145], v192 offset:64512
	s_waitcnt lgkmcnt(8)
	v_pk_fma_f32 v[162:163], v[146:147], v[124:125], v[162:163] op_sel:[0,1,0] op_sel_hi:[1,1,1]
	v_pk_fma_f32 v[164:165], v[148:149], v[124:125], v[164:165] op_sel:[0,1,0] op_sel_hi:[1,1,1]
	v_pk_fma_f32 v[166:167], v[150:151], v[124:125], v[166:167] op_sel:[0,1,0] op_sel_hi:[1,1,1]
	v_pk_fma_f32 v[168:169], v[152:153], v[124:125], v[168:169] op_sel:[0,1,0] op_sel_hi:[1,1,1]
	s_waitcnt lgkmcnt(6)
	v_pk_fma_f32 v[162:163], v[154:155], v[126:127], v[162:163] op_sel_hi:[1,0,1]
	v_pk_fma_f32 v[164:165], v[156:157], v[126:127], v[164:165] op_sel_hi:[1,0,1]
	v_pk_fma_f32 v[166:167], v[158:159], v[126:127], v[166:167] op_sel_hi:[1,0,1]
	v_pk_fma_f32 v[168:169], v[160:161], v[126:127], v[168:169] op_sel_hi:[1,0,1]
	s_waitcnt lgkmcnt(4)
	v_pk_fma_f32 v[162:163], v[178:179], v[126:127], v[162:163] op_sel:[0,1,0] op_sel_hi:[1,1,1]
	v_pk_fma_f32 v[164:165], v[180:181], v[126:127], v[164:165] op_sel:[0,1,0] op_sel_hi:[1,1,1]
	v_pk_fma_f32 v[166:167], v[182:183], v[126:127], v[166:167] op_sel:[0,1,0] op_sel_hi:[1,1,1]
	v_pk_fma_f32 v[168:169], v[184:185], v[126:127], v[168:169] op_sel:[0,1,0] op_sel_hi:[1,1,1]
	s_waitcnt lgkmcnt(2)
	v_pk_fma_f32 v[162:163], v[130:131], v[128:129], v[162:163] op_sel_hi:[1,0,1]
	v_pk_fma_f32 v[164:165], v[132:133], v[128:129], v[164:165] op_sel_hi:[1,0,1]
	v_pk_fma_f32 v[166:167], v[134:135], v[128:129], v[166:167] op_sel_hi:[1,0,1]
	v_pk_fma_f32 v[168:169], v[136:137], v[128:129], v[168:169] op_sel_hi:[1,0,1]
	s_waitcnt lgkmcnt(0)
	v_pk_fma_f32 v[162:163], v[138:139], v[128:129], v[162:163] op_sel:[0,1,0] op_sel_hi:[1,1,1]
	v_pk_fma_f32 v[164:165], v[140:141], v[128:129], v[164:165] op_sel:[0,1,0] op_sel_hi:[1,1,1]
	v_pk_fma_f32 v[166:167], v[142:143], v[128:129], v[166:167] op_sel:[0,1,0] op_sel_hi:[1,1,1]
	v_pk_fma_f32 v[168:169], v[144:145], v[128:129], v[168:169] op_sel:[0,1,0] op_sel_hi:[1,1,1]
	s_nop 1
	v_add_f32_dpp v162, v162, v162 quad_perm:[1,0,3,2] row_mask:0xf bank_mask:0xf
	v_add_f32_dpp v163, v163, v163 quad_perm:[1,0,3,2] row_mask:0xf bank_mask:0xf
	v_add_f32_dpp v164, v164, v164 quad_perm:[1,0,3,2] row_mask:0xf bank_mask:0xf
	v_add_f32_dpp v165, v165, v165 quad_perm:[1,0,3,2] row_mask:0xf bank_mask:0xf
	v_add_f32_dpp v166, v166, v166 quad_perm:[1,0,3,2] row_mask:0xf bank_mask:0xf
	v_add_f32_dpp v167, v167, v167 quad_perm:[1,0,3,2] row_mask:0xf bank_mask:0xf
	v_add_f32_dpp v168, v168, v168 quad_perm:[1,0,3,2] row_mask:0xf bank_mask:0xf
	v_add_f32_dpp v169, v169, v169 quad_perm:[1,0,3,2] row_mask:0xf bank_mask:0xf
	v_add_f32_dpp v162, v162, v162 quad_perm:[2,3,0,1] row_mask:0xf bank_mask:0xf
	v_add_f32_dpp v163, v163, v163 quad_perm:[2,3,0,1] row_mask:0xf bank_mask:0xf
	v_add_f32_dpp v164, v164, v164 quad_perm:[2,3,0,1] row_mask:0xf bank_mask:0xf
	v_add_f32_dpp v165, v165, v165 quad_perm:[2,3,0,1] row_mask:0xf bank_mask:0xf
	v_add_f32_dpp v166, v166, v166 quad_perm:[2,3,0,1] row_mask:0xf bank_mask:0xf
	v_add_f32_dpp v167, v167, v167 quad_perm:[2,3,0,1] row_mask:0xf bank_mask:0xf
	v_add_f32_dpp v168, v168, v168 quad_perm:[2,3,0,1] row_mask:0xf bank_mask:0xf
	v_add_f32_dpp v169, v169, v169 quad_perm:[2,3,0,1] row_mask:0xf bank_mask:0xf
	v_add_f32_dpp v162, v162, v162 row_half_mirror row_mask:0xf bank_mask:0xf
	v_add_f32_dpp v163, v163, v163 row_half_mirror row_mask:0xf bank_mask:0xf
	v_add_f32_dpp v164, v164, v164 row_half_mirror row_mask:0xf bank_mask:0xf
	v_add_f32_dpp v165, v165, v165 row_half_mirror row_mask:0xf bank_mask:0xf
	v_add_f32_dpp v166, v166, v166 row_half_mirror row_mask:0xf bank_mask:0xf
	v_add_f32_dpp v167, v167, v167 row_half_mirror row_mask:0xf bank_mask:0xf
	v_add_f32_dpp v168, v168, v168 row_half_mirror row_mask:0xf bank_mask:0xf
	v_add_f32_dpp v169, v169, v169 row_half_mirror row_mask:0xf bank_mask:0xf
	v_add_f32_dpp v162, v162, v162 row_mirror row_mask:0xf bank_mask:0xf
	v_add_f32_dpp v163, v163, v163 row_mirror row_mask:0xf bank_mask:0xf
	v_add_f32_dpp v164, v164, v164 row_mirror row_mask:0xf bank_mask:0xf
	v_add_f32_dpp v165, v165, v165 row_mirror row_mask:0xf bank_mask:0xf
	v_add_f32_dpp v166, v166, v166 row_mirror row_mask:0xf bank_mask:0xf
	v_add_f32_dpp v167, v167, v167 row_mirror row_mask:0xf bank_mask:0xf
	v_add_f32_dpp v168, v168, v168 row_mirror row_mask:0xf bank_mask:0xf
	v_add_f32_dpp v169, v169, v169 row_mirror row_mask:0xf bank_mask:0xf
	v_mov_b32_e32 v170, v162
	v_mov_b32_e32 v171, v163
	v_mov_b32_e32 v172, v164
	v_mov_b32_e32 v173, v165
	v_mov_b32_e32 v174, v166
	v_mov_b32_e32 v175, v167
	v_mov_b32_e32 v176, v168
	v_mov_b32_e32 v177, v169
	v_permlane16_swap_b32 v170, v162
	v_permlane16_swap_b32 v171, v163
	v_permlane16_swap_b32 v172, v164
	v_permlane16_swap_b32 v173, v165
	v_permlane16_swap_b32 v174, v166
	v_permlane16_swap_b32 v175, v167
	v_permlane16_swap_b32 v176, v168
	v_permlane16_swap_b32 v177, v169
	v_add_f32_e32 v162, v162, v170
	v_add_f32_e32 v163, v163, v171
	v_add_f32_e32 v164, v164, v172
	v_add_f32_e32 v165, v165, v173
	v_add_f32_e32 v166, v166, v174
	v_add_f32_e32 v167, v167, v175
	v_add_f32_e32 v168, v168, v176
	v_add_f32_e32 v169, v169, v177
	v_mov_b32_e32 v170, v162
	v_mov_b32_e32 v171, v163
	v_mov_b32_e32 v172, v164
	v_mov_b32_e32 v173, v165
	v_mov_b32_e32 v174, v166
	v_mov_b32_e32 v175, v167
	v_mov_b32_e32 v176, v168
	v_mov_b32_e32 v177, v169
	v_permlane32_swap_b32 v170, v162
	v_permlane32_swap_b32 v171, v163
	v_permlane32_swap_b32 v172, v164
	v_permlane32_swap_b32 v173, v165
	v_permlane32_swap_b32 v174, v166
	v_permlane32_swap_b32 v175, v167
	v_permlane32_swap_b32 v176, v168
	v_permlane32_swap_b32 v177, v169
	v_add_f32_e32 v162, v162, v170
	v_add_f32_e32 v163, v163, v171
	v_add_f32_e32 v164, v164, v172
	v_add_f32_e32 v165, v165, v173
	v_add_f32_e32 v166, v166, v174
	v_add_f32_e32 v167, v167, v175
	v_add_f32_e32 v168, v168, v176
	v_add_f32_e32 v169, v169, v177
	v_readfirstlane_b32 s98, v162
	v_readfirstlane_b32 s99, v163
	v_readfirstlane_b32 s100, v164
	v_readfirstlane_b32 s101, v165
	v_writelane_b32 v230, s98, 32
	v_writelane_b32 v230, s99, 33
	v_writelane_b32 v230, s100, 34
	v_writelane_b32 v230, s101, 35
	v_readfirstlane_b32 s98, v166
	v_readfirstlane_b32 s99, v167
	v_readfirstlane_b32 s100, v168
	v_readfirstlane_b32 s101, v169
	v_writelane_b32 v230, s98, 36
	v_writelane_b32 v230, s99, 37
	v_writelane_b32 v230, s100, 38
	v_writelane_b32 v230, s101, 39
	s_waitcnt vmcnt(16)
	v_pk_mul_f32 v[198:199], v[66:67], v[66:67]
	v_pk_mul_f32 v[200:201], v[68:69], v[68:69]
	v_pk_fma_f32 v[198:199], v[70:71], v[70:71], v[198:199]
	v_pk_fma_f32 v[200:201], v[72:73], v[72:73], v[200:201]
	v_pk_fma_f32 v[198:199], v[74:75], v[74:75], v[198:199]
	v_pk_fma_f32 v[200:201], v[76:77], v[76:77], v[200:201]
	v_pk_fma_f32 v[198:199], v[78:79], v[78:79], v[198:199]
	v_pk_fma_f32 v[200:201], v[80:81], v[80:81], v[200:201]
	v_pk_fma_f32 v[198:199], v[82:83], v[82:83], v[198:199]
	v_pk_fma_f32 v[200:201], v[84:85], v[84:85], v[200:201]
	v_pk_fma_f32 v[198:199], v[86:87], v[86:87], v[198:199]
	v_pk_fma_f32 v[200:201], v[88:89], v[88:89], v[200:201]
	v_pk_fma_f32 v[198:199], v[90:91], v[90:91], v[198:199]
	v_pk_fma_f32 v[200:201], v[92:93], v[92:93], v[200:201]
	v_pk_fma_f32 v[198:199], v[94:95], v[94:95], v[198:199]
	v_pk_fma_f32 v[200:201], v[96:97], v[96:97], v[200:201]
	v_pk_add_f32 v[198:199], v[198:199], v[200:201]
	v_add_f32_e32 v198, v198, v199
	s_nop 1
	v_add_f32_dpp v198, v198, v198 quad_perm:[1,0,3,2] row_mask:0xf bank_mask:0xf
	s_nop 1
	v_add_f32_dpp v198, v198, v198 quad_perm:[2,3,0,1] row_mask:0xf bank_mask:0xf
	s_nop 1
	v_add_f32_dpp v198, v198, v198 row_half_mirror row_mask:0xf bank_mask:0xf
	s_nop 1
	v_add_f32_dpp v198, v198, v198 row_mirror row_mask:0xf bank_mask:0xf
	v_mov_b32_e32 v199, v198
	s_nop 1
	v_permlane16_swap_b32 v199, v198
	v_add_f32_e32 v198, v198, v199
	v_mov_b32_e32 v199, v198
	s_nop 1
	v_permlane32_swap_b32 v199, v198
	v_add_f32_e32 v198, v198, v199
	ds_read_b128 v[130:133], v192
	ds_read_b128 v[134:137], v192 offset:1024
	ds_read_b128 v[138:141], v192 offset:2048
	ds_read_b128 v[142:145], v192 offset:3072
	ds_read_b128 v[146:149], v192 offset:4096
	ds_read_b128 v[150:153], v192 offset:5120
	ds_read_b128 v[154:157], v192 offset:6144
	ds_read_b128 v[158:161], v192 offset:7168
	ds_read_b128 v[178:181], v192 offset:8192
	ds_read_b128 v[182:185], v192 offset:9216
	v_fmamk_f32 v198, v198, 0x3a000000, v241
	v_mul_f32_e32 v199, 0x4b800000, v198
	v_cmp_gt_f32_e32 vcc, s17, v198
	s_nop 1
	v_cndmask_b32_e32 v198, v198, v199, vcc
	v_rsq_f32_e32 v198, v198
	s_nop 0
	v_mul_f32_e32 v199, 0x45800000, v198
	v_cndmask_b32_e32 v202, v198, v199, vcc
	v_pk_mul_f32 v[98:99], v[66:67], v[202:203] op_sel_hi:[1,0]
	v_pk_mul_f32 v[98:99], v[2:3], v[98:99]
	v_pk_mul_f32 v[100:101], v[68:69], v[202:203] op_sel_hi:[1,0]
	v_pk_mul_f32 v[100:101], v[4:5], v[100:101]
	v_cvt_pk_bf16_f32 v206, v98, v99
	v_cvt_pk_bf16_f32 v207, v100, v101
	global_store_dwordx2 v194, v[206:207], s[52:53]
	v_pk_mul_f32 v[102:103], v[70:71], v[202:203] op_sel_hi:[1,0]
	v_pk_mul_f32 v[102:103], v[6:7], v[102:103]
	v_pk_mul_f32 v[104:105], v[72:73], v[202:203] op_sel_hi:[1,0]
	v_pk_mul_f32 v[104:105], v[8:9], v[104:105]
	v_cvt_pk_bf16_f32 v206, v102, v103
	v_cvt_pk_bf16_f32 v207, v104, v105
	global_store_dwordx2 v194, v[206:207], s[52:53] offset:512
	v_pk_mul_f32 v[106:107], v[74:75], v[202:203] op_sel_hi:[1,0]
	v_pk_mul_f32 v[106:107], v[10:11], v[106:107]
	v_pk_mul_f32 v[108:109], v[76:77], v[202:203] op_sel_hi:[1,0]
	v_pk_mul_f32 v[108:109], v[12:13], v[108:109]
	v_cvt_pk_bf16_f32 v206, v106, v107
	v_cvt_pk_bf16_f32 v207, v108, v109
	global_store_dwordx2 v194, v[206:207], s[52:53] offset:1024
	v_pk_mul_f32 v[110:111], v[78:79], v[202:203] op_sel_hi:[1,0]
	v_pk_mul_f32 v[110:111], v[14:15], v[110:111]
	v_pk_mul_f32 v[112:113], v[80:81], v[202:203] op_sel_hi:[1,0]
	v_pk_mul_f32 v[112:113], v[16:17], v[112:113]
	v_cvt_pk_bf16_f32 v206, v110, v111
	v_cvt_pk_bf16_f32 v207, v112, v113
	global_store_dwordx2 v194, v[206:207], s[52:53] offset:1536
	v_pk_mul_f32 v[114:115], v[82:83], v[202:203] op_sel_hi:[1,0]
	v_pk_mul_f32 v[114:115], v[18:19], v[114:115]
	v_pk_mul_f32 v[116:117], v[84:85], v[202:203] op_sel_hi:[1,0]
	v_pk_mul_f32 v[116:117], v[20:21], v[116:117]
	v_cvt_pk_bf16_f32 v206, v114, v115
	v_cvt_pk_bf16_f32 v207, v116, v117
	global_store_dwordx2 v194, v[206:207], s[52:53] offset:2048
	v_pk_mul_f32 v[118:119], v[86:87], v[202:203] op_sel_hi:[1,0]
	v_pk_mul_f32 v[118:119], v[22:23], v[118:119]
	v_pk_mul_f32 v[120:121], v[88:89], v[202:203] op_sel_hi:[1,0]
	v_pk_mul_f32 v[120:121], v[24:25], v[120:121]
	v_cvt_pk_bf16_f32 v206, v118, v119
	v_cvt_pk_bf16_f32 v207, v120, v121
	global_store_dwordx2 v194, v[206:207], s[52:53] offset:2560
	v_pk_mul_f32 v[122:123], v[90:91], v[202:203] op_sel_hi:[1,0]
	v_pk_mul_f32 v[122:123], v[26:27], v[122:123]
	v_pk_mul_f32 v[124:125], v[92:93], v[202:203] op_sel_hi:[1,0]
	v_pk_mul_f32 v[124:125], v[28:29], v[124:125]
	v_cvt_pk_bf16_f32 v206, v122, v123
	v_cvt_pk_bf16_f32 v207, v124, v125
	global_store_dwordx2 v194, v[206:207], s[52:53] offset:3072
	v_pk_mul_f32 v[126:127], v[94:95], v[202:203] op_sel_hi:[1,0]
	v_pk_mul_f32 v[126:127], v[30:31], v[126:127]
	v_pk_mul_f32 v[128:129], v[96:97], v[202:203] op_sel_hi:[1,0]
	v_pk_mul_f32 v[128:129], v[32:33], v[128:129]
	v_cvt_pk_bf16_f32 v206, v126, v127
	v_cvt_pk_bf16_f32 v207, v128, v129
	global_store_dwordx2 v194, v[206:207], s[52:53] offset:3584
	v_add_u32_e32 v194, 0x800000, v194
	global_load_dwordx4 v[66:69], v193, s[12:13] offset:-4096 nt
	global_load_dwordx4 v[70:73], v193, s[12:13] offset:-3072 nt
	global_load_dwordx4 v[74:77], v193, s[12:13] offset:-2048 nt
	global_load_dwordx4 v[78:81], v193, s[12:13] offset:-1024 nt
	global_load_dwordx4 v[82:85], v193, s[12:13] offset:0 nt
	global_load_dwordx4 v[86:89], v193, s[12:13] offset:1024 nt
	global_load_dwordx4 v[90:93], v193, s[12:13] offset:2048 nt
	global_load_dwordx4 v[94:97], v193, s[12:13] offset:3072 nt
	v_add_u32_e32 v193, s0, v193
	s_waitcnt lgkmcnt(8)
	v_pk_mul_f32 v[162:163], v[130:131], v[98:99] op_sel_hi:[1,0]
	v_pk_mul_f32 v[164:165], v[132:133], v[98:99] op_sel_hi:[1,0]
	v_pk_mul_f32 v[166:167], v[134:135], v[98:99] op_sel_hi:[1,0]
	v_pk_mul_f32 v[168:169], v[136:137], v[98:99] op_sel_hi:[1,0]
	ds_read_b128 v[130:133], v192 offset:10240
	ds_read_b128 v[134:137], v192 offset:11264
	s_waitcnt lgkmcnt(8)
	v_pk_fma_f32 v[162:163], v[138:139], v[98:99], v[162:163] op_sel:[0,1,0] op_sel_hi:[1,1,1]
	v_pk_fma_f32 v[164:165], v[140:141], v[98:99], v[164:165] op_sel:[0,1,0] op_sel_hi:[1,1,1]
	v_pk_fma_f32 v[166:167], v[142:143], v[98:99], v[166:167] op_sel:[0,1,0] op_sel_hi:[1,1,1]
	v_pk_fma_f32 v[168:169], v[144:145], v[98:99], v[168:169] op_sel:[0,1,0] op_sel_hi:[1,1,1]
	ds_read_b128 v[138:141], v192 offset:12288
	ds_read_b128 v[142:145], v192 offset:13312
	s_waitcnt lgkmcnt(8)
	v_pk_fma_f32 v[162:163], v[146:147], v[100:101], v[162:163] op_sel_hi:[1,0,1]
	v_pk_fma_f32 v[164:165], v[148:149], v[100:101], v[164:165] op_sel_hi:[1,0,1]
	v_pk_fma_f32 v[166:167], v[150:151], v[100:101], v[166:167] op_sel_hi:[1,0,1]
	v_pk_fma_f32 v[168:169], v[152:153], v[100:101], v[168:169] op_sel_hi:[1,0,1]
	ds_read_b128 v[146:149], v192 offset:14336
	ds_read_b128 v[150:153], v192 offset:15360
	s_waitcnt lgkmcnt(8)
	v_pk_fma_f32 v[162:163], v[154:155], v[100:101], v[162:163] op_sel:[0,1,0] op_sel_hi:[1,1,1]
	v_pk_fma_f32 v[164:165], v[156:157], v[100:101], v[164:165] op_sel:[0,1,0] op_sel_hi:[1,1,1]
	v_pk_fma_f32 v[166:167], v[158:159], v[100:101], v[166:167] op_sel:[0,1,0] op_sel_hi:[1,1,1]
	v_pk_fma_f32 v[168:169], v[160:161], v[100:101], v[168:169] op_sel:[0,1,0] op_sel_hi:[1,1,1]
	ds_read_b128 v[154:157], v192 offset:16384
	ds_read_b128 v[158:161], v192 offset:17408
	s_waitcnt lgkmcnt(8)
	v_pk_fma_f32 v[162:163], v[178:179], v[102:103], v[162:163] op_sel_hi:[1,0,1]
	v_pk_fma_f32 v[164:165], v[180:181], v[102:103], v[164:165] op_sel_hi:[1,0,1]
	v_pk_fma_f32 v[166:167], v[182:183], v[102:103], v[166:167] op_sel_hi:[1,0,1]
	v_pk_fma_f32 v[168:169], v[184:185], v[102:103], v[168:169] op_sel_hi:[1,0,1]
	ds_read_b128 v[178:181], v192 offset:18432
	ds_read_b128 v[182:185], v192 offset:19456
	s_waitcnt lgkmcnt(8)
	v_pk_fma_f32 v[162:163], v[130:131], v[102:103], v[162:163] op_sel:[0,1,0] op_sel_hi:[1,1,1]
	v_pk_fma_f32 v[164:165], v[132:133], v[102:103], v[164:165] op_sel:[0,1,0] op_sel_hi:[1,1,1]
	v_pk_fma_f32 v[166:167], v[134:135], v[102:103], v[166:167] op_sel:[0,1,0] op_sel_hi:[1,1,1]
	v_pk_fma_f32 v[168:169], v[136:137], v[102:103], v[168:169] op_sel:[0,1,0] op_sel_hi:[1,1,1]
	ds_read_b128 v[130:133], v192 offset:20480
	ds_read_b128 v[134:137], v192 offset:21504
	s_waitcnt lgkmcnt(8)
	v_pk_fma_f32 v[162:163], v[138:139], v[104:105], v[162:163] op_sel_hi:[1,0,1]
	v_pk_fma_f32 v[164:165], v[140:141], v[104:105], v[164:165] op_sel_hi:[1,0,1]
	v_pk_fma_f32 v[166:167], v[142:143], v[104:105], v[166:167] op_sel_hi:[1,0,1]
	v_pk_fma_f32 v[168:169], v[144:145], v[104:105], v[168:169] op_sel_hi:[1,0,1]
	ds_read_b128 v[138:141], v192 offset:22528
	ds_read_b128 v[142:145], v192 offset:23552
	s_waitcnt lgkmcnt(8)
	v_pk_fma_f32 v[162:163], v[146:147], v[104:105], v[162:163] op_sel:[0,1,0] op_sel_hi:[1,1,1]
	v_pk_fma_f32 v[164:165], v[148:149], v[104:105], v[164:165] op_sel:[0,1,0] op_sel_hi:[1,1,1]
	v_pk_fma_f32 v[166:167], v[150:151], v[104:105], v[166:167] op_sel:[0,1,0] op_sel_hi:[1,1,1]
	v_pk_fma_f32 v[168:169], v[152:153], v[104:105], v[168:169] op_sel:[0,1,0] op_sel_hi:[1,1,1]
	ds_read_b128 v[146:149], v192 offset:24576
	ds_read_b128 v[150:153], v192 offset:25600
	s_waitcnt lgkmcnt(8)
	v_pk_fma_f32 v[162:163], v[154:155], v[106:107], v[162:163] op_sel_hi:[1,0,1]
	v_pk_fma_f32 v[164:165], v[156:157], v[106:107], v[164:165] op_sel_hi:[1,0,1]
	v_pk_fma_f32 v[166:167], v[158:159], v[106:107], v[166:167] op_sel_hi:[1,0,1]
	v_pk_fma_f32 v[168:169], v[160:161], v[106:107], v[168:169] op_sel_hi:[1,0,1]
	ds_read_b128 v[154:157], v192 offset:26624
	ds_read_b128 v[158:161], v192 offset:27648
	s_waitcnt lgkmcnt(8)
	v_pk_fma_f32 v[162:163], v[178:179], v[106:107], v[162:163] op_sel:[0,1,0] op_sel_hi:[1,1,1]
	v_pk_fma_f32 v[164:165], v[180:181], v[106:107], v[164:165] op_sel:[0,1,0] op_sel_hi:[1,1,1]
	v_pk_fma_f32 v[166:167], v[182:183], v[106:107], v[166:167] op_sel:[0,1,0] op_sel_hi:[1,1,1]
	v_pk_fma_f32 v[168:169], v[184:185], v[106:107], v[168:169] op_sel:[0,1,0] op_sel_hi:[1,1,1]
	ds_read_b128 v[178:181], v192 offset:28672
	ds_read_b128 v[182:185], v192 offset:29696
	s_waitcnt lgkmcnt(8)
	v_pk_fma_f32 v[162:163], v[130:131], v[108:109], v[162:163] op_sel_hi:[1,0,1]
	v_pk_fma_f32 v[164:165], v[132:133], v[108:109], v[164:165] op_sel_hi:[1,0,1]
	v_pk_fma_f32 v[166:167], v[134:135], v[108:109], v[166:167] op_sel_hi:[1,0,1]
	v_pk_fma_f32 v[168:169], v[136:137], v[108:109], v[168:169] op_sel_hi:[1,0,1]
	ds_read_b128 v[130:133], v192 offset:30720
	ds_read_b128 v[134:137], v192 offset:31744
	s_waitcnt lgkmcnt(8)
	v_pk_fma_f32 v[162:163], v[138:139], v[108:109], v[162:163] op_sel:[0,1,0] op_sel_hi:[1,1,1]
	v_pk_fma_f32 v[164:165], v[140:141], v[108:109], v[164:165] op_sel:[0,1,0] op_sel_hi:[1,1,1]
	v_pk_fma_f32 v[166:167], v[142:143], v[108:109], v[166:167] op_sel:[0,1,0] op_sel_hi:[1,1,1]
	v_pk_fma_f32 v[168:169], v[144:145], v[108:109], v[168:169] op_sel:[0,1,0] op_sel_hi:[1,1,1]
	ds_read_b128 v[138:141], v192 offset:32768
	ds_read_b128 v[142:145], v192 offset:33792
	s_waitcnt lgkmcnt(8)
	v_pk_fma_f32 v[162:163], v[146:147], v[110:111], v[162:163] op_sel_hi:[1,0,1]
	v_pk_fma_f32 v[164:165], v[148:149], v[110:111], v[164:165] op_sel_hi:[1,0,1]
	v_pk_fma_f32 v[166:167], v[150:151], v[110:111], v[166:167] op_sel_hi:[1,0,1]
	v_pk_fma_f32 v[168:169], v[152:153], v[110:111], v[168:169] op_sel_hi:[1,0,1]
	ds_read_b128 v[146:149], v192 offset:34816
	ds_read_b128 v[150:153], v192 offset:35840
	s_waitcnt lgkmcnt(8)
	v_pk_fma_f32 v[162:163], v[154:155], v[110:111], v[162:163] op_sel:[0,1,0] op_sel_hi:[1,1,1]
	v_pk_fma_f32 v[164:165], v[156:157], v[110:111], v[164:165] op_sel:[0,1,0] op_sel_hi:[1,1,1]
	v_pk_fma_f32 v[166:167], v[158:159], v[110:111], v[166:167] op_sel:[0,1,0] op_sel_hi:[1,1,1]
	v_pk_fma_f32 v[168:169], v[160:161], v[110:111], v[168:169] op_sel:[0,1,0] op_sel_hi:[1,1,1]
	ds_read_b128 v[154:157], v192 offset:36864
	ds_read_b128 v[158:161], v192 offset:37888
	s_waitcnt lgkmcnt(8)
	v_pk_fma_f32 v[162:163], v[178:179], v[112:113], v[162:163] op_sel_hi:[1,0,1]
	v_pk_fma_f32 v[164:165], v[180:181], v[112:113], v[164:165] op_sel_hi:[1,0,1]
	v_pk_fma_f32 v[166:167], v[182:183], v[112:113], v[166:167] op_sel_hi:[1,0,1]
	v_pk_fma_f32 v[168:169], v[184:185], v[112:113], v[168:169] op_sel_hi:[1,0,1]
	ds_read_b128 v[178:181], v192 offset:38912
	ds_read_b128 v[182:185], v192 offset:39936
	s_waitcnt lgkmcnt(8)
	v_pk_fma_f32 v[162:163], v[130:131], v[112:113], v[162:163] op_sel:[0,1,0] op_sel_hi:[1,1,1]
	v_pk_fma_f32 v[164:165], v[132:133], v[112:113], v[164:165] op_sel:[0,1,0] op_sel_hi:[1,1,1]
	v_pk_fma_f32 v[166:167], v[134:135], v[112:113], v[166:167] op_sel:[0,1,0] op_sel_hi:[1,1,1]
	v_pk_fma_f32 v[168:169], v[136:137], v[112:113], v[168:169] op_sel:[0,1,0] op_sel_hi:[1,1,1]
	ds_read_b128 v[130:133], v192 offset:40960
	ds_read_b128 v[134:137], v192 offset:41984
	s_waitcnt lgkmcnt(8)
	v_pk_fma_f32 v[162:163], v[138:139], v[114:115], v[162:163] op_sel_hi:[1,0,1]
	v_pk_fma_f32 v[164:165], v[140:141], v[114:115], v[164:165] op_sel_hi:[1,0,1]
	v_pk_fma_f32 v[166:167], v[142:143], v[114:115], v[166:167] op_sel_hi:[1,0,1]
	v_pk_fma_f32 v[168:169], v[144:145], v[114:115], v[168:169] op_sel_hi:[1,0,1]
	ds_read_b128 v[138:141], v192 offset:43008
	ds_read_b128 v[142:145], v192 offset:44032
	s_waitcnt lgkmcnt(8)
	v_pk_fma_f32 v[162:163], v[146:147], v[114:115], v[162:163] op_sel:[0,1,0] op_sel_hi:[1,1,1]
	v_pk_fma_f32 v[164:165], v[148:149], v[114:115], v[164:165] op_sel:[0,1,0] op_sel_hi:[1,1,1]
	v_pk_fma_f32 v[166:167], v[150:151], v[114:115], v[166:167] op_sel:[0,1,0] op_sel_hi:[1,1,1]
	v_pk_fma_f32 v[168:169], v[152:153], v[114:115], v[168:169] op_sel:[0,1,0] op_sel_hi:[1,1,1]
	ds_read_b128 v[146:149], v192 offset:45056
	ds_read_b128 v[150:153], v192 offset:46080
	s_waitcnt lgkmcnt(8)
	v_pk_fma_f32 v[162:163], v[154:155], v[116:117], v[162:163] op_sel_hi:[1,0,1]
	v_pk_fma_f32 v[164:165], v[156:157], v[116:117], v[164:165] op_sel_hi:[1,0,1]
	v_pk_fma_f32 v[166:167], v[158:159], v[116:117], v[166:167] op_sel_hi:[1,0,1]
	v_pk_fma_f32 v[168:169], v[160:161], v[116:117], v[168:169] op_sel_hi:[1,0,1]
	ds_read_b128 v[154:157], v192 offset:47104
	ds_read_b128 v[158:161], v192 offset:48128
	s_waitcnt lgkmcnt(8)
	v_pk_fma_f32 v[162:163], v[178:179], v[116:117], v[162:163] op_sel:[0,1,0] op_sel_hi:[1,1,1]
	v_pk_fma_f32 v[164:165], v[180:181], v[116:117], v[164:165] op_sel:[0,1,0] op_sel_hi:[1,1,1]
	v_pk_fma_f32 v[166:167], v[182:183], v[116:117], v[166:167] op_sel:[0,1,0] op_sel_hi:[1,1,1]
	v_pk_fma_f32 v[168:169], v[184:185], v[116:117], v[168:169] op_sel:[0,1,0] op_sel_hi:[1,1,1]
	ds_read_b128 v[178:181], v192 offset:49152
	ds_read_b128 v[182:185], v192 offset:50176
	s_waitcnt lgkmcnt(8)
	v_pk_fma_f32 v[162:163], v[130:131], v[118:119], v[162:163] op_sel_hi:[1,0,1]
	v_pk_fma_f32 v[164:165], v[132:133], v[118:119], v[164:165] op_sel_hi:[1,0,1]
	v_pk_fma_f32 v[166:167], v[134:135], v[118:119], v[166:167] op_sel_hi:[1,0,1]
	v_pk_fma_f32 v[168:169], v[136:137], v[118:119], v[168:169] op_sel_hi:[1,0,1]
	ds_read_b128 v[130:133], v192 offset:51200
	ds_read_b128 v[134:137], v192 offset:52224
	s_waitcnt lgkmcnt(8)
	v_pk_fma_f32 v[162:163], v[138:139], v[118:119], v[162:163] op_sel:[0,1,0] op_sel_hi:[1,1,1]
	v_pk_fma_f32 v[164:165], v[140:141], v[118:119], v[164:165] op_sel:[0,1,0] op_sel_hi:[1,1,1]
	v_pk_fma_f32 v[166:167], v[142:143], v[118:119], v[166:167] op_sel:[0,1,0] op_sel_hi:[1,1,1]
	v_pk_fma_f32 v[168:169], v[144:145], v[118:119], v[168:169] op_sel:[0,1,0] op_sel_hi:[1,1,1]
	ds_read_b128 v[138:141], v192 offset:53248
	ds_read_b128 v[142:145], v192 offset:54272
	s_waitcnt lgkmcnt(8)
	v_pk_fma_f32 v[162:163], v[146:147], v[120:121], v[162:163] op_sel_hi:[1,0,1]
	v_pk_fma_f32 v[164:165], v[148:149], v[120:121], v[164:165] op_sel_hi:[1,0,1]
	v_pk_fma_f32 v[166:167], v[150:151], v[120:121], v[166:167] op_sel_hi:[1,0,1]
	v_pk_fma_f32 v[168:169], v[152:153], v[120:121], v[168:169] op_sel_hi:[1,0,1]
	ds_read_b128 v[146:149], v192 offset:55296
	ds_read_b128 v[150:153], v192 offset:56320
	s_waitcnt lgkmcnt(8)
	v_pk_fma_f32 v[162:163], v[154:155], v[120:121], v[162:163] op_sel:[0,1,0] op_sel_hi:[1,1,1]
	v_pk_fma_f32 v[164:165], v[156:157], v[120:121], v[164:165] op_sel:[0,1,0] op_sel_hi:[1,1,1]
	v_pk_fma_f32 v[166:167], v[158:159], v[120:121], v[166:167] op_sel:[0,1,0] op_sel_hi:[1,1,1]
	v_pk_fma_f32 v[168:169], v[160:161], v[120:121], v[168:169] op_sel:[0,1,0] op_sel_hi:[1,1,1]
	ds_read_b128 v[154:157], v192 offset:57344
	ds_read_b128 v[158:161], v192 offset:58368
	s_waitcnt lgkmcnt(8)
	v_pk_fma_f32 v[162:163], v[178:179], v[122:123], v[162:163] op_sel_hi:[1,0,1]
	v_pk_fma_f32 v[164:165], v[180:181], v[122:123], v[164:165] op_sel_hi:[1,0,1]
	v_pk_fma_f32 v[166:167], v[182:183], v[122:123], v[166:167] op_sel_hi:[1,0,1]
	v_pk_fma_f32 v[168:169], v[184:185], v[122:123], v[168:169] op_sel_hi:[1,0,1]
	ds_read_b128 v[178:181], v192 offset:59392
	ds_read_b128 v[182:185], v192 offset:60416
	s_waitcnt lgkmcnt(8)
	v_pk_fma_f32 v[162:163], v[130:131], v[122:123], v[162:163] op_sel:[0,1,0] op_sel_hi:[1,1,1]
	v_pk_fma_f32 v[164:165], v[132:133], v[122:123], v[164:165] op_sel:[0,1,0] op_sel_hi:[1,1,1]
	v_pk_fma_f32 v[166:167], v[134:135], v[122:123], v[166:167] op_sel:[0,1,0] op_sel_hi:[1,1,1]
	v_pk_fma_f32 v[168:169], v[136:137], v[122:123], v[168:169] op_sel:[0,1,0] op_sel_hi:[1,1,1]
	ds_read_b128 v[130:133], v192 offset:61440
	ds_read_b128 v[134:137], v192 offset:62464
	s_waitcnt lgkmcnt(8)
	v_pk_fma_f32 v[162:163], v[138:139], v[124:125], v[162:163] op_sel_hi:[1,0,1]
	v_pk_fma_f32 v[164:165], v[140:141], v[124:125], v[164:165] op_sel_hi:[1,0,1]
	v_pk_fma_f32 v[166:167], v[142:143], v[124:125], v[166:167] op_sel_hi:[1,0,1]
	v_pk_fma_f32 v[168:169], v[144:145], v[124:125], v[168:169] op_sel_hi:[1,0,1]
	ds_read_b128 v[138:141], v192 offset:63488
	ds_read_b128 v[142:145], v192 offset:64512
	s_waitcnt lgkmcnt(8)
	v_pk_fma_f32 v[162:163], v[146:147], v[124:125], v[162:163] op_sel:[0,1,0] op_sel_hi:[1,1,1]
	v_pk_fma_f32 v[164:165], v[148:149], v[124:125], v[164:165] op_sel:[0,1,0] op_sel_hi:[1,1,1]
	v_pk_fma_f32 v[166:167], v[150:151], v[124:125], v[166:167] op_sel:[0,1,0] op_sel_hi:[1,1,1]
	v_pk_fma_f32 v[168:169], v[152:153], v[124:125], v[168:169] op_sel:[0,1,0] op_sel_hi:[1,1,1]
	s_waitcnt lgkmcnt(6)
	v_pk_fma_f32 v[162:163], v[154:155], v[126:127], v[162:163] op_sel_hi:[1,0,1]
	v_pk_fma_f32 v[164:165], v[156:157], v[126:127], v[164:165] op_sel_hi:[1,0,1]
	v_pk_fma_f32 v[166:167], v[158:159], v[126:127], v[166:167] op_sel_hi:[1,0,1]
	v_pk_fma_f32 v[168:169], v[160:161], v[126:127], v[168:169] op_sel_hi:[1,0,1]
	s_waitcnt lgkmcnt(4)
	v_pk_fma_f32 v[162:163], v[178:179], v[126:127], v[162:163] op_sel:[0,1,0] op_sel_hi:[1,1,1]
	v_pk_fma_f32 v[164:165], v[180:181], v[126:127], v[164:165] op_sel:[0,1,0] op_sel_hi:[1,1,1]
	v_pk_fma_f32 v[166:167], v[182:183], v[126:127], v[166:167] op_sel:[0,1,0] op_sel_hi:[1,1,1]
	v_pk_fma_f32 v[168:169], v[184:185], v[126:127], v[168:169] op_sel:[0,1,0] op_sel_hi:[1,1,1]
	s_waitcnt lgkmcnt(2)
	v_pk_fma_f32 v[162:163], v[130:131], v[128:129], v[162:163] op_sel_hi:[1,0,1]
	v_pk_fma_f32 v[164:165], v[132:133], v[128:129], v[164:165] op_sel_hi:[1,0,1]
	v_pk_fma_f32 v[166:167], v[134:135], v[128:129], v[166:167] op_sel_hi:[1,0,1]
	v_pk_fma_f32 v[168:169], v[136:137], v[128:129], v[168:169] op_sel_hi:[1,0,1]
	s_waitcnt lgkmcnt(0)
	v_pk_fma_f32 v[162:163], v[138:139], v[128:129], v[162:163] op_sel:[0,1,0] op_sel_hi:[1,1,1]
	v_pk_fma_f32 v[164:165], v[140:141], v[128:129], v[164:165] op_sel:[0,1,0] op_sel_hi:[1,1,1]
	v_pk_fma_f32 v[166:167], v[142:143], v[128:129], v[166:167] op_sel:[0,1,0] op_sel_hi:[1,1,1]
	v_pk_fma_f32 v[168:169], v[144:145], v[128:129], v[168:169] op_sel:[0,1,0] op_sel_hi:[1,1,1]
	s_nop 1
	v_add_f32_dpp v162, v162, v162 quad_perm:[1,0,3,2] row_mask:0xf bank_mask:0xf
	v_add_f32_dpp v163, v163, v163 quad_perm:[1,0,3,2] row_mask:0xf bank_mask:0xf
	v_add_f32_dpp v164, v164, v164 quad_perm:[1,0,3,2] row_mask:0xf bank_mask:0xf
	v_add_f32_dpp v165, v165, v165 quad_perm:[1,0,3,2] row_mask:0xf bank_mask:0xf
	v_add_f32_dpp v166, v166, v166 quad_perm:[1,0,3,2] row_mask:0xf bank_mask:0xf
	v_add_f32_dpp v167, v167, v167 quad_perm:[1,0,3,2] row_mask:0xf bank_mask:0xf
	v_add_f32_dpp v168, v168, v168 quad_perm:[1,0,3,2] row_mask:0xf bank_mask:0xf
	v_add_f32_dpp v169, v169, v169 quad_perm:[1,0,3,2] row_mask:0xf bank_mask:0xf
	v_add_f32_dpp v162, v162, v162 quad_perm:[2,3,0,1] row_mask:0xf bank_mask:0xf
	v_add_f32_dpp v163, v163, v163 quad_perm:[2,3,0,1] row_mask:0xf bank_mask:0xf
	v_add_f32_dpp v164, v164, v164 quad_perm:[2,3,0,1] row_mask:0xf bank_mask:0xf
	v_add_f32_dpp v165, v165, v165 quad_perm:[2,3,0,1] row_mask:0xf bank_mask:0xf
	v_add_f32_dpp v166, v166, v166 quad_perm:[2,3,0,1] row_mask:0xf bank_mask:0xf
	v_add_f32_dpp v167, v167, v167 quad_perm:[2,3,0,1] row_mask:0xf bank_mask:0xf
	v_add_f32_dpp v168, v168, v168 quad_perm:[2,3,0,1] row_mask:0xf bank_mask:0xf
	v_add_f32_dpp v169, v169, v169 quad_perm:[2,3,0,1] row_mask:0xf bank_mask:0xf
	v_add_f32_dpp v162, v162, v162 row_half_mirror row_mask:0xf bank_mask:0xf
	v_add_f32_dpp v163, v163, v163 row_half_mirror row_mask:0xf bank_mask:0xf
	v_add_f32_dpp v164, v164, v164 row_half_mirror row_mask:0xf bank_mask:0xf
	v_add_f32_dpp v165, v165, v165 row_half_mirror row_mask:0xf bank_mask:0xf
	v_add_f32_dpp v166, v166, v166 row_half_mirror row_mask:0xf bank_mask:0xf
	v_add_f32_dpp v167, v167, v167 row_half_mirror row_mask:0xf bank_mask:0xf
	v_add_f32_dpp v168, v168, v168 row_half_mirror row_mask:0xf bank_mask:0xf
	v_add_f32_dpp v169, v169, v169 row_half_mirror row_mask:0xf bank_mask:0xf
	v_add_f32_dpp v162, v162, v162 row_mirror row_mask:0xf bank_mask:0xf
	v_add_f32_dpp v163, v163, v163 row_mirror row_mask:0xf bank_mask:0xf
	v_add_f32_dpp v164, v164, v164 row_mirror row_mask:0xf bank_mask:0xf
	v_add_f32_dpp v165, v165, v165 row_mirror row_mask:0xf bank_mask:0xf
	v_add_f32_dpp v166, v166, v166 row_mirror row_mask:0xf bank_mask:0xf
	v_add_f32_dpp v167, v167, v167 row_mirror row_mask:0xf bank_mask:0xf
	v_add_f32_dpp v168, v168, v168 row_mirror row_mask:0xf bank_mask:0xf
	v_add_f32_dpp v169, v169, v169 row_mirror row_mask:0xf bank_mask:0xf
	v_mov_b32_e32 v170, v162
	v_mov_b32_e32 v171, v163
	v_mov_b32_e32 v172, v164
	v_mov_b32_e32 v173, v165
	v_mov_b32_e32 v174, v166
	v_mov_b32_e32 v175, v167
	v_mov_b32_e32 v176, v168
	v_mov_b32_e32 v177, v169
	v_permlane16_swap_b32 v170, v162
	v_permlane16_swap_b32 v171, v163
	v_permlane16_swap_b32 v172, v164
	v_permlane16_swap_b32 v173, v165
	v_permlane16_swap_b32 v174, v166
	v_permlane16_swap_b32 v175, v167
	v_permlane16_swap_b32 v176, v168
	v_permlane16_swap_b32 v177, v169
	v_add_f32_e32 v162, v162, v170
	v_add_f32_e32 v163, v163, v171
	v_add_f32_e32 v164, v164, v172
	v_add_f32_e32 v165, v165, v173
	v_add_f32_e32 v166, v166, v174
	v_add_f32_e32 v167, v167, v175
	v_add_f32_e32 v168, v168, v176
	v_add_f32_e32 v169, v169, v177
	v_mov_b32_e32 v170, v162
	v_mov_b32_e32 v171, v163
	v_mov_b32_e32 v172, v164
	v_mov_b32_e32 v173, v165
	v_mov_b32_e32 v174, v166
	v_mov_b32_e32 v175, v167
	v_mov_b32_e32 v176, v168
	v_mov_b32_e32 v177, v169
	v_permlane32_swap_b32 v170, v162
	v_permlane32_swap_b32 v171, v163
	v_permlane32_swap_b32 v172, v164
	v_permlane32_swap_b32 v173, v165
	v_permlane32_swap_b32 v174, v166
	v_permlane32_swap_b32 v175, v167
	v_permlane32_swap_b32 v176, v168
	v_permlane32_swap_b32 v177, v169
	v_add_f32_e32 v162, v162, v170
	v_add_f32_e32 v163, v163, v171
	v_add_f32_e32 v164, v164, v172
	v_add_f32_e32 v165, v165, v173
	v_add_f32_e32 v166, v166, v174
	v_add_f32_e32 v167, v167, v175
	v_add_f32_e32 v168, v168, v176
	v_add_f32_e32 v169, v169, v177
	v_readfirstlane_b32 s98, v162
	v_readfirstlane_b32 s99, v163
	v_readfirstlane_b32 s100, v164
	v_readfirstlane_b32 s101, v165
	v_writelane_b32 v230, s98, 40
	v_writelane_b32 v230, s99, 41
	v_writelane_b32 v230, s100, 42
	v_writelane_b32 v230, s101, 43
	v_readfirstlane_b32 s98, v166
	v_readfirstlane_b32 s99, v167
	v_readfirstlane_b32 s100, v168
	v_readfirstlane_b32 s101, v169
	v_writelane_b32 v230, s98, 44
	v_writelane_b32 v230, s99, 45
	v_writelane_b32 v230, s100, 46
	v_writelane_b32 v230, s101, 47
	s_waitcnt vmcnt(16)
	v_pk_mul_f32 v[198:199], v[34:35], v[34:35]
	v_pk_mul_f32 v[200:201], v[36:37], v[36:37]
	v_pk_fma_f32 v[198:199], v[38:39], v[38:39], v[198:199]
	v_pk_fma_f32 v[200:201], v[40:41], v[40:41], v[200:201]
	v_pk_fma_f32 v[198:199], v[42:43], v[42:43], v[198:199]
	v_pk_fma_f32 v[200:201], v[44:45], v[44:45], v[200:201]
	v_pk_fma_f32 v[198:199], v[46:47], v[46:47], v[198:199]
	v_pk_fma_f32 v[200:201], v[48:49], v[48:49], v[200:201]
	v_pk_fma_f32 v[198:199], v[50:51], v[50:51], v[198:199]
	v_pk_fma_f32 v[200:201], v[52:53], v[52:53], v[200:201]
	v_pk_fma_f32 v[198:199], v[54:55], v[54:55], v[198:199]
	v_pk_fma_f32 v[200:201], v[56:57], v[56:57], v[200:201]
	v_pk_fma_f32 v[198:199], v[58:59], v[58:59], v[198:199]
	v_pk_fma_f32 v[200:201], v[60:61], v[60:61], v[200:201]
	v_pk_fma_f32 v[198:199], v[62:63], v[62:63], v[198:199]
	v_pk_fma_f32 v[200:201], v[64:65], v[64:65], v[200:201]
	v_pk_add_f32 v[198:199], v[198:199], v[200:201]
	v_add_f32_e32 v198, v198, v199
	s_nop 1
	v_add_f32_dpp v198, v198, v198 quad_perm:[1,0,3,2] row_mask:0xf bank_mask:0xf
	s_nop 1
	v_add_f32_dpp v198, v198, v198 quad_perm:[2,3,0,1] row_mask:0xf bank_mask:0xf
	s_nop 1
	v_add_f32_dpp v198, v198, v198 row_half_mirror row_mask:0xf bank_mask:0xf
	s_nop 1
	v_add_f32_dpp v198, v198, v198 row_mirror row_mask:0xf bank_mask:0xf
	v_mov_b32_e32 v199, v198
	s_nop 1
	v_permlane16_swap_b32 v199, v198
	v_add_f32_e32 v198, v198, v199
	v_mov_b32_e32 v199, v198
	s_nop 1
	v_permlane32_swap_b32 v199, v198
	v_add_f32_e32 v198, v198, v199
	ds_read_b128 v[130:133], v192
	ds_read_b128 v[134:137], v192 offset:1024
	ds_read_b128 v[138:141], v192 offset:2048
	ds_read_b128 v[142:145], v192 offset:3072
	ds_read_b128 v[146:149], v192 offset:4096
	ds_read_b128 v[150:153], v192 offset:5120
	ds_read_b128 v[154:157], v192 offset:6144
	ds_read_b128 v[158:161], v192 offset:7168
	ds_read_b128 v[178:181], v192 offset:8192
	ds_read_b128 v[182:185], v192 offset:9216
	v_fmamk_f32 v198, v198, 0x3a000000, v241
	v_mul_f32_e32 v199, 0x4b800000, v198
	v_cmp_gt_f32_e32 vcc, s17, v198
	s_nop 1
	v_cndmask_b32_e32 v198, v198, v199, vcc
	v_rsq_f32_e32 v198, v198
	s_nop 0
	v_mul_f32_e32 v199, 0x45800000, v198
	v_cndmask_b32_e32 v202, v198, v199, vcc
	v_pk_mul_f32 v[98:99], v[34:35], v[202:203] op_sel_hi:[1,0]
	v_pk_mul_f32 v[98:99], v[2:3], v[98:99]
	v_pk_mul_f32 v[100:101], v[36:37], v[202:203] op_sel_hi:[1,0]
	v_pk_mul_f32 v[100:101], v[4:5], v[100:101]
	v_cvt_pk_bf16_f32 v206, v98, v99
	v_cvt_pk_bf16_f32 v207, v100, v101
	global_store_dwordx2 v194, v[206:207], s[52:53]
	v_pk_mul_f32 v[102:103], v[38:39], v[202:203] op_sel_hi:[1,0]
	v_pk_mul_f32 v[102:103], v[6:7], v[102:103]
	v_pk_mul_f32 v[104:105], v[40:41], v[202:203] op_sel_hi:[1,0]
	v_pk_mul_f32 v[104:105], v[8:9], v[104:105]
	v_cvt_pk_bf16_f32 v206, v102, v103
	v_cvt_pk_bf16_f32 v207, v104, v105
	global_store_dwordx2 v194, v[206:207], s[52:53] offset:512
	v_pk_mul_f32 v[106:107], v[42:43], v[202:203] op_sel_hi:[1,0]
	v_pk_mul_f32 v[106:107], v[10:11], v[106:107]
	v_pk_mul_f32 v[108:109], v[44:45], v[202:203] op_sel_hi:[1,0]
	v_pk_mul_f32 v[108:109], v[12:13], v[108:109]
	v_cvt_pk_bf16_f32 v206, v106, v107
	v_cvt_pk_bf16_f32 v207, v108, v109
	global_store_dwordx2 v194, v[206:207], s[52:53] offset:1024
	v_pk_mul_f32 v[110:111], v[46:47], v[202:203] op_sel_hi:[1,0]
	v_pk_mul_f32 v[110:111], v[14:15], v[110:111]
	v_pk_mul_f32 v[112:113], v[48:49], v[202:203] op_sel_hi:[1,0]
	v_pk_mul_f32 v[112:113], v[16:17], v[112:113]
	v_cvt_pk_bf16_f32 v206, v110, v111
	v_cvt_pk_bf16_f32 v207, v112, v113
	global_store_dwordx2 v194, v[206:207], s[52:53] offset:1536
	v_pk_mul_f32 v[114:115], v[50:51], v[202:203] op_sel_hi:[1,0]
	v_pk_mul_f32 v[114:115], v[18:19], v[114:115]
	v_pk_mul_f32 v[116:117], v[52:53], v[202:203] op_sel_hi:[1,0]
	v_pk_mul_f32 v[116:117], v[20:21], v[116:117]
	v_cvt_pk_bf16_f32 v206, v114, v115
	v_cvt_pk_bf16_f32 v207, v116, v117
	global_store_dwordx2 v194, v[206:207], s[52:53] offset:2048
	v_pk_mul_f32 v[118:119], v[54:55], v[202:203] op_sel_hi:[1,0]
	v_pk_mul_f32 v[118:119], v[22:23], v[118:119]
	v_pk_mul_f32 v[120:121], v[56:57], v[202:203] op_sel_hi:[1,0]
	v_pk_mul_f32 v[120:121], v[24:25], v[120:121]
	v_cvt_pk_bf16_f32 v206, v118, v119
	v_cvt_pk_bf16_f32 v207, v120, v121
	global_store_dwordx2 v194, v[206:207], s[52:53] offset:2560
	v_pk_mul_f32 v[122:123], v[58:59], v[202:203] op_sel_hi:[1,0]
	v_pk_mul_f32 v[122:123], v[26:27], v[122:123]
	v_pk_mul_f32 v[124:125], v[60:61], v[202:203] op_sel_hi:[1,0]
	v_pk_mul_f32 v[124:125], v[28:29], v[124:125]
	v_cvt_pk_bf16_f32 v206, v122, v123
	v_cvt_pk_bf16_f32 v207, v124, v125
	global_store_dwordx2 v194, v[206:207], s[52:53] offset:3072
	v_pk_mul_f32 v[126:127], v[62:63], v[202:203] op_sel_hi:[1,0]
	v_pk_mul_f32 v[126:127], v[30:31], v[126:127]
	v_pk_mul_f32 v[128:129], v[64:65], v[202:203] op_sel_hi:[1,0]
	v_pk_mul_f32 v[128:129], v[32:33], v[128:129]
	v_cvt_pk_bf16_f32 v206, v126, v127
	v_cvt_pk_bf16_f32 v207, v128, v129
	global_store_dwordx2 v194, v[206:207], s[52:53] offset:3584
	v_add_u32_e32 v194, 0x800000, v194
	s_waitcnt lgkmcnt(8)
	v_pk_mul_f32 v[162:163], v[130:131], v[98:99] op_sel_hi:[1,0]
	v_pk_mul_f32 v[164:165], v[132:133], v[98:99] op_sel_hi:[1,0]
	v_pk_mul_f32 v[166:167], v[134:135], v[98:99] op_sel_hi:[1,0]
	v_pk_mul_f32 v[168:169], v[136:137], v[98:99] op_sel_hi:[1,0]
	ds_read_b128 v[130:133], v192 offset:10240
	ds_read_b128 v[134:137], v192 offset:11264
	s_waitcnt lgkmcnt(8)
	v_pk_fma_f32 v[162:163], v[138:139], v[98:99], v[162:163] op_sel:[0,1,0] op_sel_hi:[1,1,1]
	v_pk_fma_f32 v[164:165], v[140:141], v[98:99], v[164:165] op_sel:[0,1,0] op_sel_hi:[1,1,1]
	v_pk_fma_f32 v[166:167], v[142:143], v[98:99], v[166:167] op_sel:[0,1,0] op_sel_hi:[1,1,1]
	v_pk_fma_f32 v[168:169], v[144:145], v[98:99], v[168:169] op_sel:[0,1,0] op_sel_hi:[1,1,1]
	ds_read_b128 v[138:141], v192 offset:12288
	ds_read_b128 v[142:145], v192 offset:13312
	s_waitcnt lgkmcnt(8)
	v_pk_fma_f32 v[162:163], v[146:147], v[100:101], v[162:163] op_sel_hi:[1,0,1]
	v_pk_fma_f32 v[164:165], v[148:149], v[100:101], v[164:165] op_sel_hi:[1,0,1]
	v_pk_fma_f32 v[166:167], v[150:151], v[100:101], v[166:167] op_sel_hi:[1,0,1]
	v_pk_fma_f32 v[168:169], v[152:153], v[100:101], v[168:169] op_sel_hi:[1,0,1]
	ds_read_b128 v[146:149], v192 offset:14336
	ds_read_b128 v[150:153], v192 offset:15360
	s_waitcnt lgkmcnt(8)
	v_pk_fma_f32 v[162:163], v[154:155], v[100:101], v[162:163] op_sel:[0,1,0] op_sel_hi:[1,1,1]
	v_pk_fma_f32 v[164:165], v[156:157], v[100:101], v[164:165] op_sel:[0,1,0] op_sel_hi:[1,1,1]
	v_pk_fma_f32 v[166:167], v[158:159], v[100:101], v[166:167] op_sel:[0,1,0] op_sel_hi:[1,1,1]
	v_pk_fma_f32 v[168:169], v[160:161], v[100:101], v[168:169] op_sel:[0,1,0] op_sel_hi:[1,1,1]
	ds_read_b128 v[154:157], v192 offset:16384
	ds_read_b128 v[158:161], v192 offset:17408
	s_waitcnt lgkmcnt(8)
	v_pk_fma_f32 v[162:163], v[178:179], v[102:103], v[162:163] op_sel_hi:[1,0,1]
	v_pk_fma_f32 v[164:165], v[180:181], v[102:103], v[164:165] op_sel_hi:[1,0,1]
	v_pk_fma_f32 v[166:167], v[182:183], v[102:103], v[166:167] op_sel_hi:[1,0,1]
	v_pk_fma_f32 v[168:169], v[184:185], v[102:103], v[168:169] op_sel_hi:[1,0,1]
	ds_read_b128 v[178:181], v192 offset:18432
	ds_read_b128 v[182:185], v192 offset:19456
	s_waitcnt lgkmcnt(8)
	v_pk_fma_f32 v[162:163], v[130:131], v[102:103], v[162:163] op_sel:[0,1,0] op_sel_hi:[1,1,1]
	v_pk_fma_f32 v[164:165], v[132:133], v[102:103], v[164:165] op_sel:[0,1,0] op_sel_hi:[1,1,1]
	v_pk_fma_f32 v[166:167], v[134:135], v[102:103], v[166:167] op_sel:[0,1,0] op_sel_hi:[1,1,1]
	v_pk_fma_f32 v[168:169], v[136:137], v[102:103], v[168:169] op_sel:[0,1,0] op_sel_hi:[1,1,1]
	ds_read_b128 v[130:133], v192 offset:20480
	ds_read_b128 v[134:137], v192 offset:21504
	s_waitcnt lgkmcnt(8)
	v_pk_fma_f32 v[162:163], v[138:139], v[104:105], v[162:163] op_sel_hi:[1,0,1]
	v_pk_fma_f32 v[164:165], v[140:141], v[104:105], v[164:165] op_sel_hi:[1,0,1]
	v_pk_fma_f32 v[166:167], v[142:143], v[104:105], v[166:167] op_sel_hi:[1,0,1]
	v_pk_fma_f32 v[168:169], v[144:145], v[104:105], v[168:169] op_sel_hi:[1,0,1]
	ds_read_b128 v[138:141], v192 offset:22528
	ds_read_b128 v[142:145], v192 offset:23552
	s_waitcnt lgkmcnt(8)
	v_pk_fma_f32 v[162:163], v[146:147], v[104:105], v[162:163] op_sel:[0,1,0] op_sel_hi:[1,1,1]
	v_pk_fma_f32 v[164:165], v[148:149], v[104:105], v[164:165] op_sel:[0,1,0] op_sel_hi:[1,1,1]
	v_pk_fma_f32 v[166:167], v[150:151], v[104:105], v[166:167] op_sel:[0,1,0] op_sel_hi:[1,1,1]
	v_pk_fma_f32 v[168:169], v[152:153], v[104:105], v[168:169] op_sel:[0,1,0] op_sel_hi:[1,1,1]
	ds_read_b128 v[146:149], v192 offset:24576
	ds_read_b128 v[150:153], v192 offset:25600
	s_waitcnt lgkmcnt(8)
	v_pk_fma_f32 v[162:163], v[154:155], v[106:107], v[162:163] op_sel_hi:[1,0,1]
	v_pk_fma_f32 v[164:165], v[156:157], v[106:107], v[164:165] op_sel_hi:[1,0,1]
	v_pk_fma_f32 v[166:167], v[158:159], v[106:107], v[166:167] op_sel_hi:[1,0,1]
	v_pk_fma_f32 v[168:169], v[160:161], v[106:107], v[168:169] op_sel_hi:[1,0,1]
	ds_read_b128 v[154:157], v192 offset:26624
	ds_read_b128 v[158:161], v192 offset:27648
	s_waitcnt lgkmcnt(8)
	v_pk_fma_f32 v[162:163], v[178:179], v[106:107], v[162:163] op_sel:[0,1,0] op_sel_hi:[1,1,1]
	v_pk_fma_f32 v[164:165], v[180:181], v[106:107], v[164:165] op_sel:[0,1,0] op_sel_hi:[1,1,1]
	v_pk_fma_f32 v[166:167], v[182:183], v[106:107], v[166:167] op_sel:[0,1,0] op_sel_hi:[1,1,1]
	v_pk_fma_f32 v[168:169], v[184:185], v[106:107], v[168:169] op_sel:[0,1,0] op_sel_hi:[1,1,1]
	ds_read_b128 v[178:181], v192 offset:28672
	ds_read_b128 v[182:185], v192 offset:29696
	s_waitcnt lgkmcnt(8)
	v_pk_fma_f32 v[162:163], v[130:131], v[108:109], v[162:163] op_sel_hi:[1,0,1]
	v_pk_fma_f32 v[164:165], v[132:133], v[108:109], v[164:165] op_sel_hi:[1,0,1]
	v_pk_fma_f32 v[166:167], v[134:135], v[108:109], v[166:167] op_sel_hi:[1,0,1]
	v_pk_fma_f32 v[168:169], v[136:137], v[108:109], v[168:169] op_sel_hi:[1,0,1]
	ds_read_b128 v[130:133], v192 offset:30720
	ds_read_b128 v[134:137], v192 offset:31744
	s_waitcnt lgkmcnt(8)
	v_pk_fma_f32 v[162:163], v[138:139], v[108:109], v[162:163] op_sel:[0,1,0] op_sel_hi:[1,1,1]
	v_pk_fma_f32 v[164:165], v[140:141], v[108:109], v[164:165] op_sel:[0,1,0] op_sel_hi:[1,1,1]
	v_pk_fma_f32 v[166:167], v[142:143], v[108:109], v[166:167] op_sel:[0,1,0] op_sel_hi:[1,1,1]
	v_pk_fma_f32 v[168:169], v[144:145], v[108:109], v[168:169] op_sel:[0,1,0] op_sel_hi:[1,1,1]
	ds_read_b128 v[138:141], v192 offset:32768
	ds_read_b128 v[142:145], v192 offset:33792
	s_waitcnt lgkmcnt(8)
	v_pk_fma_f32 v[162:163], v[146:147], v[110:111], v[162:163] op_sel_hi:[1,0,1]
	v_pk_fma_f32 v[164:165], v[148:149], v[110:111], v[164:165] op_sel_hi:[1,0,1]
	v_pk_fma_f32 v[166:167], v[150:151], v[110:111], v[166:167] op_sel_hi:[1,0,1]
	v_pk_fma_f32 v[168:169], v[152:153], v[110:111], v[168:169] op_sel_hi:[1,0,1]
	ds_read_b128 v[146:149], v192 offset:34816
	ds_read_b128 v[150:153], v192 offset:35840
	s_waitcnt lgkmcnt(8)
	v_pk_fma_f32 v[162:163], v[154:155], v[110:111], v[162:163] op_sel:[0,1,0] op_sel_hi:[1,1,1]
	v_pk_fma_f32 v[164:165], v[156:157], v[110:111], v[164:165] op_sel:[0,1,0] op_sel_hi:[1,1,1]
	v_pk_fma_f32 v[166:167], v[158:159], v[110:111], v[166:167] op_sel:[0,1,0] op_sel_hi:[1,1,1]
	v_pk_fma_f32 v[168:169], v[160:161], v[110:111], v[168:169] op_sel:[0,1,0] op_sel_hi:[1,1,1]
	ds_read_b128 v[154:157], v192 offset:36864
	ds_read_b128 v[158:161], v192 offset:37888
	s_waitcnt lgkmcnt(8)
	v_pk_fma_f32 v[162:163], v[178:179], v[112:113], v[162:163] op_sel_hi:[1,0,1]
	v_pk_fma_f32 v[164:165], v[180:181], v[112:113], v[164:165] op_sel_hi:[1,0,1]
	v_pk_fma_f32 v[166:167], v[182:183], v[112:113], v[166:167] op_sel_hi:[1,0,1]
	v_pk_fma_f32 v[168:169], v[184:185], v[112:113], v[168:169] op_sel_hi:[1,0,1]
	ds_read_b128 v[178:181], v192 offset:38912
	ds_read_b128 v[182:185], v192 offset:39936
	s_waitcnt lgkmcnt(8)
	v_pk_fma_f32 v[162:163], v[130:131], v[112:113], v[162:163] op_sel:[0,1,0] op_sel_hi:[1,1,1]
	v_pk_fma_f32 v[164:165], v[132:133], v[112:113], v[164:165] op_sel:[0,1,0] op_sel_hi:[1,1,1]
	v_pk_fma_f32 v[166:167], v[134:135], v[112:113], v[166:167] op_sel:[0,1,0] op_sel_hi:[1,1,1]
	v_pk_fma_f32 v[168:169], v[136:137], v[112:113], v[168:169] op_sel:[0,1,0] op_sel_hi:[1,1,1]
	ds_read_b128 v[130:133], v192 offset:40960
	ds_read_b128 v[134:137], v192 offset:41984
	s_waitcnt lgkmcnt(8)
	v_pk_fma_f32 v[162:163], v[138:139], v[114:115], v[162:163] op_sel_hi:[1,0,1]
	v_pk_fma_f32 v[164:165], v[140:141], v[114:115], v[164:165] op_sel_hi:[1,0,1]
	v_pk_fma_f32 v[166:167], v[142:143], v[114:115], v[166:167] op_sel_hi:[1,0,1]
	v_pk_fma_f32 v[168:169], v[144:145], v[114:115], v[168:169] op_sel_hi:[1,0,1]
	ds_read_b128 v[138:141], v192 offset:43008
	ds_read_b128 v[142:145], v192 offset:44032
	s_waitcnt lgkmcnt(8)
	v_pk_fma_f32 v[162:163], v[146:147], v[114:115], v[162:163] op_sel:[0,1,0] op_sel_hi:[1,1,1]
	v_pk_fma_f32 v[164:165], v[148:149], v[114:115], v[164:165] op_sel:[0,1,0] op_sel_hi:[1,1,1]
	v_pk_fma_f32 v[166:167], v[150:151], v[114:115], v[166:167] op_sel:[0,1,0] op_sel_hi:[1,1,1]
	v_pk_fma_f32 v[168:169], v[152:153], v[114:115], v[168:169] op_sel:[0,1,0] op_sel_hi:[1,1,1]
	ds_read_b128 v[146:149], v192 offset:45056
	ds_read_b128 v[150:153], v192 offset:46080
	s_waitcnt lgkmcnt(8)
	v_pk_fma_f32 v[162:163], v[154:155], v[116:117], v[162:163] op_sel_hi:[1,0,1]
	v_pk_fma_f32 v[164:165], v[156:157], v[116:117], v[164:165] op_sel_hi:[1,0,1]
	v_pk_fma_f32 v[166:167], v[158:159], v[116:117], v[166:167] op_sel_hi:[1,0,1]
	v_pk_fma_f32 v[168:169], v[160:161], v[116:117], v[168:169] op_sel_hi:[1,0,1]
	ds_read_b128 v[154:157], v192 offset:47104
	ds_read_b128 v[158:161], v192 offset:48128
	s_waitcnt lgkmcnt(8)
	v_pk_fma_f32 v[162:163], v[178:179], v[116:117], v[162:163] op_sel:[0,1,0] op_sel_hi:[1,1,1]
	v_pk_fma_f32 v[164:165], v[180:181], v[116:117], v[164:165] op_sel:[0,1,0] op_sel_hi:[1,1,1]
	v_pk_fma_f32 v[166:167], v[182:183], v[116:117], v[166:167] op_sel:[0,1,0] op_sel_hi:[1,1,1]
	v_pk_fma_f32 v[168:169], v[184:185], v[116:117], v[168:169] op_sel:[0,1,0] op_sel_hi:[1,1,1]
	ds_read_b128 v[178:181], v192 offset:49152
	ds_read_b128 v[182:185], v192 offset:50176
	s_waitcnt lgkmcnt(8)
	v_pk_fma_f32 v[162:163], v[130:131], v[118:119], v[162:163] op_sel_hi:[1,0,1]
	v_pk_fma_f32 v[164:165], v[132:133], v[118:119], v[164:165] op_sel_hi:[1,0,1]
	v_pk_fma_f32 v[166:167], v[134:135], v[118:119], v[166:167] op_sel_hi:[1,0,1]
	v_pk_fma_f32 v[168:169], v[136:137], v[118:119], v[168:169] op_sel_hi:[1,0,1]
	ds_read_b128 v[130:133], v192 offset:51200
	ds_read_b128 v[134:137], v192 offset:52224
	s_waitcnt lgkmcnt(8)
	v_pk_fma_f32 v[162:163], v[138:139], v[118:119], v[162:163] op_sel:[0,1,0] op_sel_hi:[1,1,1]
	v_pk_fma_f32 v[164:165], v[140:141], v[118:119], v[164:165] op_sel:[0,1,0] op_sel_hi:[1,1,1]
	v_pk_fma_f32 v[166:167], v[142:143], v[118:119], v[166:167] op_sel:[0,1,0] op_sel_hi:[1,1,1]
	v_pk_fma_f32 v[168:169], v[144:145], v[118:119], v[168:169] op_sel:[0,1,0] op_sel_hi:[1,1,1]
	ds_read_b128 v[138:141], v192 offset:53248
	ds_read_b128 v[142:145], v192 offset:54272
	s_waitcnt lgkmcnt(8)
	v_pk_fma_f32 v[162:163], v[146:147], v[120:121], v[162:163] op_sel_hi:[1,0,1]
	v_pk_fma_f32 v[164:165], v[148:149], v[120:121], v[164:165] op_sel_hi:[1,0,1]
	v_pk_fma_f32 v[166:167], v[150:151], v[120:121], v[166:167] op_sel_hi:[1,0,1]
	v_pk_fma_f32 v[168:169], v[152:153], v[120:121], v[168:169] op_sel_hi:[1,0,1]
	ds_read_b128 v[146:149], v192 offset:55296
	ds_read_b128 v[150:153], v192 offset:56320
	s_waitcnt lgkmcnt(8)
	v_pk_fma_f32 v[162:163], v[154:155], v[120:121], v[162:163] op_sel:[0,1,0] op_sel_hi:[1,1,1]
	v_pk_fma_f32 v[164:165], v[156:157], v[120:121], v[164:165] op_sel:[0,1,0] op_sel_hi:[1,1,1]
	v_pk_fma_f32 v[166:167], v[158:159], v[120:121], v[166:167] op_sel:[0,1,0] op_sel_hi:[1,1,1]
	v_pk_fma_f32 v[168:169], v[160:161], v[120:121], v[168:169] op_sel:[0,1,0] op_sel_hi:[1,1,1]
	ds_read_b128 v[154:157], v192 offset:57344
	ds_read_b128 v[158:161], v192 offset:58368
	s_waitcnt lgkmcnt(8)
	v_pk_fma_f32 v[162:163], v[178:179], v[122:123], v[162:163] op_sel_hi:[1,0,1]
	v_pk_fma_f32 v[164:165], v[180:181], v[122:123], v[164:165] op_sel_hi:[1,0,1]
	v_pk_fma_f32 v[166:167], v[182:183], v[122:123], v[166:167] op_sel_hi:[1,0,1]
	v_pk_fma_f32 v[168:169], v[184:185], v[122:123], v[168:169] op_sel_hi:[1,0,1]
	ds_read_b128 v[178:181], v192 offset:59392
	ds_read_b128 v[182:185], v192 offset:60416
	s_waitcnt lgkmcnt(8)
	v_pk_fma_f32 v[162:163], v[130:131], v[122:123], v[162:163] op_sel:[0,1,0] op_sel_hi:[1,1,1]
	v_pk_fma_f32 v[164:165], v[132:133], v[122:123], v[164:165] op_sel:[0,1,0] op_sel_hi:[1,1,1]
	v_pk_fma_f32 v[166:167], v[134:135], v[122:123], v[166:167] op_sel:[0,1,0] op_sel_hi:[1,1,1]
	v_pk_fma_f32 v[168:169], v[136:137], v[122:123], v[168:169] op_sel:[0,1,0] op_sel_hi:[1,1,1]
	ds_read_b128 v[130:133], v192 offset:61440
	ds_read_b128 v[134:137], v192 offset:62464
	s_waitcnt lgkmcnt(8)
	v_pk_fma_f32 v[162:163], v[138:139], v[124:125], v[162:163] op_sel_hi:[1,0,1]
	v_pk_fma_f32 v[164:165], v[140:141], v[124:125], v[164:165] op_sel_hi:[1,0,1]
	v_pk_fma_f32 v[166:167], v[142:143], v[124:125], v[166:167] op_sel_hi:[1,0,1]
	v_pk_fma_f32 v[168:169], v[144:145], v[124:125], v[168:169] op_sel_hi:[1,0,1]
	ds_read_b128 v[138:141], v192 offset:63488
	ds_read_b128 v[142:145], v192 offset:64512
	s_waitcnt lgkmcnt(8)
	v_pk_fma_f32 v[162:163], v[146:147], v[124:125], v[162:163] op_sel:[0,1,0] op_sel_hi:[1,1,1]
	v_pk_fma_f32 v[164:165], v[148:149], v[124:125], v[164:165] op_sel:[0,1,0] op_sel_hi:[1,1,1]
	v_pk_fma_f32 v[166:167], v[150:151], v[124:125], v[166:167] op_sel:[0,1,0] op_sel_hi:[1,1,1]
	v_pk_fma_f32 v[168:169], v[152:153], v[124:125], v[168:169] op_sel:[0,1,0] op_sel_hi:[1,1,1]
	s_waitcnt lgkmcnt(6)
	v_pk_fma_f32 v[162:163], v[154:155], v[126:127], v[162:163] op_sel_hi:[1,0,1]
	v_pk_fma_f32 v[164:165], v[156:157], v[126:127], v[164:165] op_sel_hi:[1,0,1]
	v_pk_fma_f32 v[166:167], v[158:159], v[126:127], v[166:167] op_sel_hi:[1,0,1]
	v_pk_fma_f32 v[168:169], v[160:161], v[126:127], v[168:169] op_sel_hi:[1,0,1]
	s_waitcnt lgkmcnt(4)
	v_pk_fma_f32 v[162:163], v[178:179], v[126:127], v[162:163] op_sel:[0,1,0] op_sel_hi:[1,1,1]
	v_pk_fma_f32 v[164:165], v[180:181], v[126:127], v[164:165] op_sel:[0,1,0] op_sel_hi:[1,1,1]
	v_pk_fma_f32 v[166:167], v[182:183], v[126:127], v[166:167] op_sel:[0,1,0] op_sel_hi:[1,1,1]
	v_pk_fma_f32 v[168:169], v[184:185], v[126:127], v[168:169] op_sel:[0,1,0] op_sel_hi:[1,1,1]
	s_waitcnt lgkmcnt(2)
	v_pk_fma_f32 v[162:163], v[130:131], v[128:129], v[162:163] op_sel_hi:[1,0,1]
	v_pk_fma_f32 v[164:165], v[132:133], v[128:129], v[164:165] op_sel_hi:[1,0,1]
	v_pk_fma_f32 v[166:167], v[134:135], v[128:129], v[166:167] op_sel_hi:[1,0,1]
	v_pk_fma_f32 v[168:169], v[136:137], v[128:129], v[168:169] op_sel_hi:[1,0,1]
	s_waitcnt lgkmcnt(0)
	v_pk_fma_f32 v[162:163], v[138:139], v[128:129], v[162:163] op_sel:[0,1,0] op_sel_hi:[1,1,1]
	v_pk_fma_f32 v[164:165], v[140:141], v[128:129], v[164:165] op_sel:[0,1,0] op_sel_hi:[1,1,1]
	v_pk_fma_f32 v[166:167], v[142:143], v[128:129], v[166:167] op_sel:[0,1,0] op_sel_hi:[1,1,1]
	v_pk_fma_f32 v[168:169], v[144:145], v[128:129], v[168:169] op_sel:[0,1,0] op_sel_hi:[1,1,1]
	s_nop 1
	v_add_f32_dpp v162, v162, v162 quad_perm:[1,0,3,2] row_mask:0xf bank_mask:0xf
	v_add_f32_dpp v163, v163, v163 quad_perm:[1,0,3,2] row_mask:0xf bank_mask:0xf
	v_add_f32_dpp v164, v164, v164 quad_perm:[1,0,3,2] row_mask:0xf bank_mask:0xf
	v_add_f32_dpp v165, v165, v165 quad_perm:[1,0,3,2] row_mask:0xf bank_mask:0xf
	v_add_f32_dpp v166, v166, v166 quad_perm:[1,0,3,2] row_mask:0xf bank_mask:0xf
	v_add_f32_dpp v167, v167, v167 quad_perm:[1,0,3,2] row_mask:0xf bank_mask:0xf
	v_add_f32_dpp v168, v168, v168 quad_perm:[1,0,3,2] row_mask:0xf bank_mask:0xf
	v_add_f32_dpp v169, v169, v169 quad_perm:[1,0,3,2] row_mask:0xf bank_mask:0xf
	v_add_f32_dpp v162, v162, v162 quad_perm:[2,3,0,1] row_mask:0xf bank_mask:0xf
	v_add_f32_dpp v163, v163, v163 quad_perm:[2,3,0,1] row_mask:0xf bank_mask:0xf
	v_add_f32_dpp v164, v164, v164 quad_perm:[2,3,0,1] row_mask:0xf bank_mask:0xf
	v_add_f32_dpp v165, v165, v165 quad_perm:[2,3,0,1] row_mask:0xf bank_mask:0xf
	v_add_f32_dpp v166, v166, v166 quad_perm:[2,3,0,1] row_mask:0xf bank_mask:0xf
	v_add_f32_dpp v167, v167, v167 quad_perm:[2,3,0,1] row_mask:0xf bank_mask:0xf
	v_add_f32_dpp v168, v168, v168 quad_perm:[2,3,0,1] row_mask:0xf bank_mask:0xf
	v_add_f32_dpp v169, v169, v169 quad_perm:[2,3,0,1] row_mask:0xf bank_mask:0xf
	v_add_f32_dpp v162, v162, v162 row_half_mirror row_mask:0xf bank_mask:0xf
	v_add_f32_dpp v163, v163, v163 row_half_mirror row_mask:0xf bank_mask:0xf
	v_add_f32_dpp v164, v164, v164 row_half_mirror row_mask:0xf bank_mask:0xf
	v_add_f32_dpp v165, v165, v165 row_half_mirror row_mask:0xf bank_mask:0xf
	v_add_f32_dpp v166, v166, v166 row_half_mirror row_mask:0xf bank_mask:0xf
	v_add_f32_dpp v167, v167, v167 row_half_mirror row_mask:0xf bank_mask:0xf
	v_add_f32_dpp v168, v168, v168 row_half_mirror row_mask:0xf bank_mask:0xf
	v_add_f32_dpp v169, v169, v169 row_half_mirror row_mask:0xf bank_mask:0xf
	v_add_f32_dpp v162, v162, v162 row_mirror row_mask:0xf bank_mask:0xf
	v_add_f32_dpp v163, v163, v163 row_mirror row_mask:0xf bank_mask:0xf
	v_add_f32_dpp v164, v164, v164 row_mirror row_mask:0xf bank_mask:0xf
	v_add_f32_dpp v165, v165, v165 row_mirror row_mask:0xf bank_mask:0xf
	v_add_f32_dpp v166, v166, v166 row_mirror row_mask:0xf bank_mask:0xf
	v_add_f32_dpp v167, v167, v167 row_mirror row_mask:0xf bank_mask:0xf
	v_add_f32_dpp v168, v168, v168 row_mirror row_mask:0xf bank_mask:0xf
	v_add_f32_dpp v169, v169, v169 row_mirror row_mask:0xf bank_mask:0xf
	v_mov_b32_e32 v170, v162
	v_mov_b32_e32 v171, v163
	v_mov_b32_e32 v172, v164
	v_mov_b32_e32 v173, v165
	v_mov_b32_e32 v174, v166
	v_mov_b32_e32 v175, v167
	v_mov_b32_e32 v176, v168
	v_mov_b32_e32 v177, v169
	v_permlane16_swap_b32 v170, v162
	v_permlane16_swap_b32 v171, v163
	v_permlane16_swap_b32 v172, v164
	v_permlane16_swap_b32 v173, v165
	v_permlane16_swap_b32 v174, v166
	v_permlane16_swap_b32 v175, v167
	v_permlane16_swap_b32 v176, v168
	v_permlane16_swap_b32 v177, v169
	v_add_f32_e32 v162, v162, v170
	v_add_f32_e32 v163, v163, v171
	v_add_f32_e32 v164, v164, v172
	v_add_f32_e32 v165, v165, v173
	v_add_f32_e32 v166, v166, v174
	v_add_f32_e32 v167, v167, v175
	v_add_f32_e32 v168, v168, v176
	v_add_f32_e32 v169, v169, v177
	v_mov_b32_e32 v170, v162
	v_mov_b32_e32 v171, v163
	v_mov_b32_e32 v172, v164
	v_mov_b32_e32 v173, v165
	v_mov_b32_e32 v174, v166
	v_mov_b32_e32 v175, v167
	v_mov_b32_e32 v176, v168
	v_mov_b32_e32 v177, v169
	v_permlane32_swap_b32 v170, v162
	v_permlane32_swap_b32 v171, v163
	v_permlane32_swap_b32 v172, v164
	v_permlane32_swap_b32 v173, v165
	v_permlane32_swap_b32 v174, v166
	v_permlane32_swap_b32 v175, v167
	v_permlane32_swap_b32 v176, v168
	v_permlane32_swap_b32 v177, v169
	v_add_f32_e32 v162, v162, v170
	v_add_f32_e32 v163, v163, v171
	v_add_f32_e32 v164, v164, v172
	v_add_f32_e32 v165, v165, v173
	v_add_f32_e32 v166, v166, v174
	v_add_f32_e32 v167, v167, v175
	v_add_f32_e32 v168, v168, v176
	v_add_f32_e32 v169, v169, v177
	v_readfirstlane_b32 s98, v162
	v_readfirstlane_b32 s99, v163
	v_readfirstlane_b32 s100, v164
	v_readfirstlane_b32 s101, v165
	v_writelane_b32 v230, s98, 48
	v_writelane_b32 v230, s99, 49
	v_writelane_b32 v230, s100, 50
	v_writelane_b32 v230, s101, 51
	v_readfirstlane_b32 s98, v166
	v_readfirstlane_b32 s99, v167
	v_readfirstlane_b32 s100, v168
	v_readfirstlane_b32 s101, v169
	v_writelane_b32 v230, s98, 52
	v_writelane_b32 v230, s99, 53
	v_writelane_b32 v230, s100, 54
	v_writelane_b32 v230, s101, 55
	s_waitcnt vmcnt(8)
	v_pk_mul_f32 v[198:199], v[66:67], v[66:67]
	v_pk_mul_f32 v[200:201], v[68:69], v[68:69]
	v_pk_fma_f32 v[198:199], v[70:71], v[70:71], v[198:199]
	v_pk_fma_f32 v[200:201], v[72:73], v[72:73], v[200:201]
	v_pk_fma_f32 v[198:199], v[74:75], v[74:75], v[198:199]
	v_pk_fma_f32 v[200:201], v[76:77], v[76:77], v[200:201]
	v_pk_fma_f32 v[198:199], v[78:79], v[78:79], v[198:199]
	v_pk_fma_f32 v[200:201], v[80:81], v[80:81], v[200:201]
	v_pk_fma_f32 v[198:199], v[82:83], v[82:83], v[198:199]
	v_pk_fma_f32 v[200:201], v[84:85], v[84:85], v[200:201]
	v_pk_fma_f32 v[198:199], v[86:87], v[86:87], v[198:199]
	v_pk_fma_f32 v[200:201], v[88:89], v[88:89], v[200:201]
	v_pk_fma_f32 v[198:199], v[90:91], v[90:91], v[198:199]
	v_pk_fma_f32 v[200:201], v[92:93], v[92:93], v[200:201]
	v_pk_fma_f32 v[198:199], v[94:95], v[94:95], v[198:199]
	v_pk_fma_f32 v[200:201], v[96:97], v[96:97], v[200:201]
	v_pk_add_f32 v[198:199], v[198:199], v[200:201]
	v_add_f32_e32 v198, v198, v199
	s_nop 1
	v_add_f32_dpp v198, v198, v198 quad_perm:[1,0,3,2] row_mask:0xf bank_mask:0xf
	s_nop 1
	v_add_f32_dpp v198, v198, v198 quad_perm:[2,3,0,1] row_mask:0xf bank_mask:0xf
	s_nop 1
	v_add_f32_dpp v198, v198, v198 row_half_mirror row_mask:0xf bank_mask:0xf
	s_nop 1
	v_add_f32_dpp v198, v198, v198 row_mirror row_mask:0xf bank_mask:0xf
	v_mov_b32_e32 v199, v198
	s_nop 1
	v_permlane16_swap_b32 v199, v198
	v_add_f32_e32 v198, v198, v199
	v_mov_b32_e32 v199, v198
	s_nop 1
	v_permlane32_swap_b32 v199, v198
	v_add_f32_e32 v198, v198, v199
	ds_read_b128 v[130:133], v192
	ds_read_b128 v[134:137], v192 offset:1024
	ds_read_b128 v[138:141], v192 offset:2048
	ds_read_b128 v[142:145], v192 offset:3072
	ds_read_b128 v[146:149], v192 offset:4096
	ds_read_b128 v[150:153], v192 offset:5120
	ds_read_b128 v[154:157], v192 offset:6144
	ds_read_b128 v[158:161], v192 offset:7168
	ds_read_b128 v[178:181], v192 offset:8192
	ds_read_b128 v[182:185], v192 offset:9216
	v_fmamk_f32 v198, v198, 0x3a000000, v241
	v_mul_f32_e32 v199, 0x4b800000, v198
	v_cmp_gt_f32_e32 vcc, s17, v198
	s_nop 1
	v_cndmask_b32_e32 v198, v198, v199, vcc
	v_rsq_f32_e32 v198, v198
	s_nop 0
	v_mul_f32_e32 v199, 0x45800000, v198
	v_cndmask_b32_e32 v202, v198, v199, vcc
	v_pk_mul_f32 v[98:99], v[66:67], v[202:203] op_sel_hi:[1,0]
	v_pk_mul_f32 v[98:99], v[2:3], v[98:99]
	v_pk_mul_f32 v[100:101], v[68:69], v[202:203] op_sel_hi:[1,0]
	v_pk_mul_f32 v[100:101], v[4:5], v[100:101]
	v_cvt_pk_bf16_f32 v206, v98, v99
	v_cvt_pk_bf16_f32 v207, v100, v101
	global_store_dwordx2 v194, v[206:207], s[52:53]
	v_pk_mul_f32 v[102:103], v[70:71], v[202:203] op_sel_hi:[1,0]
	v_pk_mul_f32 v[102:103], v[6:7], v[102:103]
	v_pk_mul_f32 v[104:105], v[72:73], v[202:203] op_sel_hi:[1,0]
	v_pk_mul_f32 v[104:105], v[8:9], v[104:105]
	v_cvt_pk_bf16_f32 v206, v102, v103
	v_cvt_pk_bf16_f32 v207, v104, v105
	global_store_dwordx2 v194, v[206:207], s[52:53] offset:512
	v_pk_mul_f32 v[106:107], v[74:75], v[202:203] op_sel_hi:[1,0]
	v_pk_mul_f32 v[106:107], v[10:11], v[106:107]
	v_pk_mul_f32 v[108:109], v[76:77], v[202:203] op_sel_hi:[1,0]
	v_pk_mul_f32 v[108:109], v[12:13], v[108:109]
	v_cvt_pk_bf16_f32 v206, v106, v107
	v_cvt_pk_bf16_f32 v207, v108, v109
	global_store_dwordx2 v194, v[206:207], s[52:53] offset:1024
	v_pk_mul_f32 v[110:111], v[78:79], v[202:203] op_sel_hi:[1,0]
	v_pk_mul_f32 v[110:111], v[14:15], v[110:111]
	v_pk_mul_f32 v[112:113], v[80:81], v[202:203] op_sel_hi:[1,0]
	v_pk_mul_f32 v[112:113], v[16:17], v[112:113]
	v_cvt_pk_bf16_f32 v206, v110, v111
	v_cvt_pk_bf16_f32 v207, v112, v113
	global_store_dwordx2 v194, v[206:207], s[52:53] offset:1536
	v_pk_mul_f32 v[114:115], v[82:83], v[202:203] op_sel_hi:[1,0]
	v_pk_mul_f32 v[114:115], v[18:19], v[114:115]
	v_pk_mul_f32 v[116:117], v[84:85], v[202:203] op_sel_hi:[1,0]
	v_pk_mul_f32 v[116:117], v[20:21], v[116:117]
	v_cvt_pk_bf16_f32 v206, v114, v115
	v_cvt_pk_bf16_f32 v207, v116, v117
	global_store_dwordx2 v194, v[206:207], s[52:53] offset:2048
	v_pk_mul_f32 v[118:119], v[86:87], v[202:203] op_sel_hi:[1,0]
	v_pk_mul_f32 v[118:119], v[22:23], v[118:119]
	v_pk_mul_f32 v[120:121], v[88:89], v[202:203] op_sel_hi:[1,0]
	v_pk_mul_f32 v[120:121], v[24:25], v[120:121]
	v_cvt_pk_bf16_f32 v206, v118, v119
	v_cvt_pk_bf16_f32 v207, v120, v121
	global_store_dwordx2 v194, v[206:207], s[52:53] offset:2560
	v_pk_mul_f32 v[122:123], v[90:91], v[202:203] op_sel_hi:[1,0]
	v_pk_mul_f32 v[122:123], v[26:27], v[122:123]
	v_pk_mul_f32 v[124:125], v[92:93], v[202:203] op_sel_hi:[1,0]
	v_pk_mul_f32 v[124:125], v[28:29], v[124:125]
	v_cvt_pk_bf16_f32 v206, v122, v123
	v_cvt_pk_bf16_f32 v207, v124, v125
	global_store_dwordx2 v194, v[206:207], s[52:53] offset:3072
	v_pk_mul_f32 v[126:127], v[94:95], v[202:203] op_sel_hi:[1,0]
	v_pk_mul_f32 v[126:127], v[30:31], v[126:127]
	v_pk_mul_f32 v[128:129], v[96:97], v[202:203] op_sel_hi:[1,0]
	v_pk_mul_f32 v[128:129], v[32:33], v[128:129]
	v_cvt_pk_bf16_f32 v206, v126, v127
	v_cvt_pk_bf16_f32 v207, v128, v129
	global_store_dwordx2 v194, v[206:207], s[52:53] offset:3584
	v_add_u32_e32 v194, 0x800000, v194
	s_waitcnt lgkmcnt(8)
	v_pk_mul_f32 v[162:163], v[130:131], v[98:99] op_sel_hi:[1,0]
	v_pk_mul_f32 v[164:165], v[132:133], v[98:99] op_sel_hi:[1,0]
	v_pk_mul_f32 v[166:167], v[134:135], v[98:99] op_sel_hi:[1,0]
	v_pk_mul_f32 v[168:169], v[136:137], v[98:99] op_sel_hi:[1,0]
	ds_read_b128 v[130:133], v192 offset:10240
	ds_read_b128 v[134:137], v192 offset:11264
	s_waitcnt lgkmcnt(8)
	v_pk_fma_f32 v[162:163], v[138:139], v[98:99], v[162:163] op_sel:[0,1,0] op_sel_hi:[1,1,1]
	v_pk_fma_f32 v[164:165], v[140:141], v[98:99], v[164:165] op_sel:[0,1,0] op_sel_hi:[1,1,1]
	v_pk_fma_f32 v[166:167], v[142:143], v[98:99], v[166:167] op_sel:[0,1,0] op_sel_hi:[1,1,1]
	v_pk_fma_f32 v[168:169], v[144:145], v[98:99], v[168:169] op_sel:[0,1,0] op_sel_hi:[1,1,1]
	ds_read_b128 v[138:141], v192 offset:12288
	ds_read_b128 v[142:145], v192 offset:13312
	s_waitcnt lgkmcnt(8)
	v_pk_fma_f32 v[162:163], v[146:147], v[100:101], v[162:163] op_sel_hi:[1,0,1]
	v_pk_fma_f32 v[164:165], v[148:149], v[100:101], v[164:165] op_sel_hi:[1,0,1]
	v_pk_fma_f32 v[166:167], v[150:151], v[100:101], v[166:167] op_sel_hi:[1,0,1]
	v_pk_fma_f32 v[168:169], v[152:153], v[100:101], v[168:169] op_sel_hi:[1,0,1]
	ds_read_b128 v[146:149], v192 offset:14336
	ds_read_b128 v[150:153], v192 offset:15360
	s_waitcnt lgkmcnt(8)
	v_pk_fma_f32 v[162:163], v[154:155], v[100:101], v[162:163] op_sel:[0,1,0] op_sel_hi:[1,1,1]
	v_pk_fma_f32 v[164:165], v[156:157], v[100:101], v[164:165] op_sel:[0,1,0] op_sel_hi:[1,1,1]
	v_pk_fma_f32 v[166:167], v[158:159], v[100:101], v[166:167] op_sel:[0,1,0] op_sel_hi:[1,1,1]
	v_pk_fma_f32 v[168:169], v[160:161], v[100:101], v[168:169] op_sel:[0,1,0] op_sel_hi:[1,1,1]
	ds_read_b128 v[154:157], v192 offset:16384
	ds_read_b128 v[158:161], v192 offset:17408
	s_waitcnt lgkmcnt(8)
	v_pk_fma_f32 v[162:163], v[178:179], v[102:103], v[162:163] op_sel_hi:[1,0,1]
	v_pk_fma_f32 v[164:165], v[180:181], v[102:103], v[164:165] op_sel_hi:[1,0,1]
	v_pk_fma_f32 v[166:167], v[182:183], v[102:103], v[166:167] op_sel_hi:[1,0,1]
	v_pk_fma_f32 v[168:169], v[184:185], v[102:103], v[168:169] op_sel_hi:[1,0,1]
	ds_read_b128 v[178:181], v192 offset:18432
	ds_read_b128 v[182:185], v192 offset:19456
	s_waitcnt lgkmcnt(8)
	v_pk_fma_f32 v[162:163], v[130:131], v[102:103], v[162:163] op_sel:[0,1,0] op_sel_hi:[1,1,1]
	v_pk_fma_f32 v[164:165], v[132:133], v[102:103], v[164:165] op_sel:[0,1,0] op_sel_hi:[1,1,1]
	v_pk_fma_f32 v[166:167], v[134:135], v[102:103], v[166:167] op_sel:[0,1,0] op_sel_hi:[1,1,1]
	v_pk_fma_f32 v[168:169], v[136:137], v[102:103], v[168:169] op_sel:[0,1,0] op_sel_hi:[1,1,1]
	ds_read_b128 v[130:133], v192 offset:20480
	ds_read_b128 v[134:137], v192 offset:21504
	s_waitcnt lgkmcnt(8)
	v_pk_fma_f32 v[162:163], v[138:139], v[104:105], v[162:163] op_sel_hi:[1,0,1]
	v_pk_fma_f32 v[164:165], v[140:141], v[104:105], v[164:165] op_sel_hi:[1,0,1]
	v_pk_fma_f32 v[166:167], v[142:143], v[104:105], v[166:167] op_sel_hi:[1,0,1]
	v_pk_fma_f32 v[168:169], v[144:145], v[104:105], v[168:169] op_sel_hi:[1,0,1]
	ds_read_b128 v[138:141], v192 offset:22528
	ds_read_b128 v[142:145], v192 offset:23552
	s_waitcnt lgkmcnt(8)
	v_pk_fma_f32 v[162:163], v[146:147], v[104:105], v[162:163] op_sel:[0,1,0] op_sel_hi:[1,1,1]
	v_pk_fma_f32 v[164:165], v[148:149], v[104:105], v[164:165] op_sel:[0,1,0] op_sel_hi:[1,1,1]
	v_pk_fma_f32 v[166:167], v[150:151], v[104:105], v[166:167] op_sel:[0,1,0] op_sel_hi:[1,1,1]
	v_pk_fma_f32 v[168:169], v[152:153], v[104:105], v[168:169] op_sel:[0,1,0] op_sel_hi:[1,1,1]
	ds_read_b128 v[146:149], v192 offset:24576
	ds_read_b128 v[150:153], v192 offset:25600
	s_waitcnt lgkmcnt(8)
	v_pk_fma_f32 v[162:163], v[154:155], v[106:107], v[162:163] op_sel_hi:[1,0,1]
	v_pk_fma_f32 v[164:165], v[156:157], v[106:107], v[164:165] op_sel_hi:[1,0,1]
	v_pk_fma_f32 v[166:167], v[158:159], v[106:107], v[166:167] op_sel_hi:[1,0,1]
	v_pk_fma_f32 v[168:169], v[160:161], v[106:107], v[168:169] op_sel_hi:[1,0,1]
	ds_read_b128 v[154:157], v192 offset:26624
	ds_read_b128 v[158:161], v192 offset:27648
	s_waitcnt lgkmcnt(8)
	v_pk_fma_f32 v[162:163], v[178:179], v[106:107], v[162:163] op_sel:[0,1,0] op_sel_hi:[1,1,1]
	v_pk_fma_f32 v[164:165], v[180:181], v[106:107], v[164:165] op_sel:[0,1,0] op_sel_hi:[1,1,1]
	v_pk_fma_f32 v[166:167], v[182:183], v[106:107], v[166:167] op_sel:[0,1,0] op_sel_hi:[1,1,1]
	v_pk_fma_f32 v[168:169], v[184:185], v[106:107], v[168:169] op_sel:[0,1,0] op_sel_hi:[1,1,1]
	ds_read_b128 v[178:181], v192 offset:28672
	ds_read_b128 v[182:185], v192 offset:29696
	s_waitcnt lgkmcnt(8)
	v_pk_fma_f32 v[162:163], v[130:131], v[108:109], v[162:163] op_sel_hi:[1,0,1]
	v_pk_fma_f32 v[164:165], v[132:133], v[108:109], v[164:165] op_sel_hi:[1,0,1]
	v_pk_fma_f32 v[166:167], v[134:135], v[108:109], v[166:167] op_sel_hi:[1,0,1]
	v_pk_fma_f32 v[168:169], v[136:137], v[108:109], v[168:169] op_sel_hi:[1,0,1]
	ds_read_b128 v[130:133], v192 offset:30720
	ds_read_b128 v[134:137], v192 offset:31744
	s_waitcnt lgkmcnt(8)
	v_pk_fma_f32 v[162:163], v[138:139], v[108:109], v[162:163] op_sel:[0,1,0] op_sel_hi:[1,1,1]
	v_pk_fma_f32 v[164:165], v[140:141], v[108:109], v[164:165] op_sel:[0,1,0] op_sel_hi:[1,1,1]
	v_pk_fma_f32 v[166:167], v[142:143], v[108:109], v[166:167] op_sel:[0,1,0] op_sel_hi:[1,1,1]
	v_pk_fma_f32 v[168:169], v[144:145], v[108:109], v[168:169] op_sel:[0,1,0] op_sel_hi:[1,1,1]
	ds_read_b128 v[138:141], v192 offset:32768
	ds_read_b128 v[142:145], v192 offset:33792
	s_waitcnt lgkmcnt(8)
	v_pk_fma_f32 v[162:163], v[146:147], v[110:111], v[162:163] op_sel_hi:[1,0,1]
	v_pk_fma_f32 v[164:165], v[148:149], v[110:111], v[164:165] op_sel_hi:[1,0,1]
	v_pk_fma_f32 v[166:167], v[150:151], v[110:111], v[166:167] op_sel_hi:[1,0,1]
	v_pk_fma_f32 v[168:169], v[152:153], v[110:111], v[168:169] op_sel_hi:[1,0,1]
	ds_read_b128 v[146:149], v192 offset:34816
	ds_read_b128 v[150:153], v192 offset:35840
	s_waitcnt lgkmcnt(8)
	v_pk_fma_f32 v[162:163], v[154:155], v[110:111], v[162:163] op_sel:[0,1,0] op_sel_hi:[1,1,1]
	v_pk_fma_f32 v[164:165], v[156:157], v[110:111], v[164:165] op_sel:[0,1,0] op_sel_hi:[1,1,1]
	v_pk_fma_f32 v[166:167], v[158:159], v[110:111], v[166:167] op_sel:[0,1,0] op_sel_hi:[1,1,1]
	v_pk_fma_f32 v[168:169], v[160:161], v[110:111], v[168:169] op_sel:[0,1,0] op_sel_hi:[1,1,1]
	ds_read_b128 v[154:157], v192 offset:36864
	ds_read_b128 v[158:161], v192 offset:37888
	s_waitcnt lgkmcnt(8)
	v_pk_fma_f32 v[162:163], v[178:179], v[112:113], v[162:163] op_sel_hi:[1,0,1]
	v_pk_fma_f32 v[164:165], v[180:181], v[112:113], v[164:165] op_sel_hi:[1,0,1]
	v_pk_fma_f32 v[166:167], v[182:183], v[112:113], v[166:167] op_sel_hi:[1,0,1]
	v_pk_fma_f32 v[168:169], v[184:185], v[112:113], v[168:169] op_sel_hi:[1,0,1]
	ds_read_b128 v[178:181], v192 offset:38912
	ds_read_b128 v[182:185], v192 offset:39936
	s_waitcnt lgkmcnt(8)
	v_pk_fma_f32 v[162:163], v[130:131], v[112:113], v[162:163] op_sel:[0,1,0] op_sel_hi:[1,1,1]
	v_pk_fma_f32 v[164:165], v[132:133], v[112:113], v[164:165] op_sel:[0,1,0] op_sel_hi:[1,1,1]
	v_pk_fma_f32 v[166:167], v[134:135], v[112:113], v[166:167] op_sel:[0,1,0] op_sel_hi:[1,1,1]
	v_pk_fma_f32 v[168:169], v[136:137], v[112:113], v[168:169] op_sel:[0,1,0] op_sel_hi:[1,1,1]
	ds_read_b128 v[130:133], v192 offset:40960
	ds_read_b128 v[134:137], v192 offset:41984
	s_waitcnt lgkmcnt(8)
	v_pk_fma_f32 v[162:163], v[138:139], v[114:115], v[162:163] op_sel_hi:[1,0,1]
	v_pk_fma_f32 v[164:165], v[140:141], v[114:115], v[164:165] op_sel_hi:[1,0,1]
	v_pk_fma_f32 v[166:167], v[142:143], v[114:115], v[166:167] op_sel_hi:[1,0,1]
	v_pk_fma_f32 v[168:169], v[144:145], v[114:115], v[168:169] op_sel_hi:[1,0,1]
	ds_read_b128 v[138:141], v192 offset:43008
	ds_read_b128 v[142:145], v192 offset:44032
	s_waitcnt lgkmcnt(8)
	v_pk_fma_f32 v[162:163], v[146:147], v[114:115], v[162:163] op_sel:[0,1,0] op_sel_hi:[1,1,1]
	v_pk_fma_f32 v[164:165], v[148:149], v[114:115], v[164:165] op_sel:[0,1,0] op_sel_hi:[1,1,1]
	v_pk_fma_f32 v[166:167], v[150:151], v[114:115], v[166:167] op_sel:[0,1,0] op_sel_hi:[1,1,1]
	v_pk_fma_f32 v[168:169], v[152:153], v[114:115], v[168:169] op_sel:[0,1,0] op_sel_hi:[1,1,1]
	ds_read_b128 v[146:149], v192 offset:45056
	ds_read_b128 v[150:153], v192 offset:46080
	s_waitcnt lgkmcnt(8)
	v_pk_fma_f32 v[162:163], v[154:155], v[116:117], v[162:163] op_sel_hi:[1,0,1]
	v_pk_fma_f32 v[164:165], v[156:157], v[116:117], v[164:165] op_sel_hi:[1,0,1]
	v_pk_fma_f32 v[166:167], v[158:159], v[116:117], v[166:167] op_sel_hi:[1,0,1]
	v_pk_fma_f32 v[168:169], v[160:161], v[116:117], v[168:169] op_sel_hi:[1,0,1]
	ds_read_b128 v[154:157], v192 offset:47104
	ds_read_b128 v[158:161], v192 offset:48128
	s_waitcnt lgkmcnt(8)
	v_pk_fma_f32 v[162:163], v[178:179], v[116:117], v[162:163] op_sel:[0,1,0] op_sel_hi:[1,1,1]
	v_pk_fma_f32 v[164:165], v[180:181], v[116:117], v[164:165] op_sel:[0,1,0] op_sel_hi:[1,1,1]
	v_pk_fma_f32 v[166:167], v[182:183], v[116:117], v[166:167] op_sel:[0,1,0] op_sel_hi:[1,1,1]
	v_pk_fma_f32 v[168:169], v[184:185], v[116:117], v[168:169] op_sel:[0,1,0] op_sel_hi:[1,1,1]
	ds_read_b128 v[178:181], v192 offset:49152
	ds_read_b128 v[182:185], v192 offset:50176
	s_waitcnt lgkmcnt(8)
	v_pk_fma_f32 v[162:163], v[130:131], v[118:119], v[162:163] op_sel_hi:[1,0,1]
	v_pk_fma_f32 v[164:165], v[132:133], v[118:119], v[164:165] op_sel_hi:[1,0,1]
	v_pk_fma_f32 v[166:167], v[134:135], v[118:119], v[166:167] op_sel_hi:[1,0,1]
	v_pk_fma_f32 v[168:169], v[136:137], v[118:119], v[168:169] op_sel_hi:[1,0,1]
	ds_read_b128 v[130:133], v192 offset:51200
	ds_read_b128 v[134:137], v192 offset:52224
	s_waitcnt lgkmcnt(8)
	v_pk_fma_f32 v[162:163], v[138:139], v[118:119], v[162:163] op_sel:[0,1,0] op_sel_hi:[1,1,1]
	v_pk_fma_f32 v[164:165], v[140:141], v[118:119], v[164:165] op_sel:[0,1,0] op_sel_hi:[1,1,1]
	v_pk_fma_f32 v[166:167], v[142:143], v[118:119], v[166:167] op_sel:[0,1,0] op_sel_hi:[1,1,1]
	v_pk_fma_f32 v[168:169], v[144:145], v[118:119], v[168:169] op_sel:[0,1,0] op_sel_hi:[1,1,1]
	ds_read_b128 v[138:141], v192 offset:53248
	ds_read_b128 v[142:145], v192 offset:54272
	s_waitcnt lgkmcnt(8)
	v_pk_fma_f32 v[162:163], v[146:147], v[120:121], v[162:163] op_sel_hi:[1,0,1]
	v_pk_fma_f32 v[164:165], v[148:149], v[120:121], v[164:165] op_sel_hi:[1,0,1]
	v_pk_fma_f32 v[166:167], v[150:151], v[120:121], v[166:167] op_sel_hi:[1,0,1]
	v_pk_fma_f32 v[168:169], v[152:153], v[120:121], v[168:169] op_sel_hi:[1,0,1]
	ds_read_b128 v[146:149], v192 offset:55296
	ds_read_b128 v[150:153], v192 offset:56320
	s_waitcnt lgkmcnt(8)
	v_pk_fma_f32 v[162:163], v[154:155], v[120:121], v[162:163] op_sel:[0,1,0] op_sel_hi:[1,1,1]
	v_pk_fma_f32 v[164:165], v[156:157], v[120:121], v[164:165] op_sel:[0,1,0] op_sel_hi:[1,1,1]
	v_pk_fma_f32 v[166:167], v[158:159], v[120:121], v[166:167] op_sel:[0,1,0] op_sel_hi:[1,1,1]
	v_pk_fma_f32 v[168:169], v[160:161], v[120:121], v[168:169] op_sel:[0,1,0] op_sel_hi:[1,1,1]
	ds_read_b128 v[154:157], v192 offset:57344
	ds_read_b128 v[158:161], v192 offset:58368
	s_waitcnt lgkmcnt(8)
	v_pk_fma_f32 v[162:163], v[178:179], v[122:123], v[162:163] op_sel_hi:[1,0,1]
	v_pk_fma_f32 v[164:165], v[180:181], v[122:123], v[164:165] op_sel_hi:[1,0,1]
	v_pk_fma_f32 v[166:167], v[182:183], v[122:123], v[166:167] op_sel_hi:[1,0,1]
	v_pk_fma_f32 v[168:169], v[184:185], v[122:123], v[168:169] op_sel_hi:[1,0,1]
	ds_read_b128 v[178:181], v192 offset:59392
	ds_read_b128 v[182:185], v192 offset:60416
	s_waitcnt lgkmcnt(8)
	v_pk_fma_f32 v[162:163], v[130:131], v[122:123], v[162:163] op_sel:[0,1,0] op_sel_hi:[1,1,1]
	v_pk_fma_f32 v[164:165], v[132:133], v[122:123], v[164:165] op_sel:[0,1,0] op_sel_hi:[1,1,1]
	v_pk_fma_f32 v[166:167], v[134:135], v[122:123], v[166:167] op_sel:[0,1,0] op_sel_hi:[1,1,1]
	v_pk_fma_f32 v[168:169], v[136:137], v[122:123], v[168:169] op_sel:[0,1,0] op_sel_hi:[1,1,1]
	ds_read_b128 v[130:133], v192 offset:61440
	ds_read_b128 v[134:137], v192 offset:62464
	s_waitcnt lgkmcnt(8)
	v_pk_fma_f32 v[162:163], v[138:139], v[124:125], v[162:163] op_sel_hi:[1,0,1]
	v_pk_fma_f32 v[164:165], v[140:141], v[124:125], v[164:165] op_sel_hi:[1,0,1]
	v_pk_fma_f32 v[166:167], v[142:143], v[124:125], v[166:167] op_sel_hi:[1,0,1]
	v_pk_fma_f32 v[168:169], v[144:145], v[124:125], v[168:169] op_sel_hi:[1,0,1]
	ds_read_b128 v[138:141], v192 offset:63488
	ds_read_b128 v[142:145], v192 offset:64512
	s_waitcnt lgkmcnt(8)
	v_pk_fma_f32 v[162:163], v[146:147], v[124:125], v[162:163] op_sel:[0,1,0] op_sel_hi:[1,1,1]
	v_pk_fma_f32 v[164:165], v[148:149], v[124:125], v[164:165] op_sel:[0,1,0] op_sel_hi:[1,1,1]
	v_pk_fma_f32 v[166:167], v[150:151], v[124:125], v[166:167] op_sel:[0,1,0] op_sel_hi:[1,1,1]
	v_pk_fma_f32 v[168:169], v[152:153], v[124:125], v[168:169] op_sel:[0,1,0] op_sel_hi:[1,1,1]
	s_waitcnt lgkmcnt(6)
	v_pk_fma_f32 v[162:163], v[154:155], v[126:127], v[162:163] op_sel_hi:[1,0,1]
	v_pk_fma_f32 v[164:165], v[156:157], v[126:127], v[164:165] op_sel_hi:[1,0,1]
	v_pk_fma_f32 v[166:167], v[158:159], v[126:127], v[166:167] op_sel_hi:[1,0,1]
	v_pk_fma_f32 v[168:169], v[160:161], v[126:127], v[168:169] op_sel_hi:[1,0,1]
	s_waitcnt lgkmcnt(4)
	v_pk_fma_f32 v[162:163], v[178:179], v[126:127], v[162:163] op_sel:[0,1,0] op_sel_hi:[1,1,1]
	v_pk_fma_f32 v[164:165], v[180:181], v[126:127], v[164:165] op_sel:[0,1,0] op_sel_hi:[1,1,1]
	v_pk_fma_f32 v[166:167], v[182:183], v[126:127], v[166:167] op_sel:[0,1,0] op_sel_hi:[1,1,1]
	v_pk_fma_f32 v[168:169], v[184:185], v[126:127], v[168:169] op_sel:[0,1,0] op_sel_hi:[1,1,1]
	s_waitcnt lgkmcnt(2)
	v_pk_fma_f32 v[162:163], v[130:131], v[128:129], v[162:163] op_sel_hi:[1,0,1]
	v_pk_fma_f32 v[164:165], v[132:133], v[128:129], v[164:165] op_sel_hi:[1,0,1]
	v_pk_fma_f32 v[166:167], v[134:135], v[128:129], v[166:167] op_sel_hi:[1,0,1]
	v_pk_fma_f32 v[168:169], v[136:137], v[128:129], v[168:169] op_sel_hi:[1,0,1]
	s_waitcnt lgkmcnt(0)
	v_pk_fma_f32 v[162:163], v[138:139], v[128:129], v[162:163] op_sel:[0,1,0] op_sel_hi:[1,1,1]
	v_pk_fma_f32 v[164:165], v[140:141], v[128:129], v[164:165] op_sel:[0,1,0] op_sel_hi:[1,1,1]
	v_pk_fma_f32 v[166:167], v[142:143], v[128:129], v[166:167] op_sel:[0,1,0] op_sel_hi:[1,1,1]
	v_pk_fma_f32 v[168:169], v[144:145], v[128:129], v[168:169] op_sel:[0,1,0] op_sel_hi:[1,1,1]
	s_nop 1
	v_add_f32_dpp v162, v162, v162 quad_perm:[1,0,3,2] row_mask:0xf bank_mask:0xf
	v_add_f32_dpp v163, v163, v163 quad_perm:[1,0,3,2] row_mask:0xf bank_mask:0xf
	v_add_f32_dpp v164, v164, v164 quad_perm:[1,0,3,2] row_mask:0xf bank_mask:0xf
	v_add_f32_dpp v165, v165, v165 quad_perm:[1,0,3,2] row_mask:0xf bank_mask:0xf
	v_add_f32_dpp v166, v166, v166 quad_perm:[1,0,3,2] row_mask:0xf bank_mask:0xf
	v_add_f32_dpp v167, v167, v167 quad_perm:[1,0,3,2] row_mask:0xf bank_mask:0xf
	v_add_f32_dpp v168, v168, v168 quad_perm:[1,0,3,2] row_mask:0xf bank_mask:0xf
	v_add_f32_dpp v169, v169, v169 quad_perm:[1,0,3,2] row_mask:0xf bank_mask:0xf
	v_add_f32_dpp v162, v162, v162 quad_perm:[2,3,0,1] row_mask:0xf bank_mask:0xf
	v_add_f32_dpp v163, v163, v163 quad_perm:[2,3,0,1] row_mask:0xf bank_mask:0xf
	v_add_f32_dpp v164, v164, v164 quad_perm:[2,3,0,1] row_mask:0xf bank_mask:0xf
	v_add_f32_dpp v165, v165, v165 quad_perm:[2,3,0,1] row_mask:0xf bank_mask:0xf
	v_add_f32_dpp v166, v166, v166 quad_perm:[2,3,0,1] row_mask:0xf bank_mask:0xf
	v_add_f32_dpp v167, v167, v167 quad_perm:[2,3,0,1] row_mask:0xf bank_mask:0xf
	v_add_f32_dpp v168, v168, v168 quad_perm:[2,3,0,1] row_mask:0xf bank_mask:0xf
	v_add_f32_dpp v169, v169, v169 quad_perm:[2,3,0,1] row_mask:0xf bank_mask:0xf
	v_add_f32_dpp v162, v162, v162 row_half_mirror row_mask:0xf bank_mask:0xf
	v_add_f32_dpp v163, v163, v163 row_half_mirror row_mask:0xf bank_mask:0xf
	v_add_f32_dpp v164, v164, v164 row_half_mirror row_mask:0xf bank_mask:0xf
	v_add_f32_dpp v165, v165, v165 row_half_mirror row_mask:0xf bank_mask:0xf
	v_add_f32_dpp v166, v166, v166 row_half_mirror row_mask:0xf bank_mask:0xf
	v_add_f32_dpp v167, v167, v167 row_half_mirror row_mask:0xf bank_mask:0xf
	v_add_f32_dpp v168, v168, v168 row_half_mirror row_mask:0xf bank_mask:0xf
	v_add_f32_dpp v169, v169, v169 row_half_mirror row_mask:0xf bank_mask:0xf
	v_add_f32_dpp v162, v162, v162 row_mirror row_mask:0xf bank_mask:0xf
	v_add_f32_dpp v163, v163, v163 row_mirror row_mask:0xf bank_mask:0xf
	v_add_f32_dpp v164, v164, v164 row_mirror row_mask:0xf bank_mask:0xf
	v_add_f32_dpp v165, v165, v165 row_mirror row_mask:0xf bank_mask:0xf
	v_add_f32_dpp v166, v166, v166 row_mirror row_mask:0xf bank_mask:0xf
	v_add_f32_dpp v167, v167, v167 row_mirror row_mask:0xf bank_mask:0xf
	v_add_f32_dpp v168, v168, v168 row_mirror row_mask:0xf bank_mask:0xf
	v_add_f32_dpp v169, v169, v169 row_mirror row_mask:0xf bank_mask:0xf
	v_mov_b32_e32 v170, v162
	v_mov_b32_e32 v171, v163
	v_mov_b32_e32 v172, v164
	v_mov_b32_e32 v173, v165
	v_mov_b32_e32 v174, v166
	v_mov_b32_e32 v175, v167
	v_mov_b32_e32 v176, v168
	v_mov_b32_e32 v177, v169
	v_permlane16_swap_b32 v170, v162
	v_permlane16_swap_b32 v171, v163
	v_permlane16_swap_b32 v172, v164
	v_permlane16_swap_b32 v173, v165
	v_permlane16_swap_b32 v174, v166
	v_permlane16_swap_b32 v175, v167
	v_permlane16_swap_b32 v176, v168
	v_permlane16_swap_b32 v177, v169
	v_add_f32_e32 v162, v162, v170
	v_add_f32_e32 v163, v163, v171
	v_add_f32_e32 v164, v164, v172
	v_add_f32_e32 v165, v165, v173
	v_add_f32_e32 v166, v166, v174
	v_add_f32_e32 v167, v167, v175
	v_add_f32_e32 v168, v168, v176
	v_add_f32_e32 v169, v169, v177
	v_mov_b32_e32 v170, v162
	v_mov_b32_e32 v171, v163
	v_mov_b32_e32 v172, v164
	v_mov_b32_e32 v173, v165
	v_mov_b32_e32 v174, v166
	v_mov_b32_e32 v175, v167
	v_mov_b32_e32 v176, v168
	v_mov_b32_e32 v177, v169
	v_permlane32_swap_b32 v170, v162
	v_permlane32_swap_b32 v171, v163
	v_permlane32_swap_b32 v172, v164
	v_permlane32_swap_b32 v173, v165
	v_permlane32_swap_b32 v174, v166
	v_permlane32_swap_b32 v175, v167
	v_permlane32_swap_b32 v176, v168
	v_permlane32_swap_b32 v177, v169
	v_add_f32_e32 v162, v162, v170
	v_add_f32_e32 v163, v163, v171
	v_add_f32_e32 v164, v164, v172
	v_add_f32_e32 v165, v165, v173
	v_add_f32_e32 v166, v166, v174
	v_add_f32_e32 v167, v167, v175
	v_add_f32_e32 v168, v168, v176
	v_add_f32_e32 v169, v169, v177
	v_readfirstlane_b32 s98, v162
	v_readfirstlane_b32 s99, v163
	v_readfirstlane_b32 s100, v164
	v_readfirstlane_b32 s101, v165
	v_writelane_b32 v230, s98, 56
	v_writelane_b32 v230, s99, 57
	v_writelane_b32 v230, s100, 58
	v_writelane_b32 v230, s101, 59
	v_readfirstlane_b32 s98, v166
	v_readfirstlane_b32 s99, v167
	v_readfirstlane_b32 s100, v168
	v_readfirstlane_b32 s101, v169
	v_writelane_b32 v230, s98, 60
	v_writelane_b32 v230, s99, 61
	v_writelane_b32 v230, s100, 62
	v_writelane_b32 v230, s101, 63
	v_add_f32_e32 v223, v230, v196
	v_mul_f32_e64 v225, |v223|, s24
	v_exp_f32_e32 v210, v225
	v_min_f32_e32 v225, 0, v223
	s_nop 0
	v_add_f32_e32 v211, 1.0, v210
	v_add_f32_e32 v212, -1.0, v211
	v_frexp_mant_f32_e32 v213, v211
	v_cvt_f64_f32_e32 v[208:209], v211
	v_sub_f32_e32 v214, v212, v211
	v_frexp_exp_i32_f64_e32 v208, v[208:209]
	v_cmp_gt_f32_e32 vcc, s25, v213
	v_sub_f32_e32 v212, v210, v212
	v_add_f32_e32 v209, 1.0, v214
	v_subbrev_co_u32_e32 v208, vcc, 0, v208, vcc
	v_add_f32_e32 v209, v212, v209
	v_sub_u32_e32 v212, 0, v208
	v_cvt_f32_i32_e32 v208, v208
	v_ldexp_f32 v211, v211, v212
	v_ldexp_f32 v209, v209, v212
	v_add_f32_e32 v212, -1.0, v211
	v_add_f32_e32 v213, 1.0, v211
	v_add_f32_e32 v214, 1.0, v212
	v_add_f32_e32 v215, -1.0, v213
	v_sub_f32_e32 v214, v211, v214
	v_sub_f32_e32 v211, v211, v215
	v_mul_f32_e32 v215, 0x3f317218, v208
	v_add_f32_e32 v214, v209, v214
	v_add_f32_e32 v209, v209, v211
	v_fma_f32 v211, v208, s28, -v215
	v_add_f32_e32 v216, v212, v214
	v_add_f32_e32 v217, v213, v209
	v_fmac_f32_e32 v211, 0xb102e308, v208
	v_sub_f32_e32 v208, v216, v212
	v_sub_f32_e32 v212, v217, v213
	v_rcp_f32_e32 v213, v217
	v_add_f32_e32 v218, v215, v211
	v_sub_f32_e32 v209, v209, v212
	v_sub_f32_e32 v212, v218, v215
	v_sub_f32_e32 v211, v211, v212
	v_mul_f32_e32 v212, v216, v213
	v_sub_f32_e32 v208, v214, v208
	v_mul_f32_e32 v214, v217, v212
	v_fma_f32 v215, v212, v217, -v214
	v_fmac_f32_e32 v215, v212, v209
	v_add_f32_e32 v219, v214, v215
	v_sub_f32_e32 v220, v216, v219
	v_sub_f32_e32 v214, v219, v214
	v_sub_f32_e32 v216, v216, v220
	v_sub_f32_e32 v214, v214, v215
	v_sub_f32_e32 v215, v216, v219
	v_add_f32_e32 v208, v208, v215
	v_add_f32_e32 v208, v214, v208
	v_add_f32_e32 v214, v220, v208
	v_mul_f32_e32 v215, v213, v214
	v_sub_f32_e32 v216, v220, v214
	v_mul_f32_e32 v219, v217, v215
	v_add_f32_e32 v208, v208, v216
	v_add_f32_e32 v216, v212, v215
	v_fma_f32 v217, v215, v217, -v219
	v_sub_f32_e32 v212, v216, v212
	v_fmac_f32_e32 v217, v215, v209
	v_sub_f32_e32 v209, v215, v212
	v_add_f32_e32 v212, v219, v217
	v_sub_f32_e32 v215, v212, v219
	v_sub_f32_e32 v219, v214, v212
	v_sub_f32_e32 v214, v214, v219
	v_sub_f32_e32 v212, v214, v212
	v_sub_f32_e32 v215, v215, v217
	v_add_f32_e32 v208, v208, v212
	v_add_f32_e32 v208, v215, v208
	v_add_f32_e32 v208, v219, v208
	v_mul_f32_e32 v208, v213, v208
	v_add_f32_e32 v208, v209, v208
	v_add_f32_e32 v209, v216, v208
	v_mul_f32_e32 v212, v209, v209
	v_fmamk_f32 v215, v212, 0x3e9b6dac, v242
	v_sub_f32_e32 v213, v209, v216
	v_ldexp_f32 v214, v209, 1
	v_mul_f32_e32 v209, v209, v212
	v_fmaak_f32 v212, v212, v215, 0x3f2aaada
	v_mul_f32_e32 v209, v209, v212
	v_add_f32_e32 v212, v214, v209
	v_sub_f32_e32 v208, v208, v213
	v_sub_f32_e32 v213, v212, v214
	v_ldexp_f32 v208, v208, 1
	v_sub_f32_e32 v209, v209, v213
	v_add_f32_e32 v208, v208, v209
	v_add_f32_e32 v209, v212, v208
	v_sub_f32_e32 v212, v209, v212
	v_add_f32_e32 v213, v218, v209
	v_sub_f32_e32 v208, v208, v212
	v_sub_f32_e32 v212, v213, v218
	v_sub_f32_e32 v214, v213, v212
	v_sub_f32_e32 v209, v209, v212
	v_add_f32_e32 v212, v211, v208
	v_sub_f32_e32 v214, v218, v214
	v_sub_f32_e32 v215, v212, v211
	v_add_f32_e32 v209, v209, v214
	v_sub_f32_e32 v214, v212, v215
	v_sub_f32_e32 v208, v208, v215
	v_sub_f32_e32 v211, v211, v214
	v_add_f32_e32 v209, v212, v209
	v_add_f32_e32 v208, v208, v211
	v_add_f32_e32 v211, v213, v209
	v_sub_f32_e32 v212, v211, v213
	v_sub_f32_e32 v209, v209, v212
	v_add_f32_e32 v208, v208, v209
	v_add_f32_e32 v208, v211, v208
	v_cmp_neq_f32_e32 vcc, s29, v210
	s_nop 0
	s_nop 0
	v_cndmask_b32_e32 v208, v243, v208, vcc
	v_cmp_ngt_f32_e32 vcc, -1.0, v210
	s_nop 1
	v_cndmask_b32_e32 v208, v244, v208, vcc
	v_cmp_neq_f32_e32 vcc, -1.0, v210
	s_nop 1
	v_cndmask_b32_e32 v208, v245, v208, vcc
	v_cmp_lt_f32_e64 vcc, |v210|, s30
	s_nop 1
	v_cndmask_b32_e32 v208, v208, v210, vcc
	v_sub_f32_e32 v225, v225, v208
	v_lshrrev_b32_e32 v231, 3, v251
	v_and_b32_e32 v232, 7, v251
	v_lshlrev_b32_e32 v233, 13, v231
	v_lshl_add_u32 v233, v232, 15, v233
	v_lshl_add_u32 v233, v250, 2, v233
	v_cmp_lt_u32_e32 vcc, 3, v231
	v_mov_b32_e32 v234, 0x38000
	s_nop 0
	v_cndmask_b32_e32 v234, 0, v234, vcc
	v_add_u32_e32 v233, v233, v234
	global_store_dword v233, v225, s[74:75]
